# dilated attention: the serialized T5-bias LDS lookups (7 dependent ds_read2 round trips per score tile) hoisted and issued together into free registers
# speedup vs baseline: 1.0025x; 1.0025x over previous
; template <int DELTA> ...
;     u32x4 vv[8]; bf16x8 kf[2][4];
; #pragma unroll
;     for (int i = 0; i < 8; ++i) { const int idx = lane + 64 * i, row = idx >> 3, ch = idx & 7; vv[i] = *(const u32x4*)(vbase + (size_t)row * rstride + ch * 8); }
; #pragma unroll
;     for (int kvh = 0; kvh < 2; ++kvh)
; #pragma unroll
;         for (int d0 = 0; d0 < 4; ++d0) kf[kvh][d0] = *(const bf16x8*)(kbase + (size_t)(32 * kvh + r32) * rstride + d0 * 16);
;     SBAR0();
; #pragma unroll
;     for (int i = 0; i < 8; ++i) { const int idx = lane + 64 * i, row = idx >> 3, ch = idx & 7; *(LAS u32x4*)(wl + row * VP + ch * 16) = vv[i]; }
;     bf16x8 pb[2][4];
; #pragma unroll
;     for (int qh = 0; qh < 2; ++qh) {
;         f32x16 s[2]; float mx = -1e30f;
; #pragma unroll
;         for (int kvh = 0; kvh < 2; ++kvh) {
;             constexpr int dummy = 0; (void)dummy;
;             const int toff = 64 * DELTA + 32 * (kvh - qh);
; template <int P_>
; __device__ __forceinline__ void dil_wave_unit(LAS unsigned char* wl, const bf16_t* DIL, bf16_t* Y, bf16_t* ST, float* LSE, const float* BT, int b, int h, int r, int nb) {
;     ...
;     const size_t tok0 = (size_t)b * SEQ; const size_t rstride = (size_t)dil * 64;
;     LAS float* bt = (LAS float*)(wl + VT_B);
;     for (int i = lane; i < 257; i += 64) { int j = i - 64; j = j < 0 ? 0 : (j > 128 ? 128 : j); bt[i] = BT[(P_ * 8 + h) * 129 + j]; }
;     const int btb = 128 * 4;
;     const int bvar = btb + 4 * (4 * hi - r32);
;     bf16x8 qf[2][4];
;     const bf16_t* rowb = DIL + ((size_t)(b * 8 + h) * SEQ + (size_t)(64 * nb) * dil + r) * 64;
;     constexpr size_t KOFF = pg8::DPLANE, VOFF = 2 * pg8::DPLANE;
; #pragma unroll
;     for (int qh = 0; qh < 2; ++qh)
; #pragma unroll
;         for (int d0 = 0; d0 < 4; ++d0) qf[qh][d0] = *(const bf16x8*)(rowb + (size_t)(32 * qh + r32) * rstride + hi * 8 + d0 * 16);
;     f32x16 o[2][2];
; #pragma unroll
;     for (int a = 0; a < 2; ++a)
; #pragma unroll
;         for (int c = 0; c < 2; ++c)
; #pragma unroll
;             for (int i = 0; i < 16; ++i) o[a][c][i] = 0.f;
;     float m_run[2] = {-1e30f, -1e30f}, l_run[2] = {0.f, 0.f};
;     const int voff = (4 * hi + ((lane & 15) >> 2)) * VP + (16 * ((lane >> 4) & 1) + 4 * (lane & 3)) * 2;
;     LDS_WAIT();
;     dil_block<0>(wl, rowb + KOFF + hi * 8, rowb + VOFF, rstride, qf, o, m_run, l_run, bvar, voff, lane, r32, hi, btb);
.LBB0_438:
	s_or_b64 exec, exec, s[6:7]
	s_or_b32 s37, s35, s9
	s_lshl_b32 s35, s37, 6
	s_ashr_i32 s7, s35, 31
	s_add_u32 s6, s18, s35
	s_addc_u32 s7, s19, s7
	s_lshl_b64 s[6:7], s[6:7], 7
	v_and_b32_e32 v210, 31, v2
	v_lshrrev_b32_e32 v3, 5, v209
	s_add_u32 s6, s4, s6
	s_addc_u32 s7, s5, s7
	v_lshlrev_b32_e32 v169, 6, v210
	s_waitcnt vmcnt(0)
	v_lshlrev_b32_e32 v0, 4, v3
	v_lshl_add_u64 v[4:5], s[6:7], 0, v[0:1]
	v_lshlrev_b32_e32 v16, 7, v210
	v_mov_b32_e32 v17, v1
	v_or_b32_e32 v0, 0x800, v169
	v_lshl_add_u64 v[6:7], v[4:5], 0, v[16:17]
	v_lshlrev_b32_e32 v0, 1, v0
	s_mov_b64 s[38:39], 0x4000000
	global_load_dwordx4 v[126:129], v[6:7], off
	global_load_dwordx4 v[114:117], v[6:7], off offset:32
	global_load_dwordx4 v[118:121], v[6:7], off offset:64
	global_load_dwordx4 v[122:125], v[6:7], off offset:96
	v_lshl_add_u64 v[6:7], v[4:5], 0, v[0:1]
	v_lshl_add_u64 v[18:19], v[4:5], 0, s[38:39]
	v_lshlrev_b32_e32 v4, 3, v209
	v_and_b32_e32 v4, 56, v4
	v_lshlrev_b32_e32 v146, 1, v4
	v_mov_b32_e32 v147, v1
	v_lshrrev_b32_e32 v70, 3, v209
	v_lshl_add_u64 v[94:95], s[6:7], 0, v[146:147]
	s_mov_b64 s[38:39], 0x8000000
	v_or_b32_e32 v71, 8, v70
	v_or_b32_e32 v72, 16, v70
	v_or_b32_e32 v73, 24, v70
	global_load_dwordx4 v[110:113], v[6:7], off
	global_load_dwordx4 v[106:109], v[6:7], off offset:32
	global_load_dwordx4 v[98:101], v[6:7], off offset:64
	global_load_dwordx4 v[102:105], v[6:7], off offset:96
	v_lshl_add_u64 v[20:21], v[94:95], 0, s[38:39]
	v_lshlrev_b32_e32 v4, 7, v70
	v_mov_b32_e32 v5, v1
	v_lshlrev_b32_e32 v6, 7, v71
	v_mov_b32_e32 v7, v1
	v_lshlrev_b32_e32 v12, 7, v72
	v_mov_b32_e32 v13, v1
	v_lshlrev_b32_e32 v14, 7, v73
	v_mov_b32_e32 v15, v1
	s_waitcnt lgkmcnt(0)
	v_lshl_add_u64 v[4:5], v[20:21], 0, v[4:5]
	v_lshl_add_u64 v[8:9], v[20:21], 0, v[6:7]
	v_lshl_add_u64 v[12:13], v[20:21], 0, v[12:13]
	v_lshl_add_u64 v[22:23], v[20:21], 0, v[14:15]
	v_or_b32_e32 v74, 32, v70
	global_load_dwordx4 v[4:7], v[4:5], off
	s_nop 0
	global_load_dwordx4 v[8:11], v[8:9], off
	s_nop 0
	global_load_dwordx4 v[12:15], v[12:13], off
	s_nop 0
	global_load_dwordx4 v[34:37], v[22:23], off
	v_lshlrev_b32_e32 v22, 7, v74
	v_mov_b32_e32 v23, v1
	v_or_b32_e32 v75, 40, v70
	v_lshl_add_u64 v[22:23], v[20:21], 0, v[22:23]
	v_lshlrev_b32_e32 v24, 7, v75
	v_mov_b32_e32 v25, v1
	v_or_b32_e32 v76, 48, v70
	v_lshl_add_u64 v[24:25], v[20:21], 0, v[24:25]
	global_load_dwordx4 v[54:57], v[22:23], off
	global_load_dwordx4 v[58:61], v[24:25], off
	v_lshlrev_b32_e32 v22, 7, v76
	v_mov_b32_e32 v23, v1
	v_or_b32_e32 v77, 56, v70
	v_lshl_add_u64 v[22:23], v[20:21], 0, v[22:23]
	v_lshlrev_b32_e32 v24, 7, v77
	v_mov_b32_e32 v25, v1
	v_lshl_add_u64 v[16:17], v[18:19], 0, v[16:17]
	v_lshl_add_u64 v[20:21], v[20:21], 0, v[24:25]
	global_load_dwordx4 v[62:65], v[22:23], off
	global_load_dwordx4 v[66:69], v[20:21], off
	global_load_dwordx4 v[50:53], v[16:17], off
	global_load_dwordx4 v[46:49], v[16:17], off offset:32
	global_load_dwordx4 v[42:45], v[16:17], off offset:64
	global_load_dwordx4 v[38:41], v[16:17], off offset:96
	v_lshl_add_u64 v[16:17], v[18:19], 0, v[0:1]
	global_load_dwordx4 v[30:33], v[16:17], off
	global_load_dwordx4 v[26:29], v[16:17], off offset:32
	global_load_dwordx4 v[18:21], v[16:17], off offset:64
	global_load_dwordx4 v[22:25], v[16:17], off offset:96
	v_lshlrev_b32_e32 v16, 2, v3
	v_sub_u32_e32 v17, v16, v210
	v_lshlrev_b32_e32 v168, 3, v3
	v_lshrrev_b32_e32 v3, 2, v2
	v_lshlrev_b32_e32 v147, 2, v17
	v_and_or_b32 v181, v3, 3, v16
	v_and_b32_e32 v3, 16, v2
	v_lshlrev_b32_e32 v2, 2, v2
	v_add_u32_e32 v211, 0x200, v147
	v_and_or_b32 v2, v2, 12, v3
	v_lshlrev_b32_e32 v182, 1, v2
	v_lshlrev_b32_e32 v171, 6, v70
	v_lshlrev_b32_e32 v172, 6, v71
	v_lshlrev_b32_e32 v173, 6, v72
	v_lshlrev_b32_e32 v174, 6, v73
	v_lshlrev_b32_e32 v175, 6, v74
	v_lshlrev_b32_e32 v176, 6, v75
	v_lshlrev_b32_e32 v177, 6, v76
	v_lshlrev_b32_e32 v178, 6, v77
	v_lshlrev_b32_e32 v2, 4, v209
	v_and_b32_e32 v2, 0x70, v2
	v_add_u32_e32 v179, s10, v2
	v_mad_u32_u24 v2, v70, s33, v179
	v_and_b32_e32 v3, 64, v228
	s_waitcnt vmcnt(15)
	ds_write_b128 v2, v[4:7]
	s_waitcnt vmcnt(14)
	ds_write_b128 v2, v[8:11] offset:1536
	s_waitcnt vmcnt(13)
	ds_write_b128 v2, v[12:15] offset:3072
	s_waitcnt vmcnt(12)
	ds_write_b128 v2, v[34:37] offset:4608
	s_waitcnt vmcnt(11)
	ds_write_b128 v2, v[54:57] offset:6144
	s_waitcnt vmcnt(10)
	ds_write_b128 v2, v[58:61] offset:7680
	s_waitcnt vmcnt(9)
	ds_write_b128 v2, v[62:65] offset:9216
	s_waitcnt vmcnt(8)
	ds_write_b128 v2, v[66:69] offset:10752
	v_xor_b32_e32 v2, 32, v228
	v_add_u32_e32 v3, 64, v3
	v_cmp_lt_i32_e32 vcc, v2, v3
	v_add_u32_e32 v212, s10, v147
	v_add_u32_e32 v55, 0x3200, v212
	v_cndmask_b32_e32 v2, v228, v2, vcc
	v_lshlrev_b32_e32 v208, 2, v2
	s_waitcnt vmcnt(7)
	v_mfma_f32_32x32x16_bf16 v[2:17], v[50:53], v[126:129], 0
	ds_read2_b32 v[36:37], v55 offset1:1
	v_add_u32_e32 v63, 0x3208, v212
	v_add_u32_e32 v65, 0x3220, v212
	v_add_u32_e32 v79, 0x3228, v212
	v_add_u32_e32 v81, 0x3240, v212
	v_add_u32_e32 v61, 0x3248, v212
	v_add_u32_e32 v59, 0x3260, v212
	s_waitcnt vmcnt(6)
	v_mfma_f32_32x32x16_bf16 v[2:17], v[46:49], v[114:117], v[2:17]
	v_add_u32_e32 v57, 0x3268, v212
	v_mul_u32_u24_e32 v180, 0xc0, v70
	v_add_u32_e32 v214, 0x3280, v212
	v_add_u32_e32 v213, 0x3288, v212
	v_add_u32_e32 v215, 0x32a0, v212
	v_add_u32_e32 v216, 0x32a8, v212
	v_add_u32_e32 v217, 0x32c0, v212
	s_waitcnt vmcnt(5)
	v_mfma_f32_32x32x16_bf16 v[2:17], v[42:45], v[118:121], v[2:17]
	v_add_u32_e32 v218, 0x32c8, v212
	v_add_u32_e32 v219, 0x32e0, v212
	v_add_u32_e32 v220, 0x32e8, v212
	v_add_u32_e32 v183, 0x3180, v212
	v_add_u32_e32 v184, 0x3188, v212
	v_add_u32_e32 v185, 0x31a0, v212
	v_add_u32_e32 v186, 0x31a8, v212
	s_waitcnt vmcnt(4)
; #define LAS __attribute__((address_space(3)))
; #define MFMA32(a, b, c) __builtin_amdgcn_mfma_f32_32x32x16_bf16((a), (b), (c), 0, 0, 0)
; template <int DELTA> ...
;     ...
;     for (int qh = 0; qh < 2; ++qh) {
;         f32x16 s[2]; float mx = -1e30f;
; #pragma unroll
;         for (int kvh = 0; kvh < 2; ++kvh) {
;             constexpr int dummy = 0; (void)dummy;
;             const int toff = 64 * DELTA + 32 * (kvh - qh);
;             if (toff > 64 || toff < -64) continue;
; #pragma unroll
;             for (int i = 0; i < 16; ++i) s[kvh][i] = 0.f;
; #pragma unroll
;             for (int d0 = 0; d0 < 4; ++d0) s[kvh] = MFMA32(kf[kvh][d0], qf[qh][d0], s[kvh]);
; #pragma unroll
;             for (int rr = 0; rr < 16; ++rr) { const int c4 = 4 * ((rr & 3) + 8 * (rr >> 2)); const float bias = *(const LAS float*)(wl + bvar + (VT_B + c4 + toff * 4));
;                 float v = s[kvh][rr] + bias;
;                 if (toff == 64) v = (bvar <= btb - c4) ? v : -1e30f;
;                 if (toff == -64) v = (bvar >= btb - c4) ? v : -1e30f;
;                 s[kvh][rr] = v; mx = fmaxf(mx, v); }
;         }
;         mx = fmaxf(mx, __shfl_xor(mx, 32));
;         const float m_new = fmaxf(m_run[qh], mx); const float alpha = __builtin_amdgcn_exp2f(m_run[qh] - m_new); m_run[qh] = m_new;
;         float ls = 0.f;
; #pragma unroll
;         for (int kvh = 0; kvh < 2; ++kvh) { const int toff = 64 * DELTA + 32 * (kvh - qh);
;             if (toff > 64 || toff < -64) continue;
; #pragma unroll
;             for (int rr = 0; rr < 16; ++rr) { const float e = __builtin_amdgcn_exp2f(s[kvh][rr] - m_new); s[kvh][rr] = e; ls += e; }
;             pb[qh][2 * kvh] = packp(s[kvh], 0); pb[qh][2 * kvh + 1] = packp(s[kvh], 8); }
	v_mfma_f32_32x32x16_bf16 v[2:17], v[38:41], v[122:125], v[2:17]
	v_add_u32_e32 v187, 0x31c0, v212
	v_add_u32_e32 v188, 0x31c8, v212
	v_add_u32_e32 v189, 0x31e0, v212
	v_add_u32_e32 v190, 0x31e8, v212
	s_cmp_lt_i32 s37, 1
	v_add_u32_e32 v233, v179, v180
	s_waitcnt lgkmcnt(0)
	s_nop 4
	v_add_f32_e32 v35, v2, v36
	v_add_f32_e32 v34, v3, v37
	ds_read2_b32 v[240:241], v63 offset1:1
	ds_read2_b32 v[242:243], v65 offset1:1
	ds_read2_b32 v[244:245], v79 offset1:1
	ds_read2_b32 v[246:247], v81 offset1:1
	ds_read2_b32 v[248:249], v61 offset1:1
	ds_read2_b32 v[250:251], v59 offset1:1
	ds_read2_b32 v[252:253], v57 offset1:1
	v_max3_f32 v36, v35, s79, v34
	s_waitcnt lgkmcnt(0)
	v_add_f32_e32 v54, v4, v240
	v_add_f32_e32 v56, v5, v241
	v_max3_f32 v4, v36, v54, v56
	ds_read2_b32 v[36:37], v214 offset1:1
	s_waitcnt lgkmcnt(1)
	v_add_f32_e32 v58, v6, v242
	v_add_f32_e32 v60, v7, v243
	v_max3_f32 v4, v4, v58, v60
	s_waitcnt lgkmcnt(0)
	v_add_f32_e32 v62, v8, v244
	v_add_f32_e32 v64, v9, v245
	v_max3_f32 v4, v4, v62, v64
	s_waitcnt lgkmcnt(0)
	v_add_f32_e32 v66, v10, v246
	v_add_f32_e32 v67, v11, v247
	v_max3_f32 v4, v4, v66, v67
	s_waitcnt lgkmcnt(0)
	v_add_f32_e32 v68, v12, v248
	v_add_f32_e32 v69, v13, v249
	v_max3_f32 v4, v4, v68, v69
	s_waitcnt lgkmcnt(0)
	v_add_f32_e32 v70, v14, v250
	v_add_f32_e32 v71, v15, v251
	v_max3_f32 v4, v4, v70, v71
	s_waitcnt lgkmcnt(0)
	v_add_f32_e32 v72, v16, v252
	v_add_f32_e32 v73, v17, v253
	v_max3_f32 v74, v4, v72, v73
	s_waitcnt vmcnt(3)
	v_mfma_f32_32x32x16_bf16 v[2:17], v[30:33], v[126:129], 0
	s_waitcnt vmcnt(2)
	v_mfma_f32_32x32x16_bf16 v[2:17], v[26:29], v[114:117], v[2:17]
	s_waitcnt vmcnt(1)
	v_mfma_f32_32x32x16_bf16 v[2:17], v[18:21], v[118:121], v[2:17]
	s_waitcnt vmcnt(0)
	v_mfma_f32_32x32x16_bf16 v[2:17], v[22:25], v[122:125], v[2:17]
	s_nop 11
	v_add_f32_e32 v75, v2, v36
	v_add_f32_e32 v76, v3, v37
	ds_read2_b32 v[240:241], v213 offset1:1
	ds_read2_b32 v[242:243], v215 offset1:1
	ds_read2_b32 v[244:245], v216 offset1:1
	ds_read2_b32 v[246:247], v217 offset1:1
	ds_read2_b32 v[248:249], v218 offset1:1
	ds_read2_b32 v[250:251], v219 offset1:1
	ds_read2_b32 v[252:253], v220 offset1:1
	v_max3_f32 v36, v74, v75, v76
	s_waitcnt lgkmcnt(0)
	v_add_f32_e32 v4, v4, v240
	v_add_f32_e32 v5, v5, v241
	v_max3_f32 v36, v36, v4, v5
	s_waitcnt lgkmcnt(0)
	v_add_f32_e32 v6, v6, v242
	v_add_f32_e32 v7, v7, v243
	v_max3_f32 v36, v36, v6, v7
	s_waitcnt lgkmcnt(0)
	v_add_f32_e32 v8, v8, v244
	v_add_f32_e32 v9, v9, v245
	v_max3_f32 v36, v36, v8, v9
	s_waitcnt lgkmcnt(0)
	v_add_f32_e32 v10, v10, v246
	v_add_f32_e32 v11, v11, v247
	v_max3_f32 v36, v36, v10, v11
	s_waitcnt lgkmcnt(0)
	v_add_f32_e32 v12, v12, v248
	v_add_f32_e32 v13, v13, v249
	v_max3_f32 v36, v36, v12, v13
	s_waitcnt lgkmcnt(0)
	v_add_f32_e32 v14, v14, v250
	v_add_f32_e32 v15, v15, v251
	v_max3_f32 v36, v36, v14, v15
	s_waitcnt lgkmcnt(0)
	v_add_f32_e32 v2, v16, v252
	v_add_f32_e32 v3, v17, v253
	v_max3_f32 v16, v36, v2, v3
	ds_bpermute_b32 v17, v208, v16
	s_waitcnt lgkmcnt(0)
	v_max3_f32 v170, v16, v17, s79
	v_sub_f32_e32 v17, v35, v170
	v_exp_f32_e32 v82, v17
	v_sub_f32_e32 v17, v34, v170
	v_exp_f32_e32 v84, v17
	v_sub_f32_e32 v17, v54, v170
	v_exp_f32_e32 v86, v17
	v_sub_f32_e32 v17, v56, v170
	v_exp_f32_e32 v88, v17
	v_sub_f32_e32 v17, v58, v170
	v_exp_f32_e32 v142, v17
	v_sub_f32_e32 v17, v60, v170
	v_exp_f32_e32 v148, v17
	v_sub_f32_e32 v17, v62, v170
	v_sub_f32_e32 v4, v4, v170
	v_exp_f32_e32 v150, v17
	v_sub_f32_e32 v17, v64, v170
	v_exp_f32_e32 v90, v4
	v_sub_f32_e32 v4, v5, v170
	v_exp_f32_e32 v156, v17
	v_sub_f32_e32 v17, v66, v170
	v_exp_f32_e32 v92, v4
	v_sub_f32_e32 v4, v6, v170
	v_exp_f32_e32 v144, v17
	v_sub_f32_e32 v17, v67, v170
	v_exp_f32_e32 v96, v4
	v_sub_f32_e32 v4, v7, v170
	v_exp_f32_e32 v152, v17
	v_sub_f32_e32 v17, v68, v170
	v_exp_f32_e32 v132, v4
	v_sub_f32_e32 v4, v8, v170
	v_exp_f32_e32 v154, v17
	v_sub_f32_e32 v17, v69, v170
	v_exp_f32_e32 v134, v4
	v_sub_f32_e32 v4, v9, v170
	v_exp_f32_e32 v158, v17
	v_sub_f32_e32 v17, v70, v170
	v_exp_f32_e32 v140, v4
	v_sub_f32_e32 v4, v10, v170
	v_exp_f32_e32 v160, v17
	v_sub_f32_e32 v17, v71, v170
	v_exp_f32_e32 v130, v4
	v_sub_f32_e32 v4, v11, v170
	v_exp_f32_e32 v162, v17
	v_sub_f32_e32 v17, v72, v170
	v_exp_f32_e32 v136, v4
	v_sub_f32_e32 v4, v12, v170
	v_exp_f32_e32 v164, v17
	v_sub_f32_e32 v17, v73, v170
	v_exp_f32_e32 v138, v4
	v_sub_f32_e32 v4, v13, v170
	v_exp_f32_e32 v166, v17
	v_sub_f32_e32 v17, v75, v170
	v_exp_f32_e32 v56, v4
	v_sub_f32_e32 v4, v14, v170
	v_sub_f32_e32 v2, v2, v170
	v_sub_f32_e32 v16, 0xf149f2ca, v170
	v_exp_f32_e32 v78, v17
	v_sub_f32_e32 v17, v76, v170
	v_exp_f32_e32 v58, v4
	v_sub_f32_e32 v4, v15, v170
	v_exp_f32_e32 v62, v2
	v_sub_f32_e32 v2, v3, v170
	v_exp_f32_e32 v80, v17
	v_exp_f32_e32 v60, v4
	v_exp_f32_e32 v64, v2
	v_exp_f32_e32 v54, v16
	v_mfma_f32_32x32x16_bf16 v[2:17], v[50:53], v[110:113], 0
	v_cvt_pk_bf16_f32 v34, v82, v84
	v_cvt_pk_bf16_f32 v35, v86, v88
	v_cvt_pk_bf16_f32 v36, v142, v148
	v_cvt_pk_bf16_f32 v37, v150, v156
	v_cvt_pk_bf16_f32 v70, v144, v152
	v_cvt_pk_bf16_f32 v71, v154, v158
	v_cvt_pk_bf16_f32 v72, v160, v162
	v_mfma_f32_32x32x16_bf16 v[2:17], v[46:49], v[106:109], v[2:17]
	v_cvt_pk_bf16_f32 v73, v164, v166
	v_cvt_pk_bf16_f32 v74, v78, v80
	v_cvt_pk_bf16_f32 v75, v90, v92
	v_cvt_pk_bf16_f32 v76, v96, v132
	v_cvt_pk_bf16_f32 v77, v134, v140
	v_cvt_pk_bf16_f32 v66, v130, v136
	v_cvt_pk_bf16_f32 v67, v138, v56
	v_mfma_f32_32x32x16_bf16 v[2:17], v[42:45], v[98:101], v[2:17]
	v_cvt_pk_bf16_f32 v68, v58, v60
	v_cvt_pk_bf16_f32 v69, v62, v64
	v_mfma_f32_32x32x16_bf16 v[2:17], v[38:41], v[102:105], v[2:17]
	ds_read2_b32 v[38:39], v183 offset1:1
	s_waitcnt lgkmcnt(0)
; #define LAS __attribute__((address_space(3)))
; #define MFMA32(a, b, c) __builtin_amdgcn_mfma_f32_32x32x16_bf16((a), (b), (c), 0, 0, 0)
; template <int DELTA> ...
;     ...
;     for (int qh = 0; qh < 2; ++qh) {
;         f32x16 s[2]; float mx = -1e30f;
; #pragma unroll
;         for (int kvh = 0; kvh < 2; ++kvh) {
;             constexpr int dummy = 0; (void)dummy;
;             const int toff = 64 * DELTA + 32 * (kvh - qh);
;             if (toff > 64 || toff < -64) continue;
; #pragma unroll
;             for (int i = 0; i < 16; ++i) s[kvh][i] = 0.f;
; #pragma unroll
;             for (int d0 = 0; d0 < 4; ++d0) s[kvh] = MFMA32(kf[kvh][d0], qf[qh][d0], s[kvh]);
; #pragma unroll
;             for (int rr = 0; rr < 16; ++rr) { const int c4 = 4 * ((rr & 3) + 8 * (rr >> 2)); const float bias = *(const LAS float*)(wl + bvar + (VT_B + c4 + toff * 4));
;                 float v = s[kvh][rr] + bias;
;                 if (toff == 64) v = (bvar <= btb - c4) ? v : -1e30f;
;                 if (toff == -64) v = (bvar >= btb - c4) ? v : -1e30f;
;                 s[kvh][rr] = v; mx = fmaxf(mx, v); }
;         }
;         mx = fmaxf(mx, __shfl_xor(mx, 32));
;         const float m_new = fmaxf(m_run[qh], mx); const float alpha = __builtin_amdgcn_exp2f(m_run[qh] - m_new); m_run[qh] = m_new;
;         float ls = 0.f;
; #pragma unroll
;         for (int kvh = 0; kvh < 2; ++kvh) { const int toff = 64 * DELTA + 32 * (kvh - qh);
;             if (toff > 64 || toff < -64) continue;
; #pragma unroll
;             for (int rr = 0; rr < 16; ++rr) { const float e = __builtin_amdgcn_exp2f(s[kvh][rr] - m_new); s[kvh][rr] = e; ls += e; }
;             pb[qh][2 * kvh] = packp(s[kvh], 0); pb[qh][2 * kvh + 1] = packp(s[kvh], 8); }
;         l_run[qh] = l_run[qh] * alpha + ls;
	s_nop 9
	v_add_f32_e32 v40, v2, v38
	v_add_f32_e32 v39, v3, v39
	ds_read2_b32 v[240:241], v184 offset1:1
	ds_read2_b32 v[242:243], v185 offset1:1
	ds_read2_b32 v[244:245], v186 offset1:1
	ds_read2_b32 v[246:247], v187 offset1:1
	ds_read2_b32 v[248:249], v188 offset1:1
	ds_read2_b32 v[250:251], v189 offset1:1
	ds_read2_b32 v[252:253], v190 offset1:1
	v_max3_f32 v38, v40, s79, v39
	s_waitcnt lgkmcnt(0)
	v_add_f32_e32 v41, v4, v240
	v_add_f32_e32 v42, v5, v241
	v_max3_f32 v4, v38, v41, v42
	s_waitcnt lgkmcnt(0)
	v_add_f32_e32 v43, v6, v242
	v_add_f32_e32 v38, v7, v243
	v_max3_f32 v4, v4, v43, v38
	s_waitcnt lgkmcnt(0)
	v_add_f32_e32 v44, v8, v244
	v_add_f32_e32 v45, v9, v245
	v_max3_f32 v4, v4, v44, v45
	s_waitcnt lgkmcnt(0)
	v_add_f32_e32 v46, v10, v246
	v_add_f32_e32 v47, v11, v247
	v_max3_f32 v4, v4, v46, v47
	s_waitcnt lgkmcnt(0)
	v_add_f32_e32 v48, v12, v248
	v_add_f32_e32 v49, v13, v249
	v_max3_f32 v4, v4, v48, v49
	s_waitcnt lgkmcnt(0)
	v_add_f32_e32 v50, v14, v250
	v_add_f32_e32 v51, v15, v251
	v_max3_f32 v4, v4, v50, v51
	s_waitcnt lgkmcnt(0)
	v_add_f32_e32 v52, v16, v252
	v_add_f32_e32 v53, v17, v253
	v_max3_f32 v83, v4, v52, v53
	v_mfma_f32_32x32x16_bf16 v[2:17], v[30:33], v[110:113], 0
	v_mfma_f32_32x32x16_bf16 v[2:17], v[26:29], v[106:109], v[2:17]
	v_mfma_f32_32x32x16_bf16 v[2:17], v[18:21], v[98:101], v[2:17]
	ds_read2_b32 v[18:19], v55 offset1:1
	v_mfma_f32_32x32x16_bf16 v[2:17], v[22:25], v[102:105], v[2:17]
	s_waitcnt lgkmcnt(0)
	s_nop 10
	v_add_f32_e32 v18, v2, v18
	v_add_f32_e32 v19, v3, v19
	ds_read2_b32 v[240:241], v63 offset1:1
	ds_read2_b32 v[242:243], v65 offset1:1
	ds_read2_b32 v[244:245], v79 offset1:1
	ds_read2_b32 v[246:247], v81 offset1:1
	ds_read2_b32 v[248:249], v61 offset1:1
	ds_read2_b32 v[250:251], v59 offset1:1
	ds_read2_b32 v[252:253], v57 offset1:1
	v_max3_f32 v20, v83, v18, v19
	s_waitcnt lgkmcnt(0)
	v_add_f32_e32 v4, v4, v240
	v_add_f32_e32 v5, v5, v241
	v_max3_f32 v20, v20, v4, v5
	s_waitcnt lgkmcnt(0)
	v_add_f32_e32 v6, v6, v242
	v_add_f32_e32 v7, v7, v243
	v_max3_f32 v20, v20, v6, v7
	s_waitcnt lgkmcnt(0)
	v_add_f32_e32 v8, v8, v244
	v_add_f32_e32 v9, v9, v245
	v_max3_f32 v20, v20, v8, v9
	s_waitcnt lgkmcnt(0)
	v_add_f32_e32 v10, v10, v246
	v_add_f32_e32 v11, v11, v247
	v_max3_f32 v20, v20, v10, v11
	s_waitcnt lgkmcnt(0)
	v_add_f32_e32 v12, v12, v248
	v_add_f32_e32 v13, v13, v249
	v_max3_f32 v20, v20, v12, v13
	s_waitcnt lgkmcnt(0)
	v_add_f32_e32 v14, v14, v250
	v_add_f32_e32 v15, v15, v251
	v_max3_f32 v20, v20, v14, v15
	s_waitcnt lgkmcnt(0)
	v_add_f32_e32 v16, v16, v252
	v_add_f32_e32 v17, v17, v253
	v_max3_f32 v2, v20, v16, v17
	ds_bpermute_b32 v3, v208, v2
	s_waitcnt lgkmcnt(0)
	v_max3_f32 v223, v2, v3, s79
	v_sub_f32_e32 v2, v40, v223
	v_exp_f32_e32 v83, v2
	v_sub_f32_e32 v2, v39, v223
	v_exp_f32_e32 v85, v2
	v_sub_f32_e32 v2, v41, v223
	v_exp_f32_e32 v87, v2
	v_sub_f32_e32 v2, v42, v223
	v_exp_f32_e32 v89, v2
	v_sub_f32_e32 v2, v43, v223
	v_exp_f32_e32 v143, v2
	v_pk_add_f32 v[2:3], v[82:83], 0 op_sel_hi:[1,0]
	v_sub_f32_e32 v21, v38, v223
	v_pk_add_f32 v[2:3], v[84:85], v[2:3]
	v_exp_f32_e32 v149, v21
	v_sub_f32_e32 v21, v44, v223
	v_pk_add_f32 v[2:3], v[86:87], v[2:3]
	v_exp_f32_e32 v151, v21
	v_sub_f32_e32 v21, v45, v223
	v_pk_add_f32 v[2:3], v[88:89], v[2:3]
	v_exp_f32_e32 v157, v21
	v_sub_f32_e32 v21, v46, v223
	v_pk_add_f32 v[2:3], v[142:143], v[2:3]
	v_exp_f32_e32 v145, v21
	v_sub_f32_e32 v21, v47, v223
	v_exp_f32_e32 v153, v21
	v_sub_f32_e32 v21, v48, v223
	v_pk_add_f32 v[2:3], v[148:149], v[2:3]
	v_exp_f32_e32 v155, v21
	v_sub_f32_e32 v21, v49, v223
	v_pk_add_f32 v[2:3], v[150:151], v[2:3]
	v_exp_f32_e32 v159, v21
	v_sub_f32_e32 v21, v50, v223
	v_pk_add_f32 v[2:3], v[156:157], v[2:3]
	v_exp_f32_e32 v161, v21
	v_sub_f32_e32 v21, v51, v223
	v_pk_add_f32 v[2:3], v[144:145], v[2:3]
	v_exp_f32_e32 v163, v21
	v_sub_f32_e32 v21, v52, v223
	v_pk_add_f32 v[2:3], v[152:153], v[2:3]
	v_exp_f32_e32 v165, v21
	v_sub_f32_e32 v21, v53, v223
	v_pk_add_f32 v[2:3], v[154:155], v[2:3]
	v_exp_f32_e32 v167, v21
	v_pk_add_f32 v[2:3], v[158:159], v[2:3]
	v_sub_f32_e32 v18, v18, v223
	v_pk_add_f32 v[2:3], v[160:161], v[2:3]
	v_exp_f32_e32 v79, v18
	v_sub_f32_e32 v18, v19, v223
	v_pk_add_f32 v[2:3], v[162:163], v[2:3]
	v_exp_f32_e32 v81, v18
	v_sub_f32_e32 v4, v4, v223
	v_pk_add_f32 v[2:3], v[164:165], v[2:3]
	v_exp_f32_e32 v91, v4
	v_sub_f32_e32 v4, v5, v223
	v_pk_add_f32 v[2:3], v[166:167], v[2:3]
	v_exp_f32_e32 v93, v4
	v_sub_f32_e32 v4, v6, v223
	v_exp_f32_e32 v97, v4
	v_sub_f32_e32 v4, v7, v223
	v_pk_add_f32 v[2:3], v[78:79], v[2:3]
	v_exp_f32_e32 v133, v4
	v_sub_f32_e32 v4, v8, v223
	v_pk_add_f32 v[2:3], v[80:81], v[2:3]
	v_exp_f32_e32 v135, v4
	v_sub_f32_e32 v4, v9, v223
	v_pk_add_f32 v[2:3], v[90:91], v[2:3]
	v_exp_f32_e32 v141, v4
	v_sub_f32_e32 v4, v10, v223
	v_pk_add_f32 v[2:3], v[92:93], v[2:3]
	v_exp_f32_e32 v131, v4
	v_sub_f32_e32 v4, v11, v223
	v_pk_add_f32 v[2:3], v[96:97], v[2:3]
	v_exp_f32_e32 v137, v4
	v_sub_f32_e32 v4, v12, v223
	v_pk_add_f32 v[2:3], v[132:133], v[2:3]
	v_exp_f32_e32 v139, v4
	v_pk_add_f32 v[2:3], v[134:135], v[2:3]
	v_sub_f32_e32 v4, v13, v223
	v_pk_add_f32 v[2:3], v[140:141], v[2:3]
	v_exp_f32_e32 v57, v4
	v_sub_f32_e32 v4, v14, v223
	v_pk_add_f32 v[2:3], v[130:131], v[2:3]
	v_exp_f32_e32 v59, v4
	v_sub_f32_e32 v4, v15, v223
	v_pk_add_f32 v[2:3], v[136:137], v[2:3]
	v_exp_f32_e32 v61, v4
	v_sub_f32_e32 v4, v16, v223
	v_mov_b32_e32 v38, s10
	v_sub_f32_e32 v20, 0xf149f2ca, v223
	v_pk_add_f32 v[2:3], v[138:139], v[2:3]
	v_exp_f32_e32 v63, v4
	v_sub_f32_e32 v4, v17, v223
	v_mad_u32_u24 v38, v181, s33, v38
	v_cvt_pk_bf16_f32 v86, v83, v85
	v_cvt_pk_bf16_f32 v87, v87, v89
	v_cvt_pk_bf16_f32 v88, v143, v149
	v_cvt_pk_bf16_f32 v89, v151, v157
	v_cvt_pk_bf16_f32 v82, v145, v153
	v_cvt_pk_bf16_f32 v83, v155, v159
	v_cvt_pk_bf16_f32 v84, v161, v163
	v_cvt_pk_bf16_f32 v85, v165, v167
	v_exp_f32_e32 v65, v4
	v_cvt_pk_bf16_f32 v90, v79, v81
	v_cvt_pk_bf16_f32 v91, v91, v93
	v_cvt_pk_bf16_f32 v92, v97, v133
	v_cvt_pk_bf16_f32 v93, v135, v141
	v_cvt_pk_bf16_f32 v78, v131, v137
	v_cvt_pk_bf16_f32 v79, v139, v57
	v_cvt_pk_bf16_f32 v80, v59, v61
	v_cvt_pk_bf16_f32 v81, v63, v65
	v_exp_f32_e32 v55, v20
	v_pk_add_f32 v[2:3], v[56:57], v[2:3]
	s_waitcnt lgkmcnt(0)
; #define LAS __attribute__((address_space(3)))
; #define LDS_WAIT() asm volatile("s_waitcnt lgkmcnt(0)" ::: "memory")
; __device__ __forceinline__ s16x4 vtr(const LAS unsigned char* p) { return __builtin_bit_cast(s16x4, __builtin_amdgcn_ds_read_tr16_b64_v4i16((LAS v4i16_t*)p)); }
; __device__ __forceinline__ bf16x8 cat8(s16x4 a, s16x4 b) { return (bf16x8){a[0], a[1], a[2], a[3], b[0], b[1], b[2], b[3]}; }
; #define MFMA32(a, b, c) __builtin_amdgcn_mfma_f32_32x32x16_bf16((a), (b), (c), 0, 0, 0)
; #define SBAR0() __builtin_amdgcn_sched_barrier(0)
; template <int DELTA> ...
;     u32x4 vv[8]; bf16x8 kf[2][4];
; #pragma unroll
;     for (int i = 0; i < 8; ++i) { const int idx = lane + 64 * i, row = idx >> 3, ch = idx & 7; vv[i] = *(const u32x4*)(vbase + (size_t)row * rstride + ch * 8); }
; #pragma unroll
;     for (int kvh = 0; kvh < 2; ++kvh)
; #pragma unroll
;         for (int d0 = 0; d0 < 4; ++d0) kf[kvh][d0] = *(const bf16x8*)(kbase + (size_t)(32 * kvh + r32) * rstride + d0 * 16);
;     SBAR0();
; #pragma unroll
;     for (int i = 0; i < 8; ++i) { const int idx = lane + 64 * i, row = idx >> 3, ch = idx & 7; *(LAS u32x4*)(wl + row * VP + ch * 16) = vv[i]; }
;     ...
;         l_run[qh] = l_run[qh] * alpha + ls;
; #pragma unroll
;         for (int i = 0; i < 16; ++i) { o[qh][0][i] *= alpha; o[qh][1][i] *= alpha; }
;     }
;     LDS_WAIT();
; #pragma unroll
;     for (int j = 0; j < 4; ++j) { const LAS unsigned char* vj = wl + voff + 16 * j * VP;
;         const bf16x8 a0 = cat8(vtr(vj), vtr(vj + 8 * VP)); const bf16x8 a1 = cat8(vtr(vj + 64), vtr(vj + 8 * VP + 64));
; #pragma unroll
;         for (int qh = 0; qh < 2; ++qh) { const int toff = 64 * DELTA + 32 * ((j >> 1) - qh);
;             if (toff > 64 || toff < -64) continue;
;             o[qh][0] = MFMA32(a0, pb[qh][j], o[qh][0]); o[qh][1] = MFMA32(a1, pb[qh][j], o[qh][1]); } }
;     LDS_WAIT();
; }
	v_add_u32_e32 v222, v38, v182
	v_pk_add_f32 v[2:3], v[58:59], v[2:3]
	ds_read_b64_tr_b16 v[130:131], v222
	ds_read_b64_tr_b16 v[132:133], v222 offset:1536
	ds_read_b64_tr_b16 v[134:135], v222 offset:64
	ds_read_b64_tr_b16 v[136:137], v222 offset:1600
	v_pk_add_f32 v[2:3], v[60:61], v[2:3]
	v_lshlrev_b32_e32 v156, 1, v168
	v_pk_add_f32 v[2:3], v[62:63], v[2:3]
	v_lshlrev_b32_e32 v168, 1, v171
	v_pk_add_f32 v[4:5], v[64:65], v[2:3]
	v_pk_mul_f32 v[2:3], v[54:55], 0 op_sel_hi:[1,0]
	v_pk_fma_f32 v[154:155], v[54:55], 0, v[4:5] op_sel_hi:[1,0,1]
	v_mov_b32_e32 v18, v2
	v_mov_b32_e32 v19, v2
	v_mov_b32_e32 v20, v2
	v_mov_b32_e32 v21, v2
	v_mov_b32_e32 v22, v2
	v_mov_b32_e32 v23, v2
	v_mov_b32_e32 v24, v2
	v_mov_b32_e32 v25, v2
	v_mov_b32_e32 v26, v2
	v_mov_b32_e32 v27, v2
	v_mov_b32_e32 v28, v2
	v_mov_b32_e32 v29, v2
	v_mov_b32_e32 v30, v2
	v_mov_b32_e32 v31, v2
	v_mov_b32_e32 v32, v2
	v_mov_b32_e32 v33, v2
	v_mov_b32_e32 v2, v3
	v_mov_b32_e32 v4, v3
	v_mov_b32_e32 v5, v3
	v_mov_b32_e32 v6, v3
	v_mov_b32_e32 v7, v3
	v_mov_b32_e32 v8, v3
	v_mov_b32_e32 v9, v3
	v_mov_b32_e32 v10, v3
	v_mov_b32_e32 v11, v3
	v_mov_b32_e32 v12, v3
	v_mov_b32_e32 v13, v3
	v_mov_b32_e32 v14, v3
	v_mov_b32_e32 v15, v3
	v_mov_b32_e32 v16, v3
	v_mov_b32_e32 v17, v3
	s_waitcnt lgkmcnt(2)
	v_mfma_f32_32x32x16_bf16 v[50:65], v[130:133], v[34:37], v[18:33]
	v_lshlrev_b32_e32 v166, 1, v172
	v_lshlrev_b32_e32 v164, 1, v173
	v_lshlrev_b32_e32 v162, 1, v174
	v_lshlrev_b32_e32 v160, 1, v175
	v_lshlrev_b32_e32 v158, 1, v176
	v_lshlrev_b32_e32 v152, 1, v177
	v_lshlrev_b32_e32 v150, 1, v178
	s_waitcnt lgkmcnt(0)
	v_mfma_f32_32x32x16_bf16 v[18:33], v[134:137], v[34:37], v[18:33]
	v_lshlrev_b32_e32 v148, 1, v169
	v_mfma_f32_32x32x16_bf16 v[34:49], v[130:133], v[86:89], v[2:17]
	v_mfma_f32_32x32x16_bf16 v[2:17], v[134:137], v[86:89], v[2:17]
	ds_read_b64_tr_b16 v[86:87], v222 offset:3072
	ds_read_b64_tr_b16 v[88:89], v222 offset:4608
	ds_read_b64_tr_b16 v[130:131], v222 offset:3136
	ds_read_b64_tr_b16 v[132:133], v222 offset:4672
	s_waitcnt lgkmcnt(2)
	v_mfma_f32_32x32x16_bf16 v[50:65], v[86:89], v[70:73], v[50:65]
	s_waitcnt lgkmcnt(0)
	v_mfma_f32_32x32x16_bf16 v[18:33], v[130:133], v[70:73], v[18:33]
	v_mfma_f32_32x32x16_bf16 v[34:49], v[86:89], v[82:85], v[34:49]
	v_mfma_f32_32x32x16_bf16 v[2:17], v[130:133], v[82:85], v[2:17]
	ds_read_b64_tr_b16 v[70:71], v222 offset:6144
	ds_read_b64_tr_b16 v[72:73], v222 offset:7680
	ds_read_b64_tr_b16 v[82:83], v222 offset:6208
	ds_read_b64_tr_b16 v[84:85], v222 offset:7744
	s_waitcnt lgkmcnt(2)
	v_mfma_f32_32x32x16_bf16 v[50:65], v[70:73], v[74:77], v[50:65]
	s_waitcnt lgkmcnt(0)
	v_mfma_f32_32x32x16_bf16 v[18:33], v[82:85], v[74:77], v[18:33]
	v_mfma_f32_32x32x16_bf16 v[34:49], v[70:73], v[90:93], v[34:49]
	ds_read_b64_tr_b16 v[70:71], v222 offset:9216
	ds_read_b64_tr_b16 v[72:73], v222 offset:10752
	ds_read_b64_tr_b16 v[74:75], v222 offset:9280
	ds_read_b64_tr_b16 v[76:77], v222 offset:10816
	s_waitcnt lgkmcnt(0)
	v_mfma_f32_32x32x16_bf16 v[2:17], v[82:85], v[90:93], v[2:17]
	s_waitcnt lgkmcnt(2)
	v_mfma_f32_32x32x16_bf16 v[50:65], v[70:73], v[66:69], v[50:65]
	s_waitcnt lgkmcnt(0)
	v_mfma_f32_32x32x16_bf16 v[18:33], v[74:77], v[66:69], v[18:33]
	v_mfma_f32_32x32x16_bf16 v[34:49], v[70:73], v[78:81], v[34:49]
	v_mfma_f32_32x32x16_bf16 v[2:17], v[74:77], v[78:81], v[2:17]
	s_cbranch_scc1 .LBB0_440
	v_mov_b32_e32 v157, v1
	v_lshl_add_u64 v[66:67], s[6:7], 0, v[156:157]
	s_mov_b64 s[38:39], 0x3ffe000
	v_lshl_add_u64 v[70:71], v[66:67], 0, s[38:39]
	s_mov_b64 s[38:39], 0x7ffe000
	v_lshl_add_u64 v[66:67], v[94:95], 0, s[38:39]
	v_mov_b32_e32 v169, v1
	v_mov_b32_e32 v167, v1
	v_lshl_add_u64 v[68:69], v[66:67], 0, v[168:169]
	v_lshl_add_u64 v[72:73], v[66:67], 0, v[166:167]
	v_mov_b32_e32 v165, v1
	v_mov_b32_e32 v163, v1
	global_load_dwordx4 v[82:85], v[68:69], off
	global_load_dwordx4 v[86:89], v[72:73], off
	v_lshl_add_u64 v[68:69], v[66:67], 0, v[164:165]
	v_lshl_add_u64 v[72:73], v[66:67], 0, v[162:163]
	v_mov_b32_e32 v161, v1
	v_mov_b32_e32 v159, v1
	global_load_dwordx4 v[90:93], v[68:69], off
	global_load_dwordx4 v[94:97], v[72:73], off
	v_lshl_add_u64 v[68:69], v[66:67], 0, v[160:161]
	v_lshl_add_u64 v[72:73], v[66:67], 0, v[158:159]
	v_mov_b32_e32 v153, v1
	v_mov_b32_e32 v151, v1
	v_mov_b32_e32 v149, v1
	global_load_dwordx4 v[172:175], v[68:69], off
	global_load_dwordx4 v[176:179], v[72:73], off
	v_lshl_add_u64 v[68:69], v[66:67], 0, v[152:153]
	v_lshl_add_u64 v[66:67], v[66:67], 0, v[150:151]
	v_lshl_add_u64 v[72:73], v[70:71], 0, v[148:149]
	v_lshl_add_u64 v[70:71], v[70:71], 0, v[0:1]
	global_load_dwordx4 v[192:195], v[68:69], off
	global_load_dwordx4 v[196:199], v[66:67], off
	s_nop 0
	global_load_dwordx4 v[66:69], v[72:73], off
	global_load_dwordx4 v[200:203], v[72:73], off offset:32
	global_load_dwordx4 v[204:207], v[72:73], off offset:64
	global_load_dwordx4 v[234:237], v[72:73], off offset:96
	global_load_dwordx4 v[142:145], v[70:71], off
	global_load_dwordx4 v[138:141], v[70:71], off offset:32
	global_load_dwordx4 v[134:137], v[70:71], off offset:64
	global_load_dwordx4 v[130:133], v[70:71], off offset:96
	s_waitcnt vmcnt(7)
	v_mfma_f32_32x32x16_bf16 v[66:81], v[66:69], v[126:129], 0
	ds_write_b128 v233, v[82:85]
	ds_write_b128 v233, v[86:89] offset:1536
	ds_write_b128 v233, v[90:93] offset:3072
	ds_write_b128 v233, v[94:97] offset:4608
	ds_write_b128 v233, v[172:175] offset:6144
	ds_write_b128 v233, v[176:179] offset:7680
	ds_write_b128 v233, v[192:195] offset:9216
	ds_write_b128 v233, v[196:199] offset:10752
	v_add_u32_e32 v171, 0x3100, v212
	v_add_u32_e32 v173, 0x3108, v212
	v_add_u32_e32 v175, 0x3120, v212
	v_add_u32_e32 v177, 0x3128, v212
	ds_read2_b32 v[82:83], v171 offset1:1
	ds_read2_b32 v[84:85], v173 offset1:1
	ds_read2_b32 v[86:87], v175 offset1:1
	ds_read2_b32 v[88:89], v177 offset1:1
	s_waitcnt vmcnt(6)
; #define LAS __attribute__((address_space(3)))
; #define MFMA32(a, b, c) __builtin_amdgcn_mfma_f32_32x32x16_bf16((a), (b), (c), 0, 0, 0)
; template <int DELTA> ...
;     ...
;     for (int qh = 0; qh < 2; ++qh) {
;         f32x16 s[2]; float mx = -1e30f;
; #pragma unroll
;         for (int kvh = 0; kvh < 2; ++kvh) {
;             constexpr int dummy = 0; (void)dummy;
;             const int toff = 64 * DELTA + 32 * (kvh - qh);
;             if (toff > 64 || toff < -64) continue;
; #pragma unroll
;             for (int i = 0; i < 16; ++i) s[kvh][i] = 0.f;
; #pragma unroll
;             for (int d0 = 0; d0 < 4; ++d0) s[kvh] = MFMA32(kf[kvh][d0], qf[qh][d0], s[kvh]);
; #pragma unroll
;             for (int rr = 0; rr < 16; ++rr) { const int c4 = 4 * ((rr & 3) + 8 * (rr >> 2)); const float bias = *(const LAS float*)(wl + bvar + (VT_B + c4 + toff * 4));
;                 float v = s[kvh][rr] + bias;
;                 if (toff == 64) v = (bvar <= btb - c4) ? v : -1e30f;
;                 if (toff == -64) v = (bvar >= btb - c4) ? v : -1e30f;
;                 s[kvh][rr] = v; mx = fmaxf(mx, v); }
;         }
;         mx = fmaxf(mx, __shfl_xor(mx, 32));
	v_mfma_f32_32x32x16_bf16 v[66:81], v[200:203], v[114:117], v[66:81]
	v_cmp_lt_u32_e32 vcc, s84, v147
	v_cmp_gt_u32_e64 s[40:41], s74, v211
	v_cmp_gt_u32_e64 s[42:43], s24, v211
	v_cmp_gt_u32_e64 s[44:45], s25, v211
	v_cmp_gt_u32_e64 s[48:49], s20, v211
	v_cmp_gt_u32_e64 s[46:47], s26, v211
	v_cmp_gt_u32_e64 s[52:53], s28, v211
	s_waitcnt vmcnt(5)
	v_mfma_f32_32x32x16_bf16 v[66:81], v[204:207], v[118:121], v[66:81]
	v_cmp_gt_u32_e64 s[50:51], s90, v211
	v_add_u32_e32 v179, 0x3140, v212
	v_cmp_gt_u32_e64 s[54:55], s91, v211
	v_cmp_gt_u32_e64 s[56:57], s76, v211
	v_add_u32_e32 v181, 0x3148, v212
	v_add_u32_e32 v191, 0x3160, v212
	v_add_u32_e32 v193, 0x3168, v212
	s_waitcnt vmcnt(4)
	v_mfma_f32_32x32x16_bf16 v[66:81], v[234:237], v[122:125], v[66:81]
	v_cmp_gt_u32_e64 s[58:59], s80, v211
	v_cmp_gt_u32_e64 s[60:61], s81, v211
	v_cmp_gt_u32_e64 s[62:63], s27, v211
	v_cmp_gt_u32_e64 s[64:65], s78, v211
	v_cmp_gt_u32_e64 s[66:67], s77, v211
	v_cmp_gt_u32_e64 s[68:69], s36, v211
	s_waitcnt lgkmcnt(3)
	s_nop 4
	v_add_f32_e32 v66, v66, v82
	v_add_f32_e32 v67, v67, v83
	s_waitcnt lgkmcnt(2)
	v_add_f32_e32 v68, v68, v84
	v_add_f32_e32 v69, v69, v85
	v_cndmask_b32_e32 v149, v66, v230, vcc
	v_cndmask_b32_e64 v151, v67, v230, s[40:41]
	s_waitcnt lgkmcnt(1)
	v_add_f32_e32 v67, v71, v87
	v_add_f32_e32 v70, v70, v86
	v_cndmask_b32_e64 v153, v68, v230, s[42:43]
	v_cndmask_b32_e64 v157, v69, v230, s[44:45]
	v_max3_f32 v66, v149, s79, v151
	v_cndmask_b32_e64 v161, v67, v230, s[48:49]
	s_waitcnt lgkmcnt(0)
	v_add_f32_e32 v67, v72, v88
	v_max3_f32 v66, v66, v153, v157
	v_cndmask_b32_e64 v159, v70, v230, s[46:47]
	v_cndmask_b32_e64 v163, v67, v230, s[52:53]
	v_add_f32_e32 v67, v73, v89
	v_max3_f32 v66, v66, v159, v161
	v_cndmask_b32_e64 v165, v67, v230, s[50:51]
	v_max3_f32 v82, v66, v163, v165
	ds_read2_b32 v[66:67], v179 offset1:1
	ds_read2_b32 v[68:69], v181 offset1:1
	ds_read2_b32 v[70:71], v191 offset1:1
	ds_read2_b32 v[72:73], v193 offset1:1
	s_waitcnt lgkmcnt(3)
	v_add_f32_e32 v66, v74, v66
	v_cndmask_b32_e64 v74, v66, v230, s[54:55]
	v_add_f32_e32 v66, v75, v67
	v_cndmask_b32_e64 v75, v66, v230, s[56:57]
	v_max3_f32 v66, v82, v74, v75
	s_waitcnt vmcnt(3)
	v_mfma_f32_32x32x16_bf16 v[82:97], v[142:145], v[126:129], 0
	s_waitcnt lgkmcnt(2)
	v_add_f32_e32 v67, v76, v68
	v_cndmask_b32_e64 v76, v67, v230, s[58:59]
	v_add_f32_e32 v67, v77, v69
	v_cndmask_b32_e64 v77, v67, v230, s[60:61]
	s_waitcnt lgkmcnt(1)
	v_add_f32_e32 v67, v78, v70
	v_cndmask_b32_e64 v78, v67, v230, s[62:63]
	v_add_f32_e32 v67, v79, v71
	s_waitcnt vmcnt(2)
	v_mfma_f32_32x32x16_bf16 v[82:97], v[138:141], v[114:117], v[82:97]
	v_cndmask_b32_e64 v79, v67, v230, s[64:65]
	s_waitcnt lgkmcnt(0)
	v_add_f32_e32 v67, v80, v72
	v_max3_f32 v66, v66, v76, v77
	v_cndmask_b32_e64 v80, v67, v230, s[66:67]
	v_add_f32_e32 v67, v81, v73
	v_max3_f32 v66, v66, v78, v79
	v_cndmask_b32_e64 v81, v67, v230, s[68:69]
	s_waitcnt vmcnt(1)
	v_mfma_f32_32x32x16_bf16 v[82:97], v[134:137], v[118:121], v[82:97]
	v_max3_f32 v147, v66, v80, v81
	ds_read2_b32 v[66:67], v183 offset1:1
	ds_read2_b32 v[68:69], v184 offset1:1
	ds_read2_b32 v[70:71], v185 offset1:1
	ds_read2_b32 v[72:73], v186 offset1:1
	s_waitcnt vmcnt(0)
	v_mfma_f32_32x32x16_bf16 v[82:97], v[130:133], v[122:125], v[82:97]
	s_waitcnt lgkmcnt(3)
	s_nop 10
	v_add_f32_e32 v172, v82, v66
	v_add_f32_e32 v174, v83, v67
	ds_read2_b32 v[66:67], v187 offset1:1
	s_waitcnt lgkmcnt(3)
	v_add_f32_e32 v176, v84, v68
	v_add_f32_e32 v180, v85, v69
	s_waitcnt lgkmcnt(2)
	v_add_f32_e32 v182, v86, v70
	v_add_f32_e32 v183, v87, v71
	s_waitcnt lgkmcnt(1)
	v_add_f32_e32 v184, v88, v72
	v_add_f32_e32 v185, v89, v73
	ds_read2_b32 v[68:69], v188 offset1:1
	ds_read2_b32 v[70:71], v189 offset1:1
	ds_read2_b32 v[72:73], v190 offset1:1
	s_waitcnt lgkmcnt(3)
	v_add_f32_e32 v66, v90, v66
	v_add_f32_e32 v67, v91, v67
	s_waitcnt lgkmcnt(2)
	v_add_f32_e32 v90, v93, v69
	v_max3_f32 v69, v147, v172, v174
	v_max3_f32 v69, v69, v176, v180
	v_max3_f32 v69, v69, v182, v183
	v_max3_f32 v69, v69, v184, v185
	v_add_f32_e32 v68, v92, v68
	v_max3_f32 v69, v69, v66, v67
	s_waitcnt lgkmcnt(1)
	v_add_f32_e32 v91, v94, v70
	v_add_f32_e32 v92, v95, v71
	v_max3_f32 v69, v69, v68, v90
	s_waitcnt lgkmcnt(0)
	v_add_f32_e32 v93, v96, v72
	v_add_f32_e32 v94, v97, v73
	v_max3_f32 v69, v69, v91, v92
	v_max3_f32 v69, v69, v93, v94
	ds_bpermute_b32 v70, v208, v69
	s_waitcnt lgkmcnt(0)
; template <int DELTA> ...
;     ...
;         mx = fmaxf(mx, __shfl_xor(mx, 32));
;         const float m_new = fmaxf(m_run[qh], mx); const float alpha = __builtin_amdgcn_exp2f(m_run[qh] - m_new); m_run[qh] = m_new;
;         float ls = 0.f;
; #pragma unroll
;         for (int kvh = 0; kvh < 2; ++kvh) { const int toff = 64 * DELTA + 32 * (kvh - qh);
;             if (toff > 64 || toff < -64) continue;
; #pragma unroll
;             for (int rr = 0; rr < 16; ++rr) { const float e = __builtin_amdgcn_exp2f(s[kvh][rr] - m_new); s[kvh][rr] = e; ls += e; }
;             pb[qh][2 * kvh] = packp(s[kvh], 0); pb[qh][2 * kvh + 1] = packp(s[kvh], 8); }
;         l_run[qh] = l_run[qh] * alpha + ls;
; #pragma unroll
;         for (int i = 0; i < 16; ++i) { o[qh][0][i] *= alpha; o[qh][1][i] *= alpha; }
	v_max3_f32 v147, v170, v69, v70
	v_sub_f32_e32 v69, v149, v147
	v_exp_f32_e32 v225, v69
	v_sub_f32_e32 v69, v151, v147
	v_exp_f32_e32 v235, v69
	v_sub_f32_e32 v69, v153, v147
	v_exp_f32_e32 v237, v69
	v_sub_f32_e32 v69, v157, v147
	v_exp_f32_e32 v234, v69
	v_sub_f32_e32 v69, v159, v147
	v_exp_f32_e32 v236, v69
	v_sub_f32_e32 v69, v161, v147
	v_exp_f32_e32 v238, v69
	v_sub_f32_e32 v69, v163, v147
	v_exp_f32_e32 v167, v69
	v_sub_f32_e32 v69, v165, v147
	v_exp_f32_e32 v169, v69
	v_sub_f32_e32 v69, v74, v147
	v_exp_f32_e32 v153, v69
	v_sub_f32_e32 v69, v75, v147
	v_exp_f32_e32 v159, v69
	v_sub_f32_e32 v69, v76, v147
	v_exp_f32_e32 v161, v69
	v_sub_f32_e32 v69, v77, v147
	v_exp_f32_e32 v163, v69
	v_sub_f32_e32 v69, v78, v147
	v_exp_f32_e32 v165, v69
	v_sub_f32_e32 v69, v79, v147
	v_exp_f32_e32 v149, v69
	v_sub_f32_e32 v69, v80, v147
	v_exp_f32_e32 v151, v69
	v_sub_f32_e32 v69, v81, v147
	v_exp_f32_e32 v157, v69
	v_sub_f32_e32 v69, v172, v147
	v_sub_f32_e32 v187, v170, v147
	v_exp_f32_e32 v170, v69
	v_sub_f32_e32 v69, v174, v147
	v_exp_f32_e32 v174, v69
	v_sub_f32_e32 v69, v176, v147
	v_exp_f32_e32 v178, v69
	v_sub_f32_e32 v69, v180, v147
	v_exp_f32_e32 v172, v69
	v_sub_f32_e32 v69, v182, v147
	v_exp_f32_e32 v176, v69
	v_sub_f32_e32 v69, v183, v147
	v_exp_f32_e32 v180, v69
	v_sub_f32_e32 v69, v184, v147
	v_sub_f32_e32 v66, v66, v147
	v_exp_f32_e32 v182, v69
	v_sub_f32_e32 v69, v185, v147
	v_exp_f32_e32 v186, v66
	v_sub_f32_e32 v66, v67, v147
	v_exp_f32_e32 v184, v69
	v_exp_f32_e32 v188, v66
	v_sub_f32_e32 v95, v68, v147
	v_mfma_f32_32x32x16_bf16 v[66:81], v[142:145], v[110:113], 0
	v_sub_f32_e32 v90, v90, v147
	v_exp_f32_e32 v144, v90
	v_sub_f32_e32 v90, v91, v147
	v_exp_f32_e32 v190, v90
	v_sub_f32_e32 v90, v92, v147
	v_exp_f32_e32 v192, v90
	v_sub_f32_e32 v90, v93, v147
	v_mfma_f32_32x32x16_bf16 v[66:81], v[138:141], v[106:109], v[66:81]
	v_exp_f32_e32 v138, v90
	v_sub_f32_e32 v90, v94, v147
	v_cvt_pk_bf16_f32 v86, v225, v235
	v_cvt_pk_bf16_f32 v87, v237, v234
	v_cvt_pk_bf16_f32 v88, v236, v238
	v_cvt_pk_bf16_f32 v89, v167, v169
	v_cvt_pk_bf16_f32 v82, v153, v159
	v_mfma_f32_32x32x16_bf16 v[66:81], v[134:137], v[98:101], v[66:81]
	v_cvt_pk_bf16_f32 v83, v161, v163
	v_cvt_pk_bf16_f32 v84, v165, v149
	v_cvt_pk_bf16_f32 v85, v151, v157
	v_exp_f32_e32 v142, v95
	v_exp_f32_e32 v140, v90
	v_cvt_pk_bf16_f32 v94, v170, v174
	v_cvt_pk_bf16_f32 v95, v178, v172
	v_mfma_f32_32x32x16_bf16 v[66:81], v[130:133], v[102:105], v[66:81]
	v_cvt_pk_bf16_f32 v96, v176, v180
	v_cvt_pk_bf16_f32 v97, v182, v184
	v_cvt_pk_bf16_f32 v90, v186, v188
	v_cvt_pk_bf16_f32 v91, v142, v144
	v_cvt_pk_bf16_f32 v92, v190, v192
	v_cvt_pk_bf16_f32 v93, v138, v140
	ds_read2_b32 v[136:137], v171 offset1:1
	ds_read2_b32 v[130:131], v173 offset1:1
	ds_read2_b32 v[132:133], v175 offset1:1
	ds_read2_b32 v[194:195], v177 offset1:1
	v_exp_f32_e32 v134, v187
	s_waitcnt lgkmcnt(3)
	s_nop 5
	v_add_f32_e32 v66, v66, v136
	v_cndmask_b32_e32 v135, v66, v230, vcc
	v_add_f32_e32 v66, v67, v137
	v_cndmask_b32_e64 v136, v66, v230, s[40:41]
	s_waitcnt lgkmcnt(2)
	v_add_f32_e32 v66, v68, v130
	v_cndmask_b32_e64 v130, v66, v230, s[42:43]
	v_add_f32_e32 v66, v69, v131
	v_cndmask_b32_e64 v131, v66, v230, s[44:45]
	s_waitcnt lgkmcnt(1)
	v_add_f32_e32 v66, v70, v132
	v_cndmask_b32_e64 v132, v66, v230, s[46:47]
	v_add_f32_e32 v66, v71, v133
	v_cndmask_b32_e64 v133, v66, v230, s[48:49]
	s_waitcnt lgkmcnt(0)
	v_add_f32_e32 v66, v72, v194
	v_cndmask_b32_e64 v137, v66, v230, s[52:53]
	ds_read2_b32 v[66:67], v179 offset1:1
	v_add_f32_e32 v68, v73, v195
	v_cndmask_b32_e64 v139, v68, v230, s[50:51]
	ds_read2_b32 v[68:69], v181 offset1:1
	ds_read2_b32 v[70:71], v191 offset1:1
	ds_read2_b32 v[72:73], v193 offset1:1
	v_pk_mul_f32 v[64:65], v[64:65], v[134:135] op_sel_hi:[1,0]
	s_waitcnt lgkmcnt(3)
	v_add_f32_e32 v66, v74, v66
	v_max3_f32 v74, v135, s79, v136
	v_max3_f32 v74, v74, v130, v131
	v_add_f32_e32 v67, v75, v67
	v_max3_f32 v74, v74, v132, v133
	v_cndmask_b32_e64 v66, v66, v230, s[54:55]
	v_cndmask_b32_e64 v67, v67, v230, s[56:57]
	s_waitcnt lgkmcnt(2)
	v_add_f32_e32 v68, v76, v68
	v_add_f32_e32 v69, v77, v69
	v_max3_f32 v74, v74, v137, v139
	v_cndmask_b32_e64 v68, v68, v230, s[58:59]
	v_cndmask_b32_e64 v69, v69, v230, s[60:61]
	s_waitcnt lgkmcnt(1)
	v_add_f32_e32 v70, v78, v70
	v_add_f32_e32 v71, v79, v71
	v_max3_f32 v74, v74, v66, v67
	v_cndmask_b32_e64 v70, v70, v230, s[62:63]
	v_cndmask_b32_e64 v71, v71, v230, s[64:65]
	s_waitcnt lgkmcnt(0)
	v_add_f32_e32 v72, v80, v72
	v_add_f32_e32 v73, v81, v73
	v_max3_f32 v74, v74, v68, v69
	v_cndmask_b32_e64 v72, v72, v230, s[66:67]
	v_cndmask_b32_e64 v73, v73, v230, s[68:69]
	v_max3_f32 v74, v74, v70, v71
	v_max3_f32 v74, v74, v72, v73
	ds_bpermute_b32 v75, v208, v74
	v_pk_mul_f32 v[62:63], v[62:63], v[134:135] op_sel_hi:[1,0]
	v_pk_mul_f32 v[60:61], v[60:61], v[134:135] op_sel_hi:[1,0]
	v_pk_mul_f32 v[58:59], v[58:59], v[134:135] op_sel_hi:[1,0]
	v_pk_mul_f32 v[56:57], v[56:57], v[134:135] op_sel_hi:[1,0]
	s_waitcnt lgkmcnt(0)
	v_max3_f32 v194, v223, v74, v75
	v_sub_f32_e32 v74, v135, v194
	v_sub_f32_e32 v66, v66, v194
	v_exp_f32_e32 v171, v74
	v_sub_f32_e32 v74, v136, v194
	v_exp_f32_e32 v187, v66
	v_sub_f32_e32 v66, v67, v194
	v_exp_f32_e32 v175, v74
	v_sub_f32_e32 v74, v130, v194
	v_exp_f32_e32 v189, v66
	v_sub_f32_e32 v66, v68, v194
	v_exp_f32_e32 v179, v74
	v_sub_f32_e32 v74, v131, v194
	v_exp_f32_e32 v143, v66
	v_sub_f32_e32 v66, v69, v194
	v_exp_f32_e32 v173, v74
	v_sub_f32_e32 v74, v132, v194
	v_exp_f32_e32 v145, v66
	v_sub_f32_e32 v66, v70, v194
	v_exp_f32_e32 v177, v74
	v_sub_f32_e32 v74, v133, v194
	v_exp_f32_e32 v191, v66
	v_sub_f32_e32 v66, v71, v194
	v_exp_f32_e32 v181, v74
	v_sub_f32_e32 v74, v137, v194
	v_exp_f32_e32 v193, v66
	v_sub_f32_e32 v66, v72, v194
	v_exp_f32_e32 v183, v74
	v_sub_f32_e32 v74, v139, v194
	v_exp_f32_e32 v139, v66
	v_sub_f32_e32 v66, v73, v194
	v_exp_f32_e32 v185, v74
	v_exp_f32_e32 v141, v66
	v_cvt_pk_bf16_f32 v70, v171, v175
	v_cvt_pk_bf16_f32 v71, v179, v173
	v_cvt_pk_bf16_f32 v72, v177, v181
	v_cvt_pk_bf16_f32 v73, v183, v185
	v_cvt_pk_bf16_f32 v66, v187, v189
	v_cvt_pk_bf16_f32 v67, v143, v145
	v_cvt_pk_bf16_f32 v68, v191, v193
	v_cvt_pk_bf16_f32 v69, v139, v141
	s_waitcnt lgkmcnt(0)
; #define LAS __attribute__((address_space(3)))
; #define LDS_WAIT() asm volatile("s_waitcnt lgkmcnt(0)" ::: "memory")
; __device__ __forceinline__ s16x4 vtr(const LAS unsigned char* p) { return __builtin_bit_cast(s16x4, __builtin_amdgcn_ds_read_tr16_b64_v4i16((LAS v4i16_t*)p)); }
; __device__ __forceinline__ bf16x8 cat8(s16x4 a, s16x4 b) { return (bf16x8){a[0], a[1], a[2], a[3], b[0], b[1], b[2], b[3]}; }
; #define MFMA32(a, b, c) __builtin_amdgcn_mfma_f32_32x32x16_bf16((a), (b), (c), 0, 0, 0)
; template <int DELTA> ...
;     ...
;         mx = fmaxf(mx, __shfl_xor(mx, 32));
;         const float m_new = fmaxf(m_run[qh], mx); const float alpha = __builtin_amdgcn_exp2f(m_run[qh] - m_new); m_run[qh] = m_new;
;         float ls = 0.f;
; #pragma unroll
;         for (int kvh = 0; kvh < 2; ++kvh) { const int toff = 64 * DELTA + 32 * (kvh - qh);
;             if (toff > 64 || toff < -64) continue;
; #pragma unroll
;             for (int rr = 0; rr < 16; ++rr) { const float e = __builtin_amdgcn_exp2f(s[kvh][rr] - m_new); s[kvh][rr] = e; ls += e; }
;             pb[qh][2 * kvh] = packp(s[kvh], 0); pb[qh][2 * kvh + 1] = packp(s[kvh], 8); }
;         l_run[qh] = l_run[qh] * alpha + ls;
; #pragma unroll
;         for (int i = 0; i < 16; ++i) { o[qh][0][i] *= alpha; o[qh][1][i] *= alpha; }
;     }
;     LDS_WAIT();
; #pragma unroll
;     for (int j = 0; j < 4; ++j) { const LAS unsigned char* vj = wl + voff + 16 * j * VP;
;         const bf16x8 a0 = cat8(vtr(vj), vtr(vj + 8 * VP)); const bf16x8 a1 = cat8(vtr(vj + 64), vtr(vj + 8 * VP + 64));
; #pragma unroll
;         for (int qh = 0; qh < 2; ++qh) { const int toff = 64 * DELTA + 32 * ((j >> 1) - qh);
;             if (toff > 64 || toff < -64) continue;
;             o[qh][0] = MFMA32(a0, pb[qh][j], o[qh][0]); o[qh][1] = MFMA32(a1, pb[qh][j], o[qh][1]); } }
	ds_read_b64_tr_b16 v[74:75], v222
	ds_read_b64_tr_b16 v[76:77], v222 offset:1536
	ds_read_b64_tr_b16 v[80:81], v222 offset:1600
	ds_read_b64_tr_b16 v[78:79], v222 offset:64
	v_pk_mul_f32 v[54:55], v[54:55], v[134:135] op_sel_hi:[1,0]
	v_pk_mul_f32 v[52:53], v[52:53], v[134:135] op_sel_hi:[1,0]
	v_pk_mul_f32 v[50:51], v[50:51], v[134:135] op_sel_hi:[1,0]
	v_pk_mul_f32 v[32:33], v[32:33], v[134:135] op_sel_hi:[1,0]
	v_pk_mul_f32 v[30:31], v[30:31], v[134:135] op_sel_hi:[1,0]
	s_waitcnt lgkmcnt(2)
	v_mfma_f32_32x32x16_bf16 v[50:65], v[74:77], v[86:89], v[50:65]
	v_mul_f32_e64 v28, v28, v134
	v_mul_f32_e64 v29, v29, v134
	v_mul_f32_e64 v26, v26, v134
	v_mul_f32_e64 v27, v27, v134
	v_mul_f32_e64 v24, v24, v134
	v_mul_f32_e64 v25, v25, v134
	v_pk_mul_f32 v[22:23], v[22:23], v[134:135] op_sel_hi:[1,0]
	v_pk_mul_f32 v[20:21], v[20:21], v[134:135] op_sel_hi:[1,0]
	v_pk_mul_f32 v[18:19], v[18:19], v[134:135] op_sel_hi:[1,0]
	s_waitcnt lgkmcnt(0)
	s_nop 0
	v_mfma_f32_32x32x16_bf16 v[18:33], v[78:81], v[86:89], v[18:33]
	ds_read_b64_tr_b16 v[74:75], v222 offset:3072
	ds_read_b64_tr_b16 v[76:77], v222 offset:4608
	ds_read_b64_tr_b16 v[80:81], v222 offset:4672
	ds_read_b64_tr_b16 v[78:79], v222 offset:3136
	s_waitcnt lgkmcnt(2)
	v_mfma_f32_32x32x16_bf16 v[50:65], v[74:77], v[82:85], v[50:65]
	v_add_f32_e32 v74, 0, v225
	v_add_f32_e32 v74, v235, v74
	v_add_f32_e32 v86, v237, v74
	ds_read_b64_tr_b16 v[74:75], v222 offset:6144
	ds_read_b64_tr_b16 v[76:77], v222 offset:7680
	s_waitcnt lgkmcnt(2)
	v_mfma_f32_32x32x16_bf16 v[18:33], v[78:81], v[82:85], v[18:33]
	v_add_f32_e32 v78, v234, v86
	v_add_f32_e32 v78, v236, v78
	v_add_f32_e32 v82, v238, v78
	v_sub_f32_e32 v78, v223, v194
	v_exp_f32_e32 v135, v78
	ds_read_b64_tr_b16 v[80:81], v222 offset:7744
	ds_read_b64_tr_b16 v[78:79], v222 offset:6208
	v_add_f32_e32 v82, v167, v82
	v_add_f32_e32 v83, v169, v82
	v_mov_b32_e32 v82, v135
	v_pk_mul_f32 v[48:49], v[48:49], v[82:83] op_sel_hi:[1,0]
	v_pk_mul_f32 v[46:47], v[46:47], v[82:83] op_sel_hi:[1,0]
	v_pk_mul_f32 v[44:45], v[44:45], v[82:83] op_sel_hi:[1,0]
	v_pk_mul_f32 v[42:43], v[42:43], v[82:83] op_sel_hi:[1,0]
	v_pk_mul_f32 v[40:41], v[40:41], v[82:83] op_sel_hi:[1,0]
	v_pk_mul_f32 v[38:39], v[38:39], v[82:83] op_sel_hi:[1,0]
	v_pk_mul_f32 v[36:37], v[36:37], v[82:83] op_sel_hi:[1,0]
	v_pk_mul_f32 v[34:35], v[34:35], v[82:83] op_sel_hi:[1,0]
	v_pk_mul_f32 v[16:17], v[16:17], v[82:83] op_sel_hi:[1,0]
	v_pk_mul_f32 v[14:15], v[14:15], v[82:83] op_sel_hi:[1,0]
	v_pk_mul_f32 v[12:13], v[12:13], v[82:83] op_sel_hi:[1,0]
	v_pk_mul_f32 v[10:11], v[10:11], v[82:83] op_sel_hi:[1,0]
	v_pk_mul_f32 v[8:9], v[8:9], v[82:83] op_sel_hi:[1,0]
	v_pk_mul_f32 v[6:7], v[6:7], v[82:83] op_sel_hi:[1,0]
	v_pk_mul_f32 v[4:5], v[4:5], v[82:83] op_sel_hi:[1,0]
	v_pk_mul_f32 v[2:3], v[2:3], v[82:83] op_sel_hi:[1,0]
	s_waitcnt lgkmcnt(2)
	v_mfma_f32_32x32x16_bf16 v[34:49], v[74:77], v[70:73], v[34:49]
	v_mov_b32_e32 v223, v194
	s_waitcnt lgkmcnt(0)
	v_mfma_f32_32x32x16_bf16 v[2:17], v[78:81], v[70:73], v[2:17]
	v_add_f32_e32 v70, v153, v83
	v_add_f32_e32 v70, v159, v70
	v_add_f32_e32 v70, v161, v70
	v_add_f32_e32 v70, v163, v70
	v_mfma_f32_32x32x16_bf16 v[18:33], v[78:81], v[94:97], v[18:33]
	v_add_f32_e32 v78, v165, v70
	v_add_f32_e32 v78, v149, v78
	v_add_f32_e32 v78, v151, v78
	v_add_f32_e32 v78, v157, v78
	v_mov_b32_e32 v79, v1
	v_pk_add_f32 v[78:79], v[170:171], v[78:79]
	v_mov_b32_e32 v170, v147
	v_mfma_f32_32x32x16_bf16 v[50:65], v[74:77], v[94:97], v[50:65]
	v_add_f32_e64 v78, v174, v78
	v_add_f32_e64 v79, v175, v79
	ds_read_b64_tr_b16 v[74:75], v222 offset:9216
	ds_read_b64_tr_b16 v[76:77], v222 offset:10752
	v_add_f32_e64 v78, v178, v78
	v_add_f32_e64 v79, v179, v79
	ds_read_b64_tr_b16 v[72:73], v222 offset:10816
	ds_read_b64_tr_b16 v[70:71], v222 offset:9280
	v_pk_add_f32 v[78:79], v[172:173], v[78:79]
	s_waitcnt lgkmcnt(0)
	s_nop 0
	v_pk_add_f32 v[78:79], v[176:177], v[78:79]
	s_waitcnt lgkmcnt(2)
	v_mfma_f32_32x32x16_bf16 v[50:65], v[74:77], v[90:93], v[50:65]
	v_add_f32_e64 v78, v180, v78
	v_add_f32_e64 v79, v181, v79
	v_add_f32_e64 v78, v182, v78
	v_add_f32_e64 v79, v183, v79
	v_add_f32_e64 v78, v184, v78
	v_add_f32_e64 v79, v185, v79
	v_pk_add_f32 v[78:79], v[186:187], v[78:79]
	s_waitcnt lgkmcnt(0)
	v_mfma_f32_32x32x16_bf16 v[18:33], v[70:73], v[90:93], v[18:33]
	v_add_f32_e64 v78, v188, v78
	v_add_f32_e64 v79, v189, v79
	v_mfma_f32_32x32x16_bf16 v[34:49], v[74:77], v[66:69], v[34:49]
	v_add_f32_e64 v74, v142, v78
	v_add_f32_e64 v75, v143, v79
	v_add_f32_e64 v74, v144, v74
	v_add_f32_e64 v75, v145, v75
	v_add_f32_e64 v74, v190, v74
	v_add_f32_e64 v75, v191, v75
	v_pk_add_f32 v[74:75], v[192:193], v[74:75]
	v_mfma_f32_32x32x16_bf16 v[2:17], v[70:73], v[66:69], v[2:17]
	v_add_f32_e64 v74, v138, v74
	v_add_f32_e64 v75, v139, v75
	v_add_f32_e64 v74, v140, v74
	v_add_f32_e64 v75, v141, v75
	v_fma_f32 v154, v154, v134, v74
	v_fma_f32 v155, v155, v135, v75
; #define LAS __attribute__((address_space(3)))
; #define MFMA32(a, b, c) __builtin_amdgcn_mfma_f32_32x32x16_bf16((a), (b), (c), 0, 0, 0)
; #define SBAR0() __builtin_amdgcn_sched_barrier(0)
; template <int DELTA> ...
;     u32x4 vv[8]; bf16x8 kf[2][4];
; #pragma unroll
;     for (int i = 0; i < 8; ++i) { const int idx = lane + 64 * i, row = idx >> 3, ch = idx & 7; vv[i] = *(const u32x4*)(vbase + (size_t)row * rstride + ch * 8); }
; #pragma unroll
;     for (int kvh = 0; kvh < 2; ++kvh)
; #pragma unroll
;         for (int d0 = 0; d0 < 4; ++d0) kf[kvh][d0] = *(const bf16x8*)(kbase + (size_t)(32 * kvh + r32) * rstride + d0 * 16);
;     SBAR0();
; #pragma unroll
;     for (int i = 0; i < 8; ++i) { const int idx = lane + 64 * i, row = idx >> 3, ch = idx & 7; *(LAS u32x4*)(wl + row * VP + ch * 16) = vv[i]; }
;     bf16x8 pb[2][4];
; #pragma unroll
;     for (int qh = 0; qh < 2; ++qh) {
;         f32x16 s[2]; float mx = -1e30f;
; #pragma unroll
;         for (int kvh = 0; kvh < 2; ++kvh) {
;             constexpr int dummy = 0; (void)dummy;
;             const int toff = 64 * DELTA + 32 * (kvh - qh);
;             if (toff > 64 || toff < -64) continue;
; #pragma unroll
;             for (int i = 0; i < 16; ++i) s[kvh][i] = 0.f;
; #pragma unroll
;             for (int d0 = 0; d0 < 4; ++d0) s[kvh] = MFMA32(kf[kvh][d0], qf[qh][d0], s[kvh]);
; #pragma unroll
;             for (int rr = 0; rr < 16; ++rr) { const int c4 = 4 * ((rr & 3) + 8 * (rr >> 2)); const float bias = *(const LAS float*)(wl + bvar + (VT_B + c4 + toff * 4));
;                 float v = s[kvh][rr] + bias;
;                 if (toff == 64) v = (bvar <= btb - c4) ? v : -1e30f;
;                 if (toff == -64) v = (bvar >= btb - c4) ? v : -1e30f;
;                 s[kvh][rr] = v; mx = fmaxf(mx, v); }
;         }
.LBB0_440:
	s_cmp_gt_i32 s37, 62
	s_cbranch_scc1 .LBB0_442
	v_mov_b32_e32 v157, v1
	v_lshl_add_u64 v[66:67], s[6:7], 0, v[156:157]
	s_mov_b64 s[38:39], 0x4002000
	v_mov_b32_e32 v147, v1
	v_lshl_add_u64 v[90:91], v[66:67], 0, s[38:39]
	v_lshl_add_u64 v[66:67], s[6:7], 0, v[146:147]
	s_mov_b64 s[6:7], 0x8002000
	v_lshl_add_u64 v[92:93], v[66:67], 0, s[6:7]
	v_mov_b32_e32 v169, v1
	v_mov_b32_e32 v167, v1
	v_mov_b32_e32 v165, v1
	v_mov_b32_e32 v163, v1
	v_mov_b32_e32 v161, v1
	v_mov_b32_e32 v159, v1
	v_mov_b32_e32 v153, v1
	v_mov_b32_e32 v151, v1
	v_lshl_add_u64 v[66:67], v[92:93], 0, v[168:169]
	v_lshl_add_u64 v[70:71], v[92:93], 0, v[166:167]
	v_lshl_add_u64 v[74:75], v[92:93], 0, v[164:165]
	v_lshl_add_u64 v[78:79], v[92:93], 0, v[162:163]
	v_lshl_add_u64 v[82:83], v[92:93], 0, v[160:161]
	v_lshl_add_u64 v[86:87], v[92:93], 0, v[158:159]
	v_lshl_add_u64 v[94:95], v[92:93], 0, v[152:153]
	v_lshl_add_u64 v[92:93], v[92:93], 0, v[150:151]
	v_mov_b32_e32 v149, v1
	global_load_dwordx4 v[66:69], v[66:67], off
	s_nop 0
	global_load_dwordx4 v[70:73], v[70:71], off
	s_nop 0
	global_load_dwordx4 v[74:77], v[74:75], off
	s_nop 0
	global_load_dwordx4 v[78:81], v[78:79], off
	s_nop 0
	global_load_dwordx4 v[82:85], v[82:83], off
	s_nop 0
	global_load_dwordx4 v[86:89], v[86:87], off
	s_nop 0
	global_load_dwordx4 v[158:161], v[94:95], off
	global_load_dwordx4 v[162:165], v[92:93], off
	v_lshl_add_u64 v[92:93], v[90:91], 0, v[148:149]
	v_lshl_add_u64 v[94:95], v[90:91], 0, v[0:1]
	global_load_dwordx4 v[150:153], v[92:93], off
	global_load_dwordx4 v[146:149], v[92:93], off offset:32
	global_load_dwordx4 v[138:141], v[92:93], off offset:64
	global_load_dwordx4 v[142:145], v[92:93], off offset:96
	global_load_dwordx4 v[134:137], v[94:95], off
	global_load_dwordx4 v[130:133], v[94:95], off offset:32
	s_nop 0
	global_load_dwordx4 v[90:93], v[94:95], off offset:64
	s_nop 0
	global_load_dwordx4 v[94:97], v[94:95], off offset:96
	s_waitcnt vmcnt(15)
	ds_write_b128 v233, v[66:69]
	s_waitcnt vmcnt(14)
	ds_write_b128 v233, v[70:73] offset:1536
	s_waitcnt vmcnt(13)
	ds_write_b128 v233, v[74:77] offset:3072
	s_waitcnt vmcnt(12)
	ds_write_b128 v233, v[78:81] offset:4608
	s_waitcnt vmcnt(11)
	ds_write_b128 v233, v[82:85] offset:6144
	s_waitcnt vmcnt(10)
	ds_write_b128 v233, v[86:89] offset:7680
	s_waitcnt vmcnt(9)
	ds_write_b128 v233, v[158:161] offset:9216
	s_waitcnt vmcnt(8)
	ds_write_b128 v233, v[162:165] offset:10752
	s_waitcnt vmcnt(7)
	v_mfma_f32_32x32x16_bf16 v[66:81], v[150:153], v[126:129], 0
	v_cmp_lt_u32_e32 vcc, s87, v211
	v_cmp_lt_u32_e64 s[42:43], s24, v211
	v_cmp_lt_u32_e64 s[44:45], s25, v211
	v_cmp_lt_u32_e64 s[46:47], s26, v211
	v_cmp_lt_u32_e64 s[48:49], s20, v211
	v_cmp_lt_u32_e64 s[50:51], s28, v211
	v_cmp_lt_u32_e64 s[52:53], s90, v211
	s_waitcnt vmcnt(6)
	v_mfma_f32_32x32x16_bf16 v[66:81], v[146:149], v[114:117], v[66:81]
	v_add_u32_e32 v115, 0x3300, v212
	ds_read2_b32 v[82:83], v115 offset1:1
	v_add_u32_e32 v117, 0x3308, v212
	v_cmp_lt_u32_e64 s[54:55], s91, v211
	v_cmp_lt_u32_e64 s[56:57], s76, v211
	v_cmp_lt_u32_e64 s[58:59], s80, v211
	v_cmp_lt_u32_e64 s[60:61], s81, v211
	s_waitcnt vmcnt(5)
	v_mfma_f32_32x32x16_bf16 v[66:81], v[138:141], v[118:121], v[66:81]
	v_add_u32_e32 v119, 0x3320, v212
	v_add_u32_e32 v121, 0x3328, v212
	v_add_u32_e32 v127, 0x3360, v212
	v_cmp_lt_u32_e64 s[40:41], s74, v211
	v_cmp_lt_u32_e64 s[62:63], s27, v211
	v_cmp_lt_u32_e64 s[64:65], s78, v211
	v_add_u32_e32 v129, 0x3368, v212
	s_waitcnt vmcnt(4)
	v_mfma_f32_32x32x16_bf16 v[66:81], v[142:145], v[122:125], v[66:81]
	v_add_u32_e32 v123, 0x3340, v212
	v_add_u32_e32 v125, 0x3348, v212
	v_cmp_lt_u32_e64 s[66:67], s77, v211
	v_cmp_lt_u32_e64 s[68:69], s36, v211
	s_waitcnt lgkmcnt(0)
	s_nop 6
	v_add_f32_e32 v0, v66, v82
	v_cndmask_b32_e32 v82, v0, v230, vcc
	v_add_f32_e32 v0, v67, v83
	ds_read2_b32 v[240:241], v117 offset1:1
	ds_read2_b32 v[242:243], v119 offset1:1
	ds_read2_b32 v[244:245], v121 offset1:1
	ds_read2_b32 v[246:247], v123 offset1:1
	ds_read2_b32 v[248:249], v125 offset1:1
	ds_read2_b32 v[250:251], v127 offset1:1
	ds_read2_b32 v[252:253], v129 offset1:1
	v_cndmask_b32_e64 v83, v0, v230, s[40:41]
	v_max3_f32 v0, v82, s79, v83
	s_waitcnt lgkmcnt(0)
	v_add_f32_e32 v66, v68, v240
	v_cndmask_b32_e64 v68, v66, v230, s[42:43]
	v_add_f32_e32 v66, v69, v241
	v_cndmask_b32_e64 v69, v66, v230, s[44:45]
	v_max3_f32 v0, v0, v68, v69
	s_waitcnt lgkmcnt(0)
	v_add_f32_e32 v66, v70, v242
	v_cndmask_b32_e64 v70, v66, v230, s[46:47]
	v_add_f32_e32 v66, v71, v243
	v_cndmask_b32_e64 v71, v66, v230, s[48:49]
	v_max3_f32 v0, v0, v70, v71
	s_waitcnt lgkmcnt(0)
	v_add_f32_e32 v66, v72, v244
	v_cndmask_b32_e64 v72, v66, v230, s[50:51]
	v_add_f32_e32 v66, v73, v245
	v_cndmask_b32_e64 v73, v66, v230, s[52:53]
	v_max3_f32 v0, v0, v72, v73
	s_waitcnt lgkmcnt(0)
	v_add_f32_e32 v66, v74, v246
	v_cndmask_b32_e64 v74, v66, v230, s[54:55]
	v_add_f32_e32 v66, v75, v247
	v_cndmask_b32_e64 v75, v66, v230, s[56:57]
	v_max3_f32 v0, v0, v74, v75
	s_waitcnt lgkmcnt(0)
	v_add_f32_e32 v66, v76, v248
	v_cndmask_b32_e64 v76, v66, v230, s[58:59]
	v_add_f32_e32 v66, v77, v249
	v_cndmask_b32_e64 v77, v66, v230, s[60:61]
	v_max3_f32 v0, v0, v76, v77
	s_waitcnt lgkmcnt(0)
	v_add_f32_e32 v66, v78, v250
	v_cndmask_b32_e64 v78, v66, v230, s[62:63]
	v_add_f32_e32 v66, v79, v251
	v_cndmask_b32_e64 v79, v66, v230, s[64:65]
	v_max3_f32 v0, v0, v78, v79
	s_waitcnt lgkmcnt(0)
	v_add_f32_e32 v66, v80, v252
	v_add_f32_e32 v67, v81, v253
	v_cndmask_b32_e64 v66, v66, v230, s[66:67]
	v_cndmask_b32_e64 v67, v67, v230, s[68:69]
	v_max3_f32 v0, v0, v66, v67
	ds_bpermute_b32 v80, v208, v0
	s_waitcnt lgkmcnt(0)
; #define LAS __attribute__((address_space(3)))
; #define MFMA32(a, b, c) __builtin_amdgcn_mfma_f32_32x32x16_bf16((a), (b), (c), 0, 0, 0)
; template <int DELTA> ...
;     ...
;     for (int qh = 0; qh < 2; ++qh) {
;         f32x16 s[2]; float mx = -1e30f;
; #pragma unroll
;         for (int kvh = 0; kvh < 2; ++kvh) {
;             constexpr int dummy = 0; (void)dummy;
;             const int toff = 64 * DELTA + 32 * (kvh - qh);
;             if (toff > 64 || toff < -64) continue;
; #pragma unroll
;             for (int i = 0; i < 16; ++i) s[kvh][i] = 0.f;
; #pragma unroll
;             for (int d0 = 0; d0 < 4; ++d0) s[kvh] = MFMA32(kf[kvh][d0], qf[qh][d0], s[kvh]);
; #pragma unroll
;             for (int rr = 0; rr < 16; ++rr) { const int c4 = 4 * ((rr & 3) + 8 * (rr >> 2)); const float bias = *(const LAS float*)(wl + bvar + (VT_B + c4 + toff * 4));
;                 float v = s[kvh][rr] + bias;
;                 if (toff == 64) v = (bvar <= btb - c4) ? v : -1e30f;
;                 if (toff == -64) v = (bvar >= btb - c4) ? v : -1e30f;
;                 s[kvh][rr] = v; mx = fmaxf(mx, v); }
;         }
;         mx = fmaxf(mx, __shfl_xor(mx, 32));
;         const float m_new = fmaxf(m_run[qh], mx); const float alpha = __builtin_amdgcn_exp2f(m_run[qh] - m_new); m_run[qh] = m_new;
;         float ls = 0.f;
; #pragma unroll
;         for (int kvh = 0; kvh < 2; ++kvh) { const int toff = 64 * DELTA + 32 * (kvh - qh);
;             if (toff > 64 || toff < -64) continue;
; #pragma unroll
;             for (int rr = 0; rr < 16; ++rr) { const float e = __builtin_amdgcn_exp2f(s[kvh][rr] - m_new); s[kvh][rr] = e; ls += e; }
;             pb[qh][2 * kvh] = packp(s[kvh], 0); pb[qh][2 * kvh + 1] = packp(s[kvh], 8); }
;         l_run[qh] = l_run[qh] * alpha + ls;
; #pragma unroll
;         for (int i = 0; i < 16; ++i) { o[qh][0][i] *= alpha; o[qh][1][i] *= alpha; }
	v_max3_f32 v0, v170, v0, v80
	v_sub_f32_e32 v68, v68, v0
	v_exp_f32_e32 v118, v68
	v_sub_f32_e32 v68, v69, v0
	v_exp_f32_e32 v120, v68
	v_sub_f32_e32 v68, v70, v0
	v_exp_f32_e32 v122, v68
	v_sub_f32_e32 v68, v71, v0
	v_exp_f32_e32 v126, v68
	v_sub_f32_e32 v68, v72, v0
	v_exp_f32_e32 v124, v68
	v_sub_f32_e32 v68, v73, v0
	v_exp_f32_e32 v128, v68
	v_sub_f32_e32 v68, v74, v0
	v_exp_f32_e32 v158, v68
	v_sub_f32_e32 v68, v75, v0
	v_exp_f32_e32 v160, v68
	v_sub_f32_e32 v68, v76, v0
	v_exp_f32_e32 v162, v68
	v_sub_f32_e32 v68, v77, v0
	v_sub_f32_e32 v81, v82, v0
	v_exp_f32_e32 v164, v68
	v_sub_f32_e32 v68, v78, v0
	v_sub_f32_e32 v66, v66, v0
	v_sub_f32_e32 v80, v170, v0
	v_exp_f32_e32 v114, v81
	v_sub_f32_e32 v81, v83, v0
	v_exp_f32_e32 v166, v68
	v_sub_f32_e32 v68, v79, v0
	v_exp_f32_e32 v170, v66
	v_sub_f32_e32 v66, v67, v0
	v_exp_f32_e32 v116, v81
	v_exp_f32_e32 v168, v68
	v_exp_f32_e32 v172, v66
	v_exp_f32_e32 v174, v80
	v_mfma_f32_32x32x16_bf16 v[66:81], v[150:153], v[110:113], 0
	v_cvt_pk_bf16_f32 v86, v114, v116
	v_cvt_pk_bf16_f32 v87, v118, v120
	v_cvt_pk_bf16_f32 v88, v122, v126
	v_cvt_pk_bf16_f32 v89, v124, v128
	v_cvt_pk_bf16_f32 v82, v158, v160
	v_cvt_pk_bf16_f32 v83, v162, v164
	v_cvt_pk_bf16_f32 v84, v166, v168
	v_mfma_f32_32x32x16_bf16 v[66:81], v[146:149], v[106:109], v[66:81]
	v_cvt_pk_bf16_f32 v85, v170, v172
	v_mul_f32_e64 v64, v64, v174
	v_mul_f32_e64 v65, v65, v174
	v_mul_f32_e64 v62, v62, v174
	v_mul_f32_e64 v63, v63, v174
	v_mul_f32_e64 v60, v60, v174
	v_mul_f32_e64 v61, v61, v174
	v_pk_mul_f32 v[58:59], v[58:59], v[174:175] op_sel_hi:[1,0]
	v_pk_mul_f32 v[56:57], v[56:57], v[174:175] op_sel_hi:[1,0]
	v_pk_mul_f32 v[54:55], v[54:55], v[174:175] op_sel_hi:[1,0]
	v_mfma_f32_32x32x16_bf16 v[66:81], v[138:141], v[98:101], v[66:81]
	ds_read2_b32 v[138:139], v214 offset1:1
	v_mul_f32_e64 v52, v52, v174
	v_mul_f32_e64 v53, v53, v174
	v_mul_f32_e64 v50, v50, v174
	v_mul_f32_e64 v51, v51, v174
	v_pk_mul_f32 v[32:33], v[32:33], v[174:175] op_sel_hi:[1,0]
	v_pk_mul_f32 v[30:31], v[30:31], v[174:175] op_sel_hi:[1,0]
	v_pk_mul_f32 v[28:29], v[28:29], v[174:175] op_sel_hi:[1,0]
	v_pk_mul_f32 v[26:27], v[26:27], v[174:175] op_sel_hi:[1,0]
	v_mfma_f32_32x32x16_bf16 v[66:81], v[142:145], v[102:105], v[66:81]
	v_mul_f32_e64 v24, v24, v174
	v_mul_f32_e64 v25, v25, v174
	v_mul_f32_e64 v22, v22, v174
	v_mul_f32_e64 v23, v23, v174
	v_mul_f32_e64 v20, v20, v174
	v_mul_f32_e64 v21, v21, v174
	v_pk_mul_f32 v[18:19], v[18:19], v[174:175] op_sel_hi:[1,0]
	s_waitcnt lgkmcnt(0)
	s_nop 3
	v_add_f32_e32 v146, v66, v138
	v_add_f32_e32 v143, v67, v139
	ds_read2_b32 v[240:241], v213 offset1:1
	ds_read2_b32 v[242:243], v215 offset1:1
	ds_read2_b32 v[244:245], v216 offset1:1
	ds_read2_b32 v[246:247], v217 offset1:1
	ds_read2_b32 v[248:249], v218 offset1:1
	ds_read2_b32 v[250:251], v219 offset1:1
	ds_read2_b32 v[252:253], v220 offset1:1
	v_max3_f32 v138, v146, s79, v143
	s_waitcnt lgkmcnt(0)
	v_add_f32_e32 v150, v68, v240
	v_add_f32_e32 v147, v69, v241
	v_max3_f32 v68, v138, v150, v147
	s_waitcnt lgkmcnt(0)
	v_add_f32_e32 v152, v70, v242
	v_add_f32_e32 v148, v71, v243
	v_max3_f32 v68, v68, v152, v148
	s_waitcnt lgkmcnt(0)
	v_add_f32_e32 v153, v72, v244
	v_add_f32_e32 v151, v73, v245
	v_max3_f32 v68, v68, v153, v151
	s_waitcnt lgkmcnt(0)
	v_add_f32_e32 v149, v74, v246
	v_add_f32_e32 v145, v75, v247
	v_max3_f32 v68, v68, v149, v145
	s_waitcnt lgkmcnt(0)
	v_add_f32_e32 v144, v76, v248
	v_add_f32_e32 v142, v77, v249
	v_max3_f32 v68, v68, v144, v142
	s_waitcnt lgkmcnt(0)
	v_add_f32_e32 v141, v78, v250
	v_add_f32_e32 v140, v79, v251
	v_max3_f32 v68, v68, v141, v140
	s_waitcnt lgkmcnt(0)
	v_add_f32_e32 v139, v80, v252
	v_add_f32_e32 v138, v81, v253
	v_max3_f32 v157, v68, v139, v138
	s_waitcnt vmcnt(3)
	v_mfma_f32_32x32x16_bf16 v[66:81], v[134:137], v[110:113], 0
	s_waitcnt vmcnt(2)
	v_mfma_f32_32x32x16_bf16 v[66:81], v[130:133], v[106:109], v[66:81]
	s_waitcnt vmcnt(1)
	v_mfma_f32_32x32x16_bf16 v[66:81], v[90:93], v[98:101], v[66:81]
	ds_read2_b32 v[90:91], v115 offset1:1
	s_waitcnt vmcnt(0)
	v_mfma_f32_32x32x16_bf16 v[66:81], v[94:97], v[102:105], v[66:81]
	s_waitcnt lgkmcnt(0)
	s_nop 10
	v_add_f32_e32 v66, v66, v90
	v_cndmask_b32_e32 v92, v66, v230, vcc
	v_add_f32_e32 v66, v67, v91
	v_cndmask_b32_e64 v91, v66, v230, s[40:41]
	ds_read2_b32 v[240:241], v117 offset1:1
	ds_read2_b32 v[242:243], v119 offset1:1
	ds_read2_b32 v[244:245], v121 offset1:1
	ds_read2_b32 v[246:247], v123 offset1:1
	ds_read2_b32 v[248:249], v125 offset1:1
	ds_read2_b32 v[250:251], v127 offset1:1
	ds_read2_b32 v[252:253], v129 offset1:1
	s_waitcnt lgkmcnt(0)
	v_add_f32_e32 v66, v68, v240
	v_cndmask_b32_e64 v68, v66, v230, s[42:43]
	v_add_f32_e32 v66, v69, v241
	v_cndmask_b32_e64 v69, v66, v230, s[44:45]
	s_waitcnt lgkmcnt(0)
	v_add_f32_e32 v66, v70, v242
	v_cndmask_b32_e64 v70, v66, v230, s[46:47]
	v_add_f32_e32 v66, v71, v243
	v_cndmask_b32_e64 v71, v66, v230, s[48:49]
	s_waitcnt lgkmcnt(0)
	v_add_f32_e32 v66, v72, v244
	v_cndmask_b32_e64 v72, v66, v230, s[50:51]
	v_add_f32_e32 v66, v73, v245
	v_cndmask_b32_e64 v73, v66, v230, s[52:53]
	s_waitcnt lgkmcnt(0)
	v_add_f32_e32 v66, v74, v246
	v_cndmask_b32_e64 v94, v66, v230, s[54:55]
	v_add_f32_e32 v66, v75, v247
	v_cndmask_b32_e64 v95, v66, v230, s[56:57]
	v_max3_f32 v74, v157, v92, v91
	v_max3_f32 v74, v74, v68, v69
	v_max3_f32 v74, v74, v70, v71
	v_max3_f32 v74, v74, v72, v73
	s_waitcnt lgkmcnt(0)
	v_add_f32_e32 v66, v76, v248
	v_cndmask_b32_e64 v96, v66, v230, s[58:59]
	v_add_f32_e32 v66, v77, v249
	v_cndmask_b32_e64 v97, v66, v230, s[60:61]
	v_max3_f32 v74, v74, v94, v95
	v_max3_f32 v74, v74, v96, v97
	s_waitcnt lgkmcnt(0)
; #define LAS __attribute__((address_space(3)))
; #define LDS_WAIT() asm volatile("s_waitcnt lgkmcnt(0)" ::: "memory")
; __device__ __forceinline__ s16x4 vtr(const LAS unsigned char* p) { return __builtin_bit_cast(s16x4, __builtin_amdgcn_ds_read_tr16_b64_v4i16((LAS v4i16_t*)p)); }
; __device__ __forceinline__ bf16x8 cat8(s16x4 a, s16x4 b) { return (bf16x8){a[0], a[1], a[2], a[3], b[0], b[1], b[2], b[3]}; }
; #define MFMA32(a, b, c) __builtin_amdgcn_mfma_f32_32x32x16_bf16((a), (b), (c), 0, 0, 0)
; template <int DELTA> ...
;     ...
;             for (int rr = 0; rr < 16; ++rr) { const int c4 = 4 * ((rr & 3) + 8 * (rr >> 2)); const float bias = *(const LAS float*)(wl + bvar + (VT_B + c4 + toff * 4));
;                 float v = s[kvh][rr] + bias;
;                 if (toff == 64) v = (bvar <= btb - c4) ? v : -1e30f;
;                 if (toff == -64) v = (bvar >= btb - c4) ? v : -1e30f;
;                 s[kvh][rr] = v; mx = fmaxf(mx, v); }
;         }
;         mx = fmaxf(mx, __shfl_xor(mx, 32));
;         const float m_new = fmaxf(m_run[qh], mx); const float alpha = __builtin_amdgcn_exp2f(m_run[qh] - m_new); m_run[qh] = m_new;
;         float ls = 0.f;
; #pragma unroll
;         for (int kvh = 0; kvh < 2; ++kvh) { const int toff = 64 * DELTA + 32 * (kvh - qh);
;             if (toff > 64 || toff < -64) continue;
; #pragma unroll
;             for (int rr = 0; rr < 16; ++rr) { const float e = __builtin_amdgcn_exp2f(s[kvh][rr] - m_new); s[kvh][rr] = e; ls += e; }
;             pb[qh][2 * kvh] = packp(s[kvh], 0); pb[qh][2 * kvh + 1] = packp(s[kvh], 8); }
;         l_run[qh] = l_run[qh] * alpha + ls;
; #pragma unroll
;         for (int i = 0; i < 16; ++i) { o[qh][0][i] *= alpha; o[qh][1][i] *= alpha; }
;     }
;     LDS_WAIT();
; #pragma unroll
;     for (int j = 0; j < 4; ++j) { const LAS unsigned char* vj = wl + voff + 16 * j * VP;
;         const bf16x8 a0 = cat8(vtr(vj), vtr(vj + 8 * VP)); const bf16x8 a1 = cat8(vtr(vj + 64), vtr(vj + 8 * VP + 64));
; #pragma unroll
;         for (int qh = 0; qh < 2; ++qh) { const int toff = 64 * DELTA + 32 * ((j >> 1) - qh);
;             if (toff > 64 || toff < -64) continue;
;             o[qh][0] = MFMA32(a0, pb[qh][j], o[qh][0]); o[qh][1] = MFMA32(a1, pb[qh][j], o[qh][1]); } }
	v_add_f32_e32 v66, v78, v250
	v_cndmask_b32_e64 v98, v66, v230, s[62:63]
	v_add_f32_e32 v66, v79, v251
	v_cndmask_b32_e64 v99, v66, v230, s[64:65]
	v_max3_f32 v74, v74, v98, v99
	s_waitcnt lgkmcnt(0)
	v_add_f32_e32 v66, v80, v252
	v_add_f32_e32 v67, v81, v253
	v_cndmask_b32_e64 v66, v66, v230, s[66:67]
	v_cndmask_b32_e64 v67, v67, v230, s[68:69]
	v_max3_f32 v74, v74, v66, v67
	ds_bpermute_b32 v75, v208, v74
	s_waitcnt lgkmcnt(0)
	v_max3_f32 v90, v223, v74, v75
	v_sub_f32_e32 v74, v146, v90
	v_exp_f32_e32 v74, v74
	v_sub_f32_e32 v76, v143, v90
	v_exp_f32_e32 v76, v76
	v_sub_f32_e32 v77, v150, v90
	v_exp_f32_e32 v77, v77
	v_sub_f32_e32 v78, v147, v90
	v_exp_f32_e32 v79, v78
	v_sub_f32_e32 v78, v152, v90
	v_add_f32_e32 v75, 0, v74
	v_exp_f32_e32 v80, v78
	v_sub_f32_e32 v78, v148, v90
	v_add_f32_e32 v75, v76, v75
	v_exp_f32_e32 v81, v78
	v_sub_f32_e32 v78, v153, v90
	v_add_f32_e32 v75, v77, v75
	v_exp_f32_e32 v101, v78
	v_sub_f32_e32 v78, v151, v90
	v_add_f32_e32 v75, v79, v75
	v_exp_f32_e32 v102, v78
	v_sub_f32_e32 v78, v149, v90
	v_add_f32_e32 v75, v80, v75
	v_exp_f32_e32 v103, v78
	v_sub_f32_e32 v78, v145, v90
	v_add_f32_e32 v75, v81, v75
	v_exp_f32_e32 v104, v78
	v_sub_f32_e32 v78, v144, v90
	v_add_f32_e32 v75, v101, v75
	v_exp_f32_e32 v105, v78
	v_sub_f32_e32 v78, v142, v90
	v_add_f32_e32 v75, v102, v75
	v_exp_f32_e32 v106, v78
	v_sub_f32_e32 v78, v141, v90
	v_add_f32_e32 v75, v103, v75
	v_exp_f32_e32 v107, v78
	v_sub_f32_e32 v78, v140, v90
	v_add_f32_e32 v75, v104, v75
	v_exp_f32_e32 v108, v78
	v_sub_f32_e32 v78, v139, v90
	v_add_f32_e32 v75, v105, v75
	v_exp_f32_e32 v109, v78
	v_sub_f32_e32 v78, v138, v90
	v_add_f32_e32 v75, v106, v75
	v_exp_f32_e32 v110, v78
	v_sub_f32_e32 v92, v92, v90
	v_add_f32_e32 v75, v107, v75
	v_exp_f32_e32 v115, v92
	v_sub_f32_e32 v91, v91, v90
	v_add_f32_e32 v75, v108, v75
	v_exp_f32_e32 v117, v91
	v_sub_f32_e32 v68, v68, v90
	v_add_f32_e32 v75, v109, v75
	v_exp_f32_e32 v119, v68
	v_sub_f32_e32 v68, v69, v90
	v_add_f32_e32 v93, v110, v75
	v_exp_f32_e32 v121, v68
	v_sub_f32_e32 v68, v70, v90
	v_mov_b32_e32 v92, v1
	v_exp_f32_e32 v123, v68
	v_sub_f32_e32 v68, v71, v90
	v_pk_add_f32 v[92:93], v[114:115], v[92:93]
	v_exp_f32_e32 v127, v68
	v_sub_f32_e32 v68, v72, v90
	v_pk_add_f32 v[92:93], v[116:117], v[92:93]
	v_exp_f32_e32 v125, v68
	v_sub_f32_e32 v68, v73, v90
	v_pk_add_f32 v[92:93], v[118:119], v[92:93]
	v_exp_f32_e32 v129, v68
	v_sub_f32_e32 v68, v94, v90
	v_pk_add_f32 v[92:93], v[120:121], v[92:93]
	v_exp_f32_e32 v159, v68
	v_sub_f32_e32 v68, v95, v90
	v_pk_add_f32 v[92:93], v[122:123], v[92:93]
	v_exp_f32_e32 v161, v68
	v_sub_f32_e32 v68, v96, v90
	v_pk_add_f32 v[92:93], v[126:127], v[92:93]
	v_exp_f32_e32 v163, v68
	v_sub_f32_e32 v68, v97, v90
	v_pk_add_f32 v[92:93], v[124:125], v[92:93]
	v_exp_f32_e32 v165, v68
	v_sub_f32_e32 v68, v98, v90
	v_pk_add_f32 v[92:93], v[128:129], v[92:93]
	v_exp_f32_e32 v167, v68
	v_sub_f32_e32 v68, v99, v90
	v_pk_add_f32 v[92:93], v[158:159], v[92:93]
	v_exp_f32_e32 v169, v68
	v_sub_f32_e32 v66, v66, v90
	v_pk_add_f32 v[92:93], v[160:161], v[92:93]
	v_exp_f32_e32 v171, v66
	v_sub_f32_e32 v66, v67, v90
	v_pk_add_f32 v[92:93], v[162:163], v[92:93]
	v_sub_f32_e32 v100, v223, v90
	v_exp_f32_e32 v173, v66
	v_pk_add_f32 v[92:93], v[164:165], v[92:93]
	v_exp_f32_e32 v175, v100
	v_pk_add_f32 v[92:93], v[166:167], v[92:93]
	v_cvt_pk_bf16_f32 v78, v74, v76
	v_cvt_pk_bf16_f32 v79, v77, v79
	v_cvt_pk_bf16_f32 v80, v80, v81
	v_cvt_pk_bf16_f32 v81, v101, v102
	v_cvt_pk_bf16_f32 v74, v103, v104
	s_nop 0
	v_pk_add_f32 v[92:93], v[168:169], v[92:93]
	v_cvt_pk_bf16_f32 v75, v105, v106
	v_cvt_pk_bf16_f32 v76, v107, v108
	v_cvt_pk_bf16_f32 v77, v109, v110
	v_cvt_pk_bf16_f32 v70, v115, v117
	v_cvt_pk_bf16_f32 v71, v119, v121
	s_nop 0
	v_pk_add_f32 v[92:93], v[170:171], v[92:93]
	v_cvt_pk_bf16_f32 v72, v123, v127
	v_cvt_pk_bf16_f32 v73, v125, v129
	v_cvt_pk_bf16_f32 v66, v159, v161
	v_cvt_pk_bf16_f32 v67, v163, v165
	v_cvt_pk_bf16_f32 v68, v167, v169
	s_nop 0
	v_pk_add_f32 v[92:93], v[172:173], v[92:93]
	v_cvt_pk_bf16_f32 v69, v171, v173
	s_waitcnt lgkmcnt(0)
	v_mov_b32_e32 v223, v90
	v_pk_fma_f32 v[154:155], v[154:155], v[174:175], v[92:93]
	v_mov_b32_e32 v92, v175
	v_pk_mul_f32 v[48:49], v[48:49], v[92:93] op_sel_hi:[1,0]
	v_pk_mul_f32 v[46:47], v[46:47], v[92:93] op_sel_hi:[1,0]
	v_pk_mul_f32 v[44:45], v[44:45], v[92:93] op_sel_hi:[1,0]
	v_pk_mul_f32 v[42:43], v[42:43], v[92:93] op_sel_hi:[1,0]
	v_pk_mul_f32 v[40:41], v[40:41], v[92:93] op_sel_hi:[1,0]
	v_pk_mul_f32 v[38:39], v[38:39], v[92:93] op_sel_hi:[1,0]
	v_pk_mul_f32 v[36:37], v[36:37], v[92:93] op_sel_hi:[1,0]
	v_pk_mul_f32 v[34:35], v[34:35], v[92:93] op_sel_hi:[1,0]
	v_pk_mul_f32 v[16:17], v[16:17], v[92:93] op_sel_hi:[1,0]
	v_pk_mul_f32 v[14:15], v[14:15], v[92:93] op_sel_hi:[1,0]
	v_pk_mul_f32 v[12:13], v[12:13], v[92:93] op_sel_hi:[1,0]
	v_pk_mul_f32 v[10:11], v[10:11], v[92:93] op_sel_hi:[1,0]
	v_pk_mul_f32 v[8:9], v[8:9], v[92:93] op_sel_hi:[1,0]
	v_pk_mul_f32 v[6:7], v[6:7], v[92:93] op_sel_hi:[1,0]
	v_pk_mul_f32 v[4:5], v[4:5], v[92:93] op_sel_hi:[1,0]
	v_pk_mul_f32 v[2:3], v[2:3], v[92:93] op_sel_hi:[1,0]
	ds_read_b64_tr_b16 v[92:93], v222
	ds_read_b64_tr_b16 v[94:95], v222 offset:1536
	ds_read_b64_tr_b16 v[96:97], v222 offset:64
	ds_read_b64_tr_b16 v[98:99], v222 offset:1600
	s_waitcnt lgkmcnt(2)
	v_mfma_f32_32x32x16_bf16 v[34:49], v[92:95], v[78:81], v[34:49]
	v_mov_b32_e32 v170, v0
	s_waitcnt lgkmcnt(0)
	v_mfma_f32_32x32x16_bf16 v[2:17], v[96:99], v[78:81], v[2:17]
	v_mfma_f32_32x32x16_bf16 v[50:65], v[92:95], v[86:89], v[50:65]
	v_mfma_f32_32x32x16_bf16 v[18:33], v[96:99], v[86:89], v[18:33]
	ds_read_b64_tr_b16 v[78:79], v222 offset:3072
	ds_read_b64_tr_b16 v[80:81], v222 offset:4608
	ds_read_b64_tr_b16 v[86:87], v222 offset:3136
	ds_read_b64_tr_b16 v[88:89], v222 offset:4672
	s_waitcnt lgkmcnt(2)
	v_mfma_f32_32x32x16_bf16 v[34:49], v[78:81], v[74:77], v[34:49]
	s_waitcnt lgkmcnt(0)
	v_mfma_f32_32x32x16_bf16 v[2:17], v[86:89], v[74:77], v[2:17]
	v_mfma_f32_32x32x16_bf16 v[50:65], v[78:81], v[82:85], v[50:65]
	ds_read_b64_tr_b16 v[74:75], v222 offset:6144
	ds_read_b64_tr_b16 v[76:77], v222 offset:7680
	ds_read_b64_tr_b16 v[78:79], v222 offset:6208
	ds_read_b64_tr_b16 v[80:81], v222 offset:7744
	s_waitcnt lgkmcnt(2)
	v_mfma_f32_32x32x16_bf16 v[34:49], v[74:77], v[70:73], v[34:49]
	s_waitcnt lgkmcnt(0)
	v_mfma_f32_32x32x16_bf16 v[2:17], v[78:81], v[70:73], v[2:17]
	ds_read_b64_tr_b16 v[70:71], v222 offset:9216
	ds_read_b64_tr_b16 v[72:73], v222 offset:10752
	ds_read_b64_tr_b16 v[74:75], v222 offset:9280
	ds_read_b64_tr_b16 v[76:77], v222 offset:10816
	s_waitcnt lgkmcnt(0)
	v_mfma_f32_32x32x16_bf16 v[18:33], v[86:89], v[82:85], v[18:33]
	s_waitcnt lgkmcnt(2)
	v_mfma_f32_32x32x16_bf16 v[34:49], v[70:73], v[66:69], v[34:49]
	s_waitcnt lgkmcnt(0)
	v_mfma_f32_32x32x16_bf16 v[2:17], v[74:77], v[66:69], v[2:17]

; __device__ __forceinline__ int otid() { int t = (int)threadIdx.x; asm volatile("" : "+v"(t)); return t; }
; #define LAS __attribute__((address_space(3)))
; #define LDS_WAIT() asm volatile("s_waitcnt lgkmcnt(0)" ::: "memory")
; template <int P_>
; __device__ __forceinline__ void dil_wave_unit(LAS unsigned char* wl, const bf16_t* DIL, bf16_t* Y, bf16_t* ST, float* LSE, const float* BT, int b, int h, int r, int nb) {
;     constexpr int dil = P_ == 0 ? 1 : (P_ == 1 ? 4 : 16), nblk = 64 / dil; constexpr bool first = P_ == 0, last = P_ == 2;
;     const int lane = otid() & 63, r32 = lane & 31, hi = lane >> 5;
;     const size_t tok0 = (size_t)b * SEQ; const size_t rstride = (size_t)dil * 64;
;     LAS float* bt = (LAS float*)(wl + VT_B);
;     for (int i = lane; i < 257; i += 64) { int j = i - 64; j = j < 0 ? 0 : (j > 128 ? 128 : j); bt[i] = BT[(P_ * 8 + h) * 129 + j]; }
;     const int btb = 128 * 4;
;     const int bvar = btb + 4 * (4 * hi - r32);
;     bf16x8 qf[2][4];
;     const bf16_t* rowb = DIL + ((size_t)(b * 8 + h) * SEQ + (size_t)(64 * nb) * dil + r) * 64;
;     constexpr size_t KOFF = pg8::DPLANE, VOFF = 2 * pg8::DPLANE;
; #pragma unroll
;     for (int qh = 0; qh < 2; ++qh)
; #pragma unroll
;         for (int d0 = 0; d0 < 4; ++d0) qf[qh][d0] = *(const bf16x8*)(rowb + (size_t)(32 * qh + r32) * rstride + hi * 8 + d0 * 16);
;     f32x16 o[2][2];
; #pragma unroll
;     for (int a = 0; a < 2; ++a)
; #pragma unroll
;         for (int c = 0; c < 2; ++c)
; #pragma unroll
;             for (int i = 0; i < 16; ++i) o[a][c][i] = 0.f;
;     float m_run[2] = {-1e30f, -1e30f}, l_run[2] = {0.f, 0.f};
;     const int voff = (4 * hi + ((lane & 15) >> 2)) * VP + (16 * ((lane >> 4) & 1) + 4 * (lane & 3)) * 2;
;     LDS_WAIT();
;     dil_block<0>(wl, rowb + KOFF + hi * 8, rowb + VOFF, rstride, qf, o, m_run, l_run, bvar, voff, lane, r32, hi, btb);
.LBB0_452:
	s_or_b64 exec, exec, s[34:35]
	s_or_b32 s83, s38, s37
	s_lshl_b32 s82, s83, 8
	s_add_u32 s34, s8, s82
	s_addc_u32 s35, s9, 0
	s_lshl_b64 s[34:35], s[34:35], 7
	v_and_b32_e32 v210, 31, v2
	s_waitcnt vmcnt(0)
	v_lshrrev_b32_e32 v3, 5, v209
	s_add_u32 s34, s4, s34
	s_addc_u32 s35, s5, s35
	v_lshlrev_b32_e32 v169, 8, v210
	v_lshlrev_b32_e32 v0, 4, v3
	v_lshl_add_u64 v[4:5], s[34:35], 0, v[0:1]
	v_lshlrev_b32_e32 v20, 9, v210
	v_mov_b32_e32 v21, v1
	v_or_b32_e32 v0, 0x2000, v169
	v_lshl_add_u64 v[6:7], v[4:5], 0, v[20:21]
	v_lshlrev_b32_e32 v0, 1, v0
	s_mov_b64 s[38:39], 0x4000000
	global_load_dwordx4 v[126:129], v[6:7], off
	global_load_dwordx4 v[114:117], v[6:7], off offset:32
	global_load_dwordx4 v[118:121], v[6:7], off offset:64
	global_load_dwordx4 v[122:125], v[6:7], off offset:96
	v_lshl_add_u64 v[6:7], v[4:5], 0, v[0:1]
	v_lshl_add_u64 v[22:23], v[4:5], 0, s[38:39]
	v_lshlrev_b32_e32 v4, 3, v209
	v_and_b32_e32 v4, 56, v4
	v_lshlrev_b32_e32 v146, 1, v4
	v_mov_b32_e32 v147, v1
	v_lshrrev_b32_e32 v70, 3, v209
	v_lshl_add_u64 v[94:95], s[34:35], 0, v[146:147]
	s_mov_b64 s[38:39], 0x8000000
	v_or_b32_e32 v71, 8, v70
	v_or_b32_e32 v72, 16, v70
	v_or_b32_e32 v73, 24, v70
	v_or_b32_e32 v74, 32, v70
	global_load_dwordx4 v[110:113], v[6:7], off
	global_load_dwordx4 v[106:109], v[6:7], off offset:32
	global_load_dwordx4 v[98:101], v[6:7], off offset:64
	global_load_dwordx4 v[102:105], v[6:7], off offset:96
	v_lshl_add_u64 v[24:25], v[94:95], 0, s[38:39]
	v_lshlrev_b32_e32 v4, 9, v70
	v_mov_b32_e32 v5, v1
	v_lshlrev_b32_e32 v6, 9, v71
	v_mov_b32_e32 v7, v1
	v_lshlrev_b32_e32 v12, 9, v72
	v_mov_b32_e32 v13, v1
	v_lshlrev_b32_e32 v14, 9, v73
	v_mov_b32_e32 v15, v1
	v_lshlrev_b32_e32 v26, 9, v74
	v_mov_b32_e32 v27, v1
	v_or_b32_e32 v75, 40, v70
	s_waitcnt lgkmcnt(0)
	v_lshl_add_u64 v[4:5], v[24:25], 0, v[4:5]
	v_lshl_add_u64 v[8:9], v[24:25], 0, v[6:7]
	v_lshl_add_u64 v[12:13], v[24:25], 0, v[12:13]
	v_lshl_add_u64 v[16:17], v[24:25], 0, v[14:15]
	v_lshl_add_u64 v[26:27], v[24:25], 0, v[26:27]
	v_lshlrev_b32_e32 v28, 9, v75
	v_mov_b32_e32 v29, v1
	v_or_b32_e32 v76, 48, v70
	global_load_dwordx4 v[4:7], v[4:5], off
	s_nop 0
	global_load_dwordx4 v[8:11], v[8:9], off
	s_nop 0
	global_load_dwordx4 v[12:15], v[12:13], off
	s_nop 0
	global_load_dwordx4 v[16:19], v[16:17], off
	v_lshl_add_u64 v[28:29], v[24:25], 0, v[28:29]
	global_load_dwordx4 v[54:57], v[26:27], off
	global_load_dwordx4 v[58:61], v[28:29], off
	v_lshlrev_b32_e32 v26, 9, v76
	v_mov_b32_e32 v27, v1
	v_or_b32_e32 v77, 56, v70
	v_lshl_add_u64 v[26:27], v[24:25], 0, v[26:27]
	v_lshlrev_b32_e32 v28, 9, v77
	v_mov_b32_e32 v29, v1
	v_lshl_add_u64 v[20:21], v[22:23], 0, v[20:21]
	v_lshl_add_u64 v[24:25], v[24:25], 0, v[28:29]
	global_load_dwordx4 v[62:65], v[26:27], off
	global_load_dwordx4 v[66:69], v[24:25], off
	global_load_dwordx4 v[50:53], v[20:21], off
	global_load_dwordx4 v[46:49], v[20:21], off offset:32
	global_load_dwordx4 v[42:45], v[20:21], off offset:64
	global_load_dwordx4 v[38:41], v[20:21], off offset:96
	v_lshl_add_u64 v[20:21], v[22:23], 0, v[0:1]
	global_load_dwordx4 v[34:37], v[20:21], off
	global_load_dwordx4 v[30:33], v[20:21], off offset:32
	global_load_dwordx4 v[22:25], v[20:21], off offset:64
	global_load_dwordx4 v[26:29], v[20:21], off offset:96
	v_lshlrev_b32_e32 v20, 2, v3
	v_sub_u32_e32 v21, v20, v210
	v_lshlrev_b32_e32 v168, 3, v3
	v_lshrrev_b32_e32 v3, 2, v2
	v_lshlrev_b32_e32 v147, 2, v21
	v_and_or_b32 v181, v3, 3, v20
	v_and_b32_e32 v3, 16, v2
	v_lshlrev_b32_e32 v2, 2, v2
	v_add_u32_e32 v211, 0x200, v147
	v_and_or_b32 v2, v2, 12, v3
	v_lshlrev_b32_e32 v182, 1, v2
	v_lshlrev_b32_e32 v171, 8, v70
	v_lshlrev_b32_e32 v172, 8, v71
	v_lshlrev_b32_e32 v173, 8, v72
	v_lshlrev_b32_e32 v174, 8, v73
	v_lshlrev_b32_e32 v175, 8, v74
	v_lshlrev_b32_e32 v176, 8, v75
	v_lshlrev_b32_e32 v177, 8, v76
	v_lshlrev_b32_e32 v178, 8, v77
	v_lshlrev_b32_e32 v2, 4, v209
	v_and_b32_e32 v2, 0x70, v2
	v_add_u32_e32 v179, s10, v2
	v_mad_u32_u24 v2, v70, s33, v179
	s_waitcnt vmcnt(15)
	ds_write_b128 v2, v[4:7]
	s_waitcnt vmcnt(14)
	ds_write_b128 v2, v[8:11] offset:1536
	s_waitcnt vmcnt(13)
	ds_write_b128 v2, v[12:15] offset:3072
	s_waitcnt vmcnt(12)
	ds_write_b128 v2, v[16:19] offset:4608
	s_waitcnt vmcnt(11)
	ds_write_b128 v2, v[54:57] offset:6144
	s_waitcnt vmcnt(10)
	ds_write_b128 v2, v[58:61] offset:7680
	s_waitcnt vmcnt(9)
	ds_write_b128 v2, v[62:65] offset:9216
	s_waitcnt vmcnt(8)
	ds_write_b128 v2, v[66:69] offset:10752
	s_waitcnt vmcnt(7)
	v_mfma_f32_32x32x16_bf16 v[2:17], v[50:53], v[126:129], 0
	v_add_u32_e32 v212, s10, v147
	v_add_u32_e32 v55, 0x3200, v212
	ds_read2_b32 v[20:21], v55 offset1:1
	v_add_u32_e32 v61, 0x3208, v212
	v_add_u32_e32 v65, 0x3220, v212
	v_add_u32_e32 v79, 0x3228, v212
	v_add_u32_e32 v81, 0x3240, v212
	s_waitcnt vmcnt(6)
	v_mfma_f32_32x32x16_bf16 v[2:17], v[46:49], v[114:117], v[2:17]
	v_add_u32_e32 v63, 0x3248, v212
	v_add_u32_e32 v59, 0x3260, v212
	v_add_u32_e32 v57, 0x3268, v212
	v_mul_u32_u24_e32 v180, 0xc0, v70
	v_add_u32_e32 v213, 0x3280, v212
	v_add_u32_e32 v214, 0x3288, v212
	v_add_u32_e32 v215, 0x32a0, v212
	s_waitcnt vmcnt(5)
	v_mfma_f32_32x32x16_bf16 v[2:17], v[42:45], v[118:121], v[2:17]
	v_add_u32_e32 v216, 0x32a8, v212
	v_add_u32_e32 v217, 0x32c0, v212
	v_add_u32_e32 v218, 0x32c8, v212
	v_add_u32_e32 v219, 0x32e0, v212
	v_add_u32_e32 v220, 0x32e8, v212
	v_add_u32_e32 v183, 0x3180, v212
	v_add_u32_e32 v184, 0x3188, v212
	s_waitcnt vmcnt(4)
	v_mfma_f32_32x32x16_bf16 v[2:17], v[38:41], v[122:125], v[2:17]
	v_add_u32_e32 v185, 0x31a0, v212
	v_add_u32_e32 v186, 0x31a8, v212
	v_add_u32_e32 v187, 0x31c0, v212
	v_add_u32_e32 v188, 0x31c8, v212
	v_add_u32_e32 v189, 0x31e0, v212
	v_add_u32_e32 v190, 0x31e8, v212
	s_cmp_eq_u32 s83, 0
	s_waitcnt lgkmcnt(0)
; #define LAS __attribute__((address_space(3)))
; #define MFMA32(a, b, c) __builtin_amdgcn_mfma_f32_32x32x16_bf16((a), (b), (c), 0, 0, 0)
; template <int DELTA> ...
;     ...
;             for (int d0 = 0; d0 < 4; ++d0) s[kvh] = MFMA32(kf[kvh][d0], qf[qh][d0], s[kvh]);
; #pragma unroll
;             for (int rr = 0; rr < 16; ++rr) { const int c4 = 4 * ((rr & 3) + 8 * (rr >> 2)); const float bias = *(const LAS float*)(wl + bvar + (VT_B + c4 + toff * 4));
;                 float v = s[kvh][rr] + bias;
;                 if (toff == 64) v = (bvar <= btb - c4) ? v : -1e30f;
;                 if (toff == -64) v = (bvar >= btb - c4) ? v : -1e30f;
;                 s[kvh][rr] = v; mx = fmaxf(mx, v); }
;         }
;         mx = fmaxf(mx, __shfl_xor(mx, 32));
;         const float m_new = fmaxf(m_run[qh], mx); const float alpha = __builtin_amdgcn_exp2f(m_run[qh] - m_new); m_run[qh] = m_new;
;         float ls = 0.f;
; #pragma unroll
;         for (int kvh = 0; kvh < 2; ++kvh) { const int toff = 64 * DELTA + 32 * (kvh - qh);
;             if (toff > 64 || toff < -64) continue;
; #pragma unroll
;             for (int rr = 0; rr < 16; ++rr) { const float e = __builtin_amdgcn_exp2f(s[kvh][rr] - m_new); s[kvh][rr] = e; ls += e; }
;             pb[qh][2 * kvh] = packp(s[kvh], 0); pb[qh][2 * kvh + 1] = packp(s[kvh], 8); }
;         l_run[qh] = l_run[qh] * alpha + ls;
; #pragma unroll
;         for (int i = 0; i < 16; ++i) { o[qh][0][i] *= alpha; o[qh][1][i] *= alpha; }
	s_nop 3
	v_add_f32_e32 v19, v2, v20
	v_add_f32_e32 v18, v3, v21
	ds_read2_b32 v[240:241], v61 offset1:1
	ds_read2_b32 v[242:243], v65 offset1:1
	ds_read2_b32 v[244:245], v79 offset1:1
	ds_read2_b32 v[246:247], v81 offset1:1
	ds_read2_b32 v[248:249], v63 offset1:1
	ds_read2_b32 v[250:251], v59 offset1:1
	ds_read2_b32 v[252:253], v57 offset1:1
	v_max3_f32 v20, v19, s79, v18
	s_cselect_b64 s[38:39], -1, 0
	s_and_b64 vcc, exec, s[38:39]
	v_add_u32_e32 v234, v179, v180
	s_waitcnt lgkmcnt(0)
	v_add_f32_e32 v54, v4, v240
	v_add_f32_e32 v56, v5, v241
	v_max3_f32 v4, v20, v54, v56
	ds_read2_b32 v[20:21], v213 offset1:1
	s_waitcnt lgkmcnt(1)
	v_add_f32_e32 v58, v6, v242
	v_add_f32_e32 v60, v7, v243
	v_max3_f32 v4, v4, v58, v60
	s_waitcnt lgkmcnt(0)
	v_add_f32_e32 v62, v8, v244
	v_add_f32_e32 v64, v9, v245
	v_max3_f32 v4, v4, v62, v64
	s_waitcnt lgkmcnt(0)
	v_add_f32_e32 v66, v10, v246
	v_add_f32_e32 v67, v11, v247
	v_max3_f32 v4, v4, v66, v67
	s_waitcnt lgkmcnt(0)
	v_add_f32_e32 v68, v12, v248
	v_add_f32_e32 v69, v13, v249
	v_max3_f32 v4, v4, v68, v69
	s_waitcnt lgkmcnt(0)
	v_add_f32_e32 v70, v14, v250
	v_add_f32_e32 v71, v15, v251
	v_max3_f32 v4, v4, v70, v71
	s_waitcnt lgkmcnt(0)
	v_add_f32_e32 v72, v16, v252
	v_add_f32_e32 v73, v17, v253
	v_max3_f32 v74, v4, v72, v73
	s_waitcnt vmcnt(3)
	v_mfma_f32_32x32x16_bf16 v[2:17], v[34:37], v[126:129], 0
	s_waitcnt vmcnt(2)
	v_mfma_f32_32x32x16_bf16 v[2:17], v[30:33], v[114:117], v[2:17]
	s_waitcnt vmcnt(1)
	v_mfma_f32_32x32x16_bf16 v[2:17], v[22:25], v[118:121], v[2:17]
	s_waitcnt vmcnt(0)
	v_mfma_f32_32x32x16_bf16 v[2:17], v[26:29], v[122:125], v[2:17]
	s_nop 11
	v_add_f32_e32 v75, v2, v20
	v_add_f32_e32 v76, v3, v21
	ds_read2_b32 v[240:241], v214 offset1:1
	ds_read2_b32 v[242:243], v215 offset1:1
	ds_read2_b32 v[244:245], v216 offset1:1
	ds_read2_b32 v[246:247], v217 offset1:1
	ds_read2_b32 v[248:249], v218 offset1:1
	ds_read2_b32 v[250:251], v219 offset1:1
	ds_read2_b32 v[252:253], v220 offset1:1
	v_max3_f32 v20, v74, v75, v76
	s_waitcnt lgkmcnt(0)
	v_add_f32_e32 v4, v4, v240
	v_add_f32_e32 v5, v5, v241
	v_max3_f32 v20, v20, v4, v5
	s_waitcnt lgkmcnt(0)
	v_add_f32_e32 v6, v6, v242
	v_add_f32_e32 v7, v7, v243
	v_max3_f32 v20, v20, v6, v7
	s_waitcnt lgkmcnt(0)
	v_add_f32_e32 v8, v8, v244
	v_add_f32_e32 v9, v9, v245
	v_max3_f32 v20, v20, v8, v9
	s_waitcnt lgkmcnt(0)
	v_add_f32_e32 v10, v10, v246
	v_add_f32_e32 v11, v11, v247
	v_max3_f32 v20, v20, v10, v11
	s_waitcnt lgkmcnt(0)
	v_add_f32_e32 v12, v12, v248
	v_add_f32_e32 v13, v13, v249
	v_max3_f32 v20, v20, v12, v13
	s_waitcnt lgkmcnt(0)
	v_add_f32_e32 v14, v14, v250
	v_add_f32_e32 v15, v15, v251
	v_max3_f32 v20, v20, v14, v15
	s_waitcnt lgkmcnt(0)
	v_add_f32_e32 v2, v16, v252
	v_add_f32_e32 v3, v17, v253
	v_max3_f32 v16, v20, v2, v3
	ds_bpermute_b32 v17, v208, v16
	s_waitcnt lgkmcnt(0)
	v_max3_f32 v170, v16, v17, s79
	v_sub_f32_e32 v17, v19, v170
	v_exp_f32_e32 v82, v17
	v_sub_f32_e32 v17, v18, v170
	v_exp_f32_e32 v84, v17
	v_sub_f32_e32 v17, v54, v170
	v_exp_f32_e32 v86, v17
	v_sub_f32_e32 v17, v56, v170
	v_exp_f32_e32 v88, v17
	v_sub_f32_e32 v17, v58, v170
	v_exp_f32_e32 v148, v17
	v_sub_f32_e32 v17, v60, v170
	v_exp_f32_e32 v152, v17
	v_sub_f32_e32 v17, v62, v170
	v_sub_f32_e32 v4, v4, v170
	v_exp_f32_e32 v154, v17
	v_sub_f32_e32 v17, v64, v170
	v_exp_f32_e32 v90, v4
	v_sub_f32_e32 v4, v5, v170
	v_exp_f32_e32 v160, v17
	v_sub_f32_e32 v17, v66, v170
	v_exp_f32_e32 v92, v4
	v_sub_f32_e32 v4, v6, v170
	v_exp_f32_e32 v150, v17
	v_sub_f32_e32 v17, v67, v170
	v_exp_f32_e32 v132, v4
	v_sub_f32_e32 v4, v7, v170
	v_exp_f32_e32 v156, v17
	v_sub_f32_e32 v17, v68, v170
	v_exp_f32_e32 v136, v4
	v_sub_f32_e32 v4, v8, v170
	v_exp_f32_e32 v158, v17
	v_sub_f32_e32 v17, v69, v170
	v_exp_f32_e32 v138, v4
	v_sub_f32_e32 v4, v9, v170
	v_exp_f32_e32 v162, v17
	v_sub_f32_e32 v17, v70, v170
	v_exp_f32_e32 v140, v4
	v_sub_f32_e32 v4, v10, v170
	v_exp_f32_e32 v164, v17
	v_sub_f32_e32 v17, v71, v170
	v_exp_f32_e32 v134, v4
	v_sub_f32_e32 v4, v11, v170
	v_exp_f32_e32 v166, v17
	v_sub_f32_e32 v17, v72, v170
	v_exp_f32_e32 v56, v4
	v_sub_f32_e32 v4, v12, v170
	v_exp_f32_e32 v142, v17
	v_sub_f32_e32 v17, v73, v170
	v_exp_f32_e32 v58, v4
	v_sub_f32_e32 v4, v13, v170
	v_exp_f32_e32 v144, v17
	v_sub_f32_e32 v17, v75, v170
	v_exp_f32_e32 v60, v4
	v_sub_f32_e32 v4, v14, v170
	v_sub_f32_e32 v2, v2, v170
	v_sub_f32_e32 v16, 0xf149f2ca, v170
	v_exp_f32_e32 v78, v17
	v_sub_f32_e32 v17, v76, v170
	v_exp_f32_e32 v62, v4
	v_sub_f32_e32 v4, v15, v170
	v_exp_f32_e32 v96, v2
	v_sub_f32_e32 v2, v3, v170
	v_exp_f32_e32 v80, v17
	v_exp_f32_e32 v64, v4
	v_exp_f32_e32 v130, v2
	v_exp_f32_e32 v54, v16
	v_mfma_f32_32x32x16_bf16 v[2:17], v[50:53], v[110:113], 0
	v_cvt_pk_bf16_f32 v18, v82, v84
	v_cvt_pk_bf16_f32 v19, v86, v88
	v_cvt_pk_bf16_f32 v20, v148, v152
	v_cvt_pk_bf16_f32 v21, v154, v160
	v_cvt_pk_bf16_f32 v70, v150, v156
	v_cvt_pk_bf16_f32 v71, v158, v162
	v_cvt_pk_bf16_f32 v72, v164, v166
	v_mfma_f32_32x32x16_bf16 v[2:17], v[46:49], v[106:109], v[2:17]
	v_cvt_pk_bf16_f32 v73, v142, v144
	v_cvt_pk_bf16_f32 v74, v78, v80
	v_cvt_pk_bf16_f32 v75, v90, v92
	v_cvt_pk_bf16_f32 v76, v132, v136
	v_cvt_pk_bf16_f32 v77, v138, v140
	v_cvt_pk_bf16_f32 v66, v134, v56
	v_cvt_pk_bf16_f32 v67, v58, v60
	v_mfma_f32_32x32x16_bf16 v[2:17], v[42:45], v[98:101], v[2:17]
	v_cvt_pk_bf16_f32 v68, v62, v64
	v_cvt_pk_bf16_f32 v69, v96, v130
	v_mfma_f32_32x32x16_bf16 v[2:17], v[38:41], v[102:105], v[2:17]
	ds_read2_b32 v[38:39], v183 offset1:1
	s_waitcnt lgkmcnt(0)
; #define LAS __attribute__((address_space(3)))
; #define MFMA32(a, b, c) __builtin_amdgcn_mfma_f32_32x32x16_bf16((a), (b), (c), 0, 0, 0)
; template <int DELTA> ...
;     ...
;             for (int d0 = 0; d0 < 4; ++d0) s[kvh] = MFMA32(kf[kvh][d0], qf[qh][d0], s[kvh]);
; #pragma unroll
;             for (int rr = 0; rr < 16; ++rr) { const int c4 = 4 * ((rr & 3) + 8 * (rr >> 2)); const float bias = *(const LAS float*)(wl + bvar + (VT_B + c4 + toff * 4));
;                 float v = s[kvh][rr] + bias;
;                 if (toff == 64) v = (bvar <= btb - c4) ? v : -1e30f;
;                 if (toff == -64) v = (bvar >= btb - c4) ? v : -1e30f;
;                 s[kvh][rr] = v; mx = fmaxf(mx, v); }
;         }
;         mx = fmaxf(mx, __shfl_xor(mx, 32));
;         const float m_new = fmaxf(m_run[qh], mx); const float alpha = __builtin_amdgcn_exp2f(m_run[qh] - m_new); m_run[qh] = m_new;
;         float ls = 0.f;
; #pragma unroll
;         for (int kvh = 0; kvh < 2; ++kvh) { const int toff = 64 * DELTA + 32 * (kvh - qh);
;             if (toff > 64 || toff < -64) continue;
; #pragma unroll
;             for (int rr = 0; rr < 16; ++rr) { const float e = __builtin_amdgcn_exp2f(s[kvh][rr] - m_new); s[kvh][rr] = e; ls += e; }
;             pb[qh][2 * kvh] = packp(s[kvh], 0); pb[qh][2 * kvh + 1] = packp(s[kvh], 8); }
;         l_run[qh] = l_run[qh] * alpha + ls;
; #pragma unroll
;         for (int i = 0; i < 16; ++i) { o[qh][0][i] *= alpha; o[qh][1][i] *= alpha; }
	s_nop 9
	v_add_f32_e32 v41, v2, v38
	v_add_f32_e32 v42, v3, v39
	ds_read2_b32 v[240:241], v184 offset1:1
	ds_read2_b32 v[242:243], v185 offset1:1
	ds_read2_b32 v[244:245], v186 offset1:1
	ds_read2_b32 v[246:247], v187 offset1:1
	ds_read2_b32 v[248:249], v188 offset1:1
	ds_read2_b32 v[250:251], v189 offset1:1
	ds_read2_b32 v[252:253], v190 offset1:1
	v_max3_f32 v39, v41, s79, v42
	s_waitcnt lgkmcnt(0)
	v_add_f32_e32 v43, v4, v240
	v_add_f32_e32 v38, v5, v241
	v_max3_f32 v4, v39, v43, v38
	s_waitcnt lgkmcnt(0)
	v_add_f32_e32 v44, v6, v242
	v_add_f32_e32 v45, v7, v243
	v_max3_f32 v4, v4, v44, v45
	s_waitcnt lgkmcnt(0)
	v_add_f32_e32 v46, v8, v244
	v_add_f32_e32 v47, v9, v245
	v_max3_f32 v4, v4, v46, v47
	s_waitcnt lgkmcnt(0)
	v_add_f32_e32 v48, v10, v246
	v_add_f32_e32 v49, v11, v247
	v_max3_f32 v4, v4, v48, v49
	s_waitcnt lgkmcnt(0)
	v_add_f32_e32 v50, v12, v248
	v_add_f32_e32 v51, v13, v249
	v_max3_f32 v4, v4, v50, v51
	s_waitcnt lgkmcnt(0)
	v_add_f32_e32 v52, v14, v250
	v_add_f32_e32 v53, v15, v251
	v_max3_f32 v4, v4, v52, v53
	s_waitcnt lgkmcnt(0)
	v_add_f32_e32 v40, v16, v252
	v_add_f32_e32 v39, v17, v253
	v_max3_f32 v83, v4, v40, v39
	v_mfma_f32_32x32x16_bf16 v[2:17], v[34:37], v[110:113], 0
	v_mfma_f32_32x32x16_bf16 v[2:17], v[30:33], v[106:109], v[2:17]
	v_mfma_f32_32x32x16_bf16 v[2:17], v[22:25], v[98:101], v[2:17]
	ds_read2_b32 v[22:23], v55 offset1:1
	v_mfma_f32_32x32x16_bf16 v[2:17], v[26:29], v[102:105], v[2:17]
	s_waitcnt lgkmcnt(0)
	s_nop 10
	v_add_f32_e32 v22, v2, v22
	v_add_f32_e32 v23, v3, v23
	ds_read2_b32 v[240:241], v61 offset1:1
	ds_read2_b32 v[242:243], v65 offset1:1
	ds_read2_b32 v[244:245], v79 offset1:1
	ds_read2_b32 v[246:247], v81 offset1:1
	ds_read2_b32 v[248:249], v63 offset1:1
	ds_read2_b32 v[250:251], v59 offset1:1
	ds_read2_b32 v[252:253], v57 offset1:1
	v_max3_f32 v24, v83, v22, v23
	s_waitcnt lgkmcnt(0)
	v_add_f32_e32 v4, v4, v240
	v_add_f32_e32 v5, v5, v241
	v_max3_f32 v24, v24, v4, v5
	s_waitcnt lgkmcnt(0)
	v_add_f32_e32 v6, v6, v242
	v_add_f32_e32 v7, v7, v243
	v_max3_f32 v24, v24, v6, v7
	s_waitcnt lgkmcnt(0)
	v_add_f32_e32 v8, v8, v244
	v_add_f32_e32 v9, v9, v245
	v_max3_f32 v24, v24, v8, v9
	s_waitcnt lgkmcnt(0)
	v_add_f32_e32 v10, v10, v246
	v_add_f32_e32 v11, v11, v247
	v_max3_f32 v24, v24, v10, v11
	s_waitcnt lgkmcnt(0)
	v_add_f32_e32 v12, v12, v248
	v_add_f32_e32 v13, v13, v249
	v_max3_f32 v24, v24, v12, v13
	s_waitcnt lgkmcnt(0)
	v_add_f32_e32 v14, v14, v250
	v_add_f32_e32 v15, v15, v251
	v_max3_f32 v24, v24, v14, v15
	s_waitcnt lgkmcnt(0)
	v_add_f32_e32 v16, v16, v252
	v_add_f32_e32 v17, v17, v253
	v_max3_f32 v2, v24, v16, v17
	ds_bpermute_b32 v3, v208, v2
	s_waitcnt lgkmcnt(0)
	v_max3_f32 v223, v2, v3, s79
	v_sub_f32_e32 v2, v41, v223
	v_exp_f32_e32 v83, v2
	v_sub_f32_e32 v2, v42, v223
	v_exp_f32_e32 v85, v2
	v_sub_f32_e32 v2, v43, v223
	v_exp_f32_e32 v87, v2
	v_sub_f32_e32 v25, v38, v223
	v_exp_f32_e32 v89, v25
	v_sub_f32_e32 v25, v44, v223
	v_pk_add_f32 v[2:3], v[82:83], 0 op_sel_hi:[1,0]
	v_exp_f32_e32 v149, v25
	v_sub_f32_e32 v25, v45, v223
	v_pk_add_f32 v[2:3], v[84:85], v[2:3]
	v_exp_f32_e32 v153, v25
	v_sub_f32_e32 v25, v46, v223
	v_pk_add_f32 v[2:3], v[86:87], v[2:3]
	v_exp_f32_e32 v155, v25
	v_sub_f32_e32 v25, v47, v223
	v_exp_f32_e32 v161, v25
	v_sub_f32_e32 v25, v48, v223
	v_pk_add_f32 v[2:3], v[88:89], v[2:3]
	v_exp_f32_e32 v151, v25
	v_sub_f32_e32 v25, v49, v223
	v_pk_add_f32 v[2:3], v[148:149], v[2:3]
	v_exp_f32_e32 v157, v25
	v_sub_f32_e32 v25, v50, v223
	v_pk_add_f32 v[2:3], v[152:153], v[2:3]
	v_exp_f32_e32 v159, v25
	v_sub_f32_e32 v25, v51, v223
	v_pk_add_f32 v[2:3], v[154:155], v[2:3]
	v_exp_f32_e32 v163, v25
	v_sub_f32_e32 v25, v52, v223
	v_pk_add_f32 v[2:3], v[160:161], v[2:3]
	v_exp_f32_e32 v165, v25
	v_sub_f32_e32 v25, v53, v223
	v_pk_add_f32 v[2:3], v[150:151], v[2:3]
	v_exp_f32_e32 v167, v25
	v_pk_add_f32 v[2:3], v[156:157], v[2:3]
	v_sub_f32_e32 v25, v40, v223
	v_pk_add_f32 v[2:3], v[158:159], v[2:3]
	v_exp_f32_e32 v143, v25
	v_sub_f32_e32 v25, v39, v223
	v_pk_add_f32 v[2:3], v[162:163], v[2:3]
	v_exp_f32_e32 v145, v25
	v_sub_f32_e32 v22, v22, v223
	v_pk_add_f32 v[2:3], v[164:165], v[2:3]
	v_exp_f32_e32 v79, v22
	v_sub_f32_e32 v22, v23, v223
	v_pk_add_f32 v[2:3], v[166:167], v[2:3]
	v_exp_f32_e32 v81, v22
	v_sub_f32_e32 v4, v4, v223
	v_exp_f32_e32 v91, v4
	v_sub_f32_e32 v4, v5, v223
	v_pk_add_f32 v[2:3], v[142:143], v[2:3]
	v_exp_f32_e32 v93, v4
	v_sub_f32_e32 v4, v6, v223
	v_pk_add_f32 v[2:3], v[144:145], v[2:3]
	v_exp_f32_e32 v133, v4
	v_sub_f32_e32 v4, v7, v223
	v_pk_add_f32 v[2:3], v[78:79], v[2:3]
	v_exp_f32_e32 v137, v4
	v_sub_f32_e32 v4, v8, v223
	v_pk_add_f32 v[2:3], v[80:81], v[2:3]
	v_exp_f32_e32 v139, v4
	v_sub_f32_e32 v4, v9, v223
	v_pk_add_f32 v[2:3], v[90:91], v[2:3]
	v_exp_f32_e32 v141, v4
	v_sub_f32_e32 v4, v10, v223
	v_pk_add_f32 v[2:3], v[92:93], v[2:3]
	v_exp_f32_e32 v135, v4
	v_pk_add_f32 v[2:3], v[132:133], v[2:3]
	v_sub_f32_e32 v4, v11, v223
	v_pk_add_f32 v[2:3], v[136:137], v[2:3]
	v_exp_f32_e32 v57, v4
	v_sub_f32_e32 v4, v12, v223
	v_pk_add_f32 v[2:3], v[138:139], v[2:3]
	v_exp_f32_e32 v59, v4
	v_sub_f32_e32 v4, v13, v223
	v_pk_add_f32 v[2:3], v[140:141], v[2:3]
	v_exp_f32_e32 v61, v4
	v_sub_f32_e32 v4, v14, v223
	v_pk_add_f32 v[2:3], v[134:135], v[2:3]
	v_exp_f32_e32 v63, v4
	v_sub_f32_e32 v4, v15, v223
	v_exp_f32_e32 v65, v4
	v_sub_f32_e32 v4, v16, v223
	v_pk_add_f32 v[2:3], v[56:57], v[2:3]
	v_exp_f32_e32 v97, v4
	v_sub_f32_e32 v4, v17, v223
	v_pk_add_f32 v[2:3], v[58:59], v[2:3]
	v_exp_f32_e32 v131, v4
	v_pk_add_f32 v[2:3], v[60:61], v[2:3]
	v_mov_b32_e32 v22, s10
	v_pk_add_f32 v[2:3], v[62:63], v[2:3]
	v_sub_f32_e32 v24, 0xf149f2ca, v223
	v_pk_add_f32 v[2:3], v[64:65], v[2:3]
	v_mad_u32_u24 v22, v181, s33, v22
	v_cvt_pk_bf16_f32 v86, v83, v85
	v_cvt_pk_bf16_f32 v87, v87, v89
	v_cvt_pk_bf16_f32 v88, v149, v153
	v_cvt_pk_bf16_f32 v89, v155, v161
	v_cvt_pk_bf16_f32 v82, v151, v157
	v_cvt_pk_bf16_f32 v83, v159, v163
	v_cvt_pk_bf16_f32 v84, v165, v167
	v_cvt_pk_bf16_f32 v85, v143, v145
	v_cvt_pk_bf16_f32 v90, v79, v81
	v_cvt_pk_bf16_f32 v91, v91, v93
	v_cvt_pk_bf16_f32 v92, v133, v137
	v_cvt_pk_bf16_f32 v93, v139, v141
	v_cvt_pk_bf16_f32 v78, v135, v57
	v_cvt_pk_bf16_f32 v79, v59, v61
	v_cvt_pk_bf16_f32 v80, v63, v65
	v_cvt_pk_bf16_f32 v81, v97, v131
	v_exp_f32_e32 v55, v24
	v_pk_add_f32 v[2:3], v[96:97], v[2:3]
	s_waitcnt lgkmcnt(0)
; #define LAS __attribute__((address_space(3)))
; #define LDS_WAIT() asm volatile("s_waitcnt lgkmcnt(0)" ::: "memory")
; __device__ __forceinline__ s16x4 vtr(const LAS unsigned char* p) { return __builtin_bit_cast(s16x4, __builtin_amdgcn_ds_read_tr16_b64_v4i16((LAS v4i16_t*)p)); }
; __device__ __forceinline__ bf16x8 cat8(s16x4 a, s16x4 b) { return (bf16x8){a[0], a[1], a[2], a[3], b[0], b[1], b[2], b[3]}; }
; #define MFMA32(a, b, c) __builtin_amdgcn_mfma_f32_32x32x16_bf16((a), (b), (c), 0, 0, 0)
; #define SBAR0() __builtin_amdgcn_sched_barrier(0)
; template <int DELTA> ...
;     u32x4 vv[8]; bf16x8 kf[2][4];
; #pragma unroll
;     for (int i = 0; i < 8; ++i) { const int idx = lane + 64 * i, row = idx >> 3, ch = idx & 7; vv[i] = *(const u32x4*)(vbase + (size_t)row * rstride + ch * 8); }
; #pragma unroll
;     for (int kvh = 0; kvh < 2; ++kvh)
; #pragma unroll
;         for (int d0 = 0; d0 < 4; ++d0) kf[kvh][d0] = *(const bf16x8*)(kbase + (size_t)(32 * kvh + r32) * rstride + d0 * 16);
;     SBAR0();
; #pragma unroll
;     for (int i = 0; i < 8; ++i) { const int idx = lane + 64 * i, row = idx >> 3, ch = idx & 7; *(LAS u32x4*)(wl + row * VP + ch * 16) = vv[i]; }
;     ...
;     LDS_WAIT();
; #pragma unroll
;     for (int j = 0; j < 4; ++j) { const LAS unsigned char* vj = wl + voff + 16 * j * VP;
;         const bf16x8 a0 = cat8(vtr(vj), vtr(vj + 8 * VP)); const bf16x8 a1 = cat8(vtr(vj + 64), vtr(vj + 8 * VP + 64));
; #pragma unroll
;         for (int qh = 0; qh < 2; ++qh) { const int toff = 64 * DELTA + 32 * ((j >> 1) - qh);
;             if (toff > 64 || toff < -64) continue;
;             o[qh][0] = MFMA32(a0, pb[qh][j], o[qh][0]); o[qh][1] = MFMA32(a1, pb[qh][j], o[qh][1]); } }
	v_add_u32_e32 v222, v22, v182
	v_pk_add_f32 v[4:5], v[130:131], v[2:3]
	ds_read_b64_tr_b16 v[130:131], v222
	ds_read_b64_tr_b16 v[132:133], v222 offset:1536
	ds_read_b64_tr_b16 v[134:135], v222 offset:64
	ds_read_b64_tr_b16 v[136:137], v222 offset:1600
	v_pk_mul_f32 v[2:3], v[54:55], 0 op_sel_hi:[1,0]
	v_pk_fma_f32 v[154:155], v[54:55], 0, v[4:5] op_sel_hi:[1,0,1]
	v_mov_b32_e32 v34, v2
	v_mov_b32_e32 v35, v2
	v_mov_b32_e32 v36, v2
	v_mov_b32_e32 v37, v2
	v_mov_b32_e32 v38, v2
	v_mov_b32_e32 v39, v2
	v_mov_b32_e32 v40, v2
	v_mov_b32_e32 v41, v2
	v_mov_b32_e32 v42, v2
	v_mov_b32_e32 v43, v2
	v_mov_b32_e32 v44, v2
	v_mov_b32_e32 v45, v2
	v_mov_b32_e32 v46, v2
	v_mov_b32_e32 v47, v2
	v_mov_b32_e32 v48, v2
	v_mov_b32_e32 v49, v2
	v_mov_b32_e32 v2, v3
	v_mov_b32_e32 v4, v3
	v_mov_b32_e32 v5, v3
	v_mov_b32_e32 v6, v3
	v_mov_b32_e32 v7, v3
	v_mov_b32_e32 v8, v3
	v_mov_b32_e32 v9, v3
	v_mov_b32_e32 v10, v3
	v_mov_b32_e32 v11, v3
	v_mov_b32_e32 v12, v3
	v_mov_b32_e32 v13, v3
	v_mov_b32_e32 v14, v3
	v_mov_b32_e32 v15, v3
	v_mov_b32_e32 v16, v3
	v_mov_b32_e32 v17, v3
	s_waitcnt lgkmcnt(2)
	v_mfma_f32_32x32x16_bf16 v[50:65], v[130:133], v[18:21], v[34:49]
	v_lshlrev_b32_e32 v156, 1, v168
	v_lshlrev_b32_e32 v168, 1, v171
	v_lshlrev_b32_e32 v166, 1, v172
	v_lshlrev_b32_e32 v164, 1, v173
	v_lshlrev_b32_e32 v162, 1, v174
	v_lshlrev_b32_e32 v160, 1, v175
	v_lshlrev_b32_e32 v158, 1, v176
	s_waitcnt lgkmcnt(0)
	v_mfma_f32_32x32x16_bf16 v[34:49], v[134:137], v[18:21], v[34:49]
	v_lshlrev_b32_e32 v152, 1, v177
	v_lshlrev_b32_e32 v150, 1, v178
	v_lshlrev_b32_e32 v148, 1, v169
	v_mfma_f32_32x32x16_bf16 v[18:33], v[130:133], v[86:89], v[2:17]
	v_mfma_f32_32x32x16_bf16 v[2:17], v[134:137], v[86:89], v[2:17]
	ds_read_b64_tr_b16 v[86:87], v222 offset:3072
	ds_read_b64_tr_b16 v[88:89], v222 offset:4608
	ds_read_b64_tr_b16 v[130:131], v222 offset:3136
	ds_read_b64_tr_b16 v[132:133], v222 offset:4672
	s_waitcnt lgkmcnt(2)
	v_mfma_f32_32x32x16_bf16 v[50:65], v[86:89], v[70:73], v[50:65]
	s_waitcnt lgkmcnt(0)
	v_mfma_f32_32x32x16_bf16 v[34:49], v[130:133], v[70:73], v[34:49]
	v_mfma_f32_32x32x16_bf16 v[18:33], v[86:89], v[82:85], v[18:33]
	v_mfma_f32_32x32x16_bf16 v[2:17], v[130:133], v[82:85], v[2:17]
	ds_read_b64_tr_b16 v[70:71], v222 offset:6144
	ds_read_b64_tr_b16 v[72:73], v222 offset:7680
	ds_read_b64_tr_b16 v[82:83], v222 offset:6208
	ds_read_b64_tr_b16 v[84:85], v222 offset:7744
	s_waitcnt lgkmcnt(2)
	v_mfma_f32_32x32x16_bf16 v[50:65], v[70:73], v[74:77], v[50:65]
	s_waitcnt lgkmcnt(0)
	v_mfma_f32_32x32x16_bf16 v[34:49], v[82:85], v[74:77], v[34:49]
	v_mfma_f32_32x32x16_bf16 v[18:33], v[70:73], v[90:93], v[18:33]
	ds_read_b64_tr_b16 v[70:71], v222 offset:9216
	ds_read_b64_tr_b16 v[72:73], v222 offset:10752
	ds_read_b64_tr_b16 v[74:75], v222 offset:9280
	ds_read_b64_tr_b16 v[76:77], v222 offset:10816
	s_waitcnt lgkmcnt(0)
	v_mfma_f32_32x32x16_bf16 v[2:17], v[82:85], v[90:93], v[2:17]
	s_waitcnt lgkmcnt(2)
	v_mfma_f32_32x32x16_bf16 v[50:65], v[70:73], v[66:69], v[50:65]
	s_waitcnt lgkmcnt(0)
	v_mfma_f32_32x32x16_bf16 v[34:49], v[74:77], v[66:69], v[34:49]
	v_mfma_f32_32x32x16_bf16 v[18:33], v[70:73], v[78:81], v[18:33]
	v_mfma_f32_32x32x16_bf16 v[2:17], v[74:77], v[78:81], v[2:17]
	s_cbranch_vccnz .LBB0_454
	v_mov_b32_e32 v157, v1
	v_lshl_add_u64 v[66:67], s[34:35], 0, v[156:157]
	s_mov_b64 s[38:39], 0x3ff8000
	v_lshl_add_u64 v[70:71], v[66:67], 0, s[38:39]
	s_mov_b64 s[38:39], 0x7ff8000
	v_lshl_add_u64 v[66:67], v[94:95], 0, s[38:39]
	v_mov_b32_e32 v169, v1
	v_mov_b32_e32 v167, v1
	v_lshl_add_u64 v[68:69], v[66:67], 0, v[168:169]
	v_lshl_add_u64 v[72:73], v[66:67], 0, v[166:167]
	v_mov_b32_e32 v165, v1
	v_mov_b32_e32 v163, v1
	global_load_dwordx4 v[82:85], v[68:69], off
	global_load_dwordx4 v[86:89], v[72:73], off
	v_lshl_add_u64 v[68:69], v[66:67], 0, v[164:165]
	v_lshl_add_u64 v[72:73], v[66:67], 0, v[162:163]
	v_mov_b32_e32 v161, v1
	v_mov_b32_e32 v159, v1
	global_load_dwordx4 v[90:93], v[68:69], off
	global_load_dwordx4 v[94:97], v[72:73], off
	v_lshl_add_u64 v[68:69], v[66:67], 0, v[160:161]
	v_lshl_add_u64 v[72:73], v[66:67], 0, v[158:159]
	v_mov_b32_e32 v153, v1
	v_mov_b32_e32 v151, v1
	v_mov_b32_e32 v149, v1
	global_load_dwordx4 v[172:175], v[68:69], off
	global_load_dwordx4 v[176:179], v[72:73], off
	v_lshl_add_u64 v[68:69], v[66:67], 0, v[152:153]
	v_lshl_add_u64 v[66:67], v[66:67], 0, v[150:151]
	v_lshl_add_u64 v[72:73], v[70:71], 0, v[148:149]
	v_lshl_add_u64 v[70:71], v[70:71], 0, v[0:1]
	global_load_dwordx4 v[192:195], v[68:69], off
	global_load_dwordx4 v[196:199], v[66:67], off
	s_nop 0
	global_load_dwordx4 v[66:69], v[72:73], off
	global_load_dwordx4 v[200:203], v[72:73], off offset:32
	global_load_dwordx4 v[204:207], v[72:73], off offset:64
	global_load_dwordx4 v[236:239], v[72:73], off offset:96
	global_load_dwordx4 v[142:145], v[70:71], off
	global_load_dwordx4 v[138:141], v[70:71], off offset:32
	global_load_dwordx4 v[134:137], v[70:71], off offset:64
	global_load_dwordx4 v[130:133], v[70:71], off offset:96
	s_waitcnt vmcnt(7)
	v_mfma_f32_32x32x16_bf16 v[66:81], v[66:69], v[126:129], 0
	ds_write_b128 v234, v[82:85]
	ds_write_b128 v234, v[86:89] offset:1536
	ds_write_b128 v234, v[90:93] offset:3072
	ds_write_b128 v234, v[94:97] offset:4608
	ds_write_b128 v234, v[172:175] offset:6144
	ds_write_b128 v234, v[176:179] offset:7680
	ds_write_b128 v234, v[192:195] offset:9216
	ds_write_b128 v234, v[196:199] offset:10752
	v_add_u32_e32 v171, 0x3100, v212
	v_add_u32_e32 v173, 0x3108, v212
	v_add_u32_e32 v175, 0x3120, v212
	v_add_u32_e32 v177, 0x3128, v212
	ds_read2_b32 v[82:83], v171 offset1:1
	ds_read2_b32 v[84:85], v173 offset1:1
	ds_read2_b32 v[86:87], v175 offset1:1
	ds_read2_b32 v[88:89], v177 offset1:1
	s_waitcnt vmcnt(6)
; #define LAS __attribute__((address_space(3)))
; #define MFMA32(a, b, c) __builtin_amdgcn_mfma_f32_32x32x16_bf16((a), (b), (c), 0, 0, 0)
; template <int DELTA> ...
;     ...
;         for (int kvh = 0; kvh < 2; ++kvh) {
;             constexpr int dummy = 0; (void)dummy;
;             const int toff = 64 * DELTA + 32 * (kvh - qh);
;             if (toff > 64 || toff < -64) continue;
; #pragma unroll
;             for (int i = 0; i < 16; ++i) s[kvh][i] = 0.f;
; #pragma unroll
;             for (int d0 = 0; d0 < 4; ++d0) s[kvh] = MFMA32(kf[kvh][d0], qf[qh][d0], s[kvh]);
; #pragma unroll
;             for (int rr = 0; rr < 16; ++rr) { const int c4 = 4 * ((rr & 3) + 8 * (rr >> 2)); const float bias = *(const LAS float*)(wl + bvar + (VT_B + c4 + toff * 4));
;                 float v = s[kvh][rr] + bias;
;                 if (toff == 64) v = (bvar <= btb - c4) ? v : -1e30f;
;                 if (toff == -64) v = (bvar >= btb - c4) ? v : -1e30f;
;                 s[kvh][rr] = v; mx = fmaxf(mx, v); }
;         }
;         mx = fmaxf(mx, __shfl_xor(mx, 32));
	v_mfma_f32_32x32x16_bf16 v[66:81], v[200:203], v[114:117], v[66:81]
	v_cmp_lt_u32_e32 vcc, s84, v147
	v_cmp_gt_u32_e64 s[40:41], s74, v211
	v_cmp_gt_u32_e64 s[42:43], s24, v211
	v_cmp_gt_u32_e64 s[44:45], s25, v211
	v_cmp_gt_u32_e64 s[48:49], s20, v211
	v_cmp_gt_u32_e64 s[46:47], s26, v211
	v_cmp_gt_u32_e64 s[52:53], s28, v211
	s_waitcnt vmcnt(5)
	v_mfma_f32_32x32x16_bf16 v[66:81], v[204:207], v[118:121], v[66:81]
	v_cmp_gt_u32_e64 s[50:51], s90, v211
	v_add_u32_e32 v179, 0x3140, v212
	v_cmp_gt_u32_e64 s[54:55], s91, v211
	v_cmp_gt_u32_e64 s[56:57], s76, v211
	v_add_u32_e32 v181, 0x3148, v212
	v_add_u32_e32 v191, 0x3160, v212
	v_add_u32_e32 v193, 0x3168, v212
	s_waitcnt vmcnt(4)
	v_mfma_f32_32x32x16_bf16 v[66:81], v[236:239], v[122:125], v[66:81]
	v_cmp_gt_u32_e64 s[58:59], s80, v211
	v_cmp_gt_u32_e64 s[60:61], s81, v211
	v_cmp_gt_u32_e64 s[62:63], s27, v211
	v_cmp_gt_u32_e64 s[64:65], s78, v211
	v_cmp_gt_u32_e64 s[66:67], s77, v211
	v_cmp_gt_u32_e64 s[68:69], s36, v211
	s_cmp_lg_u32 s83, 15
	s_waitcnt lgkmcnt(3)
	s_nop 3
	v_add_f32_e32 v66, v66, v82
	v_add_f32_e32 v67, v67, v83
	s_waitcnt lgkmcnt(2)
	v_add_f32_e32 v68, v68, v84
	v_add_f32_e32 v69, v69, v85
	v_cndmask_b32_e32 v147, v66, v230, vcc
	v_cndmask_b32_e64 v149, v67, v230, s[40:41]
	s_waitcnt lgkmcnt(1)
	v_add_f32_e32 v67, v71, v87
	v_add_f32_e32 v70, v70, v86
	v_cndmask_b32_e64 v151, v68, v230, s[42:43]
	v_cndmask_b32_e64 v153, v69, v230, s[44:45]
	v_max3_f32 v66, v147, s79, v149
	v_cndmask_b32_e64 v159, v67, v230, s[48:49]
	s_waitcnt lgkmcnt(0)
	v_add_f32_e32 v67, v72, v88
	v_max3_f32 v66, v66, v151, v153
	v_cndmask_b32_e64 v157, v70, v230, s[46:47]
	v_cndmask_b32_e64 v161, v67, v230, s[52:53]
	v_add_f32_e32 v67, v73, v89
	v_max3_f32 v66, v66, v157, v159
	v_cndmask_b32_e64 v163, v67, v230, s[50:51]
	v_max3_f32 v82, v66, v161, v163
	ds_read2_b32 v[66:67], v179 offset1:1
	ds_read2_b32 v[68:69], v181 offset1:1
	ds_read2_b32 v[70:71], v191 offset1:1
	ds_read2_b32 v[72:73], v193 offset1:1
	s_cselect_b64 s[38:39], -1, 0
	s_waitcnt lgkmcnt(3)
	v_add_f32_e32 v66, v74, v66
	v_cndmask_b32_e64 v74, v66, v230, s[54:55]
	v_add_f32_e32 v66, v75, v67
	v_cndmask_b32_e64 v75, v66, v230, s[56:57]
	v_max3_f32 v66, v82, v74, v75
	s_waitcnt vmcnt(3)
	v_mfma_f32_32x32x16_bf16 v[82:97], v[142:145], v[126:129], 0
	s_waitcnt lgkmcnt(2)
	v_add_f32_e32 v67, v76, v68
	v_cndmask_b32_e64 v76, v67, v230, s[58:59]
	v_add_f32_e32 v67, v77, v69
	v_cndmask_b32_e64 v77, v67, v230, s[60:61]
	s_waitcnt lgkmcnt(1)
	v_add_f32_e32 v67, v78, v70
	v_cndmask_b32_e64 v78, v67, v230, s[62:63]
	v_add_f32_e32 v67, v79, v71
	s_waitcnt vmcnt(2)
	v_mfma_f32_32x32x16_bf16 v[82:97], v[138:141], v[114:117], v[82:97]
	v_cndmask_b32_e64 v79, v67, v230, s[64:65]
	s_waitcnt lgkmcnt(0)
	v_add_f32_e32 v67, v80, v72
	v_max3_f32 v66, v66, v76, v77
	v_cndmask_b32_e64 v80, v67, v230, s[66:67]
	v_add_f32_e32 v67, v81, v73
	v_max3_f32 v66, v66, v78, v79
	v_cndmask_b32_e64 v81, v67, v230, s[68:69]
	s_waitcnt vmcnt(1)
	v_mfma_f32_32x32x16_bf16 v[82:97], v[134:137], v[118:121], v[82:97]
	v_max3_f32 v165, v66, v80, v81
	ds_read2_b32 v[66:67], v183 offset1:1
	ds_read2_b32 v[68:69], v184 offset1:1
	ds_read2_b32 v[70:71], v185 offset1:1
	ds_read2_b32 v[72:73], v186 offset1:1
	s_waitcnt vmcnt(0)
	v_mfma_f32_32x32x16_bf16 v[82:97], v[130:133], v[122:125], v[82:97]
	s_waitcnt lgkmcnt(3)
	s_nop 10
	v_add_f32_e32 v172, v82, v66
	v_add_f32_e32 v174, v83, v67
	ds_read2_b32 v[66:67], v187 offset1:1
	s_waitcnt lgkmcnt(3)
	v_add_f32_e32 v176, v84, v68
	v_add_f32_e32 v180, v85, v69
	s_waitcnt lgkmcnt(2)
	v_add_f32_e32 v182, v86, v70
	v_add_f32_e32 v183, v87, v71
	s_waitcnt lgkmcnt(1)
	v_add_f32_e32 v184, v88, v72
	v_add_f32_e32 v185, v89, v73
	ds_read2_b32 v[68:69], v188 offset1:1
	ds_read2_b32 v[70:71], v189 offset1:1
	ds_read2_b32 v[72:73], v190 offset1:1
	s_waitcnt lgkmcnt(3)
	v_add_f32_e32 v66, v90, v66
	v_add_f32_e32 v67, v91, v67
	s_waitcnt lgkmcnt(2)
	v_add_f32_e32 v90, v93, v69
	v_max3_f32 v69, v165, v172, v174
	v_max3_f32 v69, v69, v176, v180
	v_max3_f32 v69, v69, v182, v183
	v_max3_f32 v69, v69, v184, v185
	v_add_f32_e32 v68, v92, v68
	v_max3_f32 v69, v69, v66, v67
	s_waitcnt lgkmcnt(1)
	v_add_f32_e32 v91, v94, v70
	v_add_f32_e32 v92, v95, v71
	v_max3_f32 v69, v69, v68, v90
	s_waitcnt lgkmcnt(0)
	v_add_f32_e32 v93, v96, v72
	v_add_f32_e32 v94, v97, v73
	v_max3_f32 v69, v69, v91, v92
	v_max3_f32 v69, v69, v93, v94
	ds_bpermute_b32 v70, v208, v69
	s_waitcnt lgkmcnt(0)
; #define LAS __attribute__((address_space(3)))
; #define MFMA32(a, b, c) __builtin_amdgcn_mfma_f32_32x32x16_bf16((a), (b), (c), 0, 0, 0)
; template <int DELTA> ...
;     ...
;             for (int d0 = 0; d0 < 4; ++d0) s[kvh] = MFMA32(kf[kvh][d0], qf[qh][d0], s[kvh]);
; #pragma unroll
;             for (int rr = 0; rr < 16; ++rr) { const int c4 = 4 * ((rr & 3) + 8 * (rr >> 2)); const float bias = *(const LAS float*)(wl + bvar + (VT_B + c4 + toff * 4));
;                 float v = s[kvh][rr] + bias;
;                 if (toff == 64) v = (bvar <= btb - c4) ? v : -1e30f;
;                 if (toff == -64) v = (bvar >= btb - c4) ? v : -1e30f;
;                 s[kvh][rr] = v; mx = fmaxf(mx, v); }
;         }
;         mx = fmaxf(mx, __shfl_xor(mx, 32));
;         const float m_new = fmaxf(m_run[qh], mx); const float alpha = __builtin_amdgcn_exp2f(m_run[qh] - m_new); m_run[qh] = m_new;
;         float ls = 0.f;
; #pragma unroll
;         for (int kvh = 0; kvh < 2; ++kvh) { const int toff = 64 * DELTA + 32 * (kvh - qh);
;             if (toff > 64 || toff < -64) continue;
; #pragma unroll
;             for (int rr = 0; rr < 16; ++rr) { const float e = __builtin_amdgcn_exp2f(s[kvh][rr] - m_new); s[kvh][rr] = e; ls += e; }
;             pb[qh][2 * kvh] = packp(s[kvh], 0); pb[qh][2 * kvh + 1] = packp(s[kvh], 8); }
;         l_run[qh] = l_run[qh] * alpha + ls;
; #pragma unroll
;         for (int i = 0; i < 16; ++i) { o[qh][0][i] *= alpha; o[qh][1][i] *= alpha; }
	v_max3_f32 v233, v170, v69, v70
	v_sub_f32_e32 v69, v147, v233
	v_exp_f32_e32 v169, v69
	v_sub_f32_e32 v69, v149, v233
	v_exp_f32_e32 v235, v69
	v_sub_f32_e32 v69, v151, v233
	v_exp_f32_e32 v237, v69
	v_sub_f32_e32 v69, v153, v233
	v_exp_f32_e32 v225, v69
	v_sub_f32_e32 v69, v157, v233
	v_exp_f32_e32 v236, v69
	v_sub_f32_e32 v69, v159, v233
	v_exp_f32_e32 v238, v69
	v_sub_f32_e32 v69, v161, v233
	v_exp_f32_e32 v165, v69
	v_sub_f32_e32 v69, v163, v233
	v_exp_f32_e32 v167, v69
	v_sub_f32_e32 v69, v74, v233
	v_exp_f32_e32 v151, v69
	v_sub_f32_e32 v69, v75, v233
	v_exp_f32_e32 v157, v69
	v_sub_f32_e32 v69, v76, v233
	v_exp_f32_e32 v159, v69
	v_sub_f32_e32 v69, v77, v233
	v_exp_f32_e32 v161, v69
	v_sub_f32_e32 v69, v78, v233
	v_exp_f32_e32 v163, v69
	v_sub_f32_e32 v69, v79, v233
	v_exp_f32_e32 v147, v69
	v_sub_f32_e32 v69, v80, v233
	v_exp_f32_e32 v149, v69
	v_sub_f32_e32 v69, v81, v233
	v_exp_f32_e32 v153, v69
	v_sub_f32_e32 v69, v172, v233
	v_sub_f32_e32 v187, v170, v233
	v_exp_f32_e32 v170, v69
	v_sub_f32_e32 v69, v174, v233
	v_exp_f32_e32 v174, v69
	v_sub_f32_e32 v69, v176, v233
	v_exp_f32_e32 v178, v69
	v_sub_f32_e32 v69, v180, v233
	v_exp_f32_e32 v172, v69
	v_sub_f32_e32 v69, v182, v233
	v_exp_f32_e32 v176, v69
	v_sub_f32_e32 v69, v183, v233
	v_exp_f32_e32 v180, v69
	v_sub_f32_e32 v69, v184, v233
	v_sub_f32_e32 v66, v66, v233
	v_exp_f32_e32 v182, v69
	v_sub_f32_e32 v69, v185, v233
	v_exp_f32_e32 v186, v66
	v_sub_f32_e32 v66, v67, v233
	v_exp_f32_e32 v184, v69
	v_exp_f32_e32 v188, v66
	v_sub_f32_e32 v95, v68, v233
	v_mfma_f32_32x32x16_bf16 v[66:81], v[142:145], v[110:113], 0
	v_sub_f32_e32 v90, v90, v233
	v_exp_f32_e32 v144, v90
	v_sub_f32_e32 v90, v91, v233
	v_exp_f32_e32 v190, v90
	v_sub_f32_e32 v90, v92, v233
	v_exp_f32_e32 v192, v90
	v_sub_f32_e32 v90, v93, v233
	v_mfma_f32_32x32x16_bf16 v[66:81], v[138:141], v[106:109], v[66:81]
	v_exp_f32_e32 v138, v90
	v_sub_f32_e32 v90, v94, v233
	v_cvt_pk_bf16_f32 v86, v169, v235
	v_cvt_pk_bf16_f32 v87, v237, v225
	v_cvt_pk_bf16_f32 v88, v236, v238
	v_cvt_pk_bf16_f32 v89, v165, v167
	v_cvt_pk_bf16_f32 v82, v151, v157
	v_mfma_f32_32x32x16_bf16 v[66:81], v[134:137], v[98:101], v[66:81]
	v_cvt_pk_bf16_f32 v83, v159, v161
	v_cvt_pk_bf16_f32 v84, v163, v147
	v_cvt_pk_bf16_f32 v85, v149, v153
	v_exp_f32_e32 v142, v95
	v_exp_f32_e32 v140, v90
	v_cvt_pk_bf16_f32 v94, v170, v174
	v_cvt_pk_bf16_f32 v95, v178, v172
	v_mfma_f32_32x32x16_bf16 v[66:81], v[130:133], v[102:105], v[66:81]
	v_cvt_pk_bf16_f32 v96, v176, v180
	v_cvt_pk_bf16_f32 v97, v182, v184
	v_cvt_pk_bf16_f32 v90, v186, v188
	v_cvt_pk_bf16_f32 v91, v142, v144
	v_cvt_pk_bf16_f32 v92, v190, v192
	v_cvt_pk_bf16_f32 v93, v138, v140
	ds_read2_b32 v[136:137], v171 offset1:1
	ds_read2_b32 v[130:131], v173 offset1:1
	ds_read2_b32 v[132:133], v175 offset1:1
	ds_read2_b32 v[194:195], v177 offset1:1
	v_exp_f32_e32 v134, v187
	s_waitcnt lgkmcnt(3)
	s_nop 5
	v_add_f32_e32 v66, v66, v136
	v_cndmask_b32_e32 v135, v66, v230, vcc
	v_add_f32_e32 v66, v67, v137
	v_cndmask_b32_e64 v136, v66, v230, s[40:41]
	s_waitcnt lgkmcnt(2)
	v_add_f32_e32 v66, v68, v130
	v_cndmask_b32_e64 v137, v66, v230, s[42:43]
	v_add_f32_e32 v66, v69, v131
	v_cndmask_b32_e64 v131, v66, v230, s[44:45]
	s_waitcnt lgkmcnt(1)
	v_add_f32_e32 v66, v70, v132
	v_cndmask_b32_e64 v132, v66, v230, s[46:47]
	v_add_f32_e32 v66, v71, v133
	v_cndmask_b32_e64 v133, v66, v230, s[48:49]
	s_waitcnt lgkmcnt(0)
	v_add_f32_e32 v66, v72, v194
	v_cndmask_b32_e64 v139, v66, v230, s[52:53]
	ds_read2_b32 v[66:67], v179 offset1:1
	v_add_f32_e32 v68, v73, v195
	v_cndmask_b32_e64 v141, v68, v230, s[50:51]
	ds_read2_b32 v[68:69], v181 offset1:1
	ds_read2_b32 v[70:71], v191 offset1:1
	ds_read2_b32 v[72:73], v193 offset1:1
	v_pk_mul_f32 v[64:65], v[64:65], v[134:135] op_sel_hi:[1,0]
	s_waitcnt lgkmcnt(3)
	v_add_f32_e32 v66, v74, v66
	v_max3_f32 v74, v135, s79, v136
	v_max3_f32 v74, v74, v137, v131
	v_add_f32_e32 v67, v75, v67
	v_max3_f32 v74, v74, v132, v133
	v_cndmask_b32_e64 v66, v66, v230, s[54:55]
	v_cndmask_b32_e64 v67, v67, v230, s[56:57]
	s_waitcnt lgkmcnt(2)
	v_add_f32_e32 v68, v76, v68
	v_add_f32_e32 v69, v77, v69
	v_max3_f32 v74, v74, v139, v141
	v_cndmask_b32_e64 v68, v68, v230, s[58:59]
	v_cndmask_b32_e64 v69, v69, v230, s[60:61]
	s_waitcnt lgkmcnt(1)
	v_add_f32_e32 v70, v78, v70
	v_add_f32_e32 v71, v79, v71
	v_max3_f32 v74, v74, v66, v67
	v_cndmask_b32_e64 v70, v70, v230, s[62:63]
	v_cndmask_b32_e64 v71, v71, v230, s[64:65]
	s_waitcnt lgkmcnt(0)
	v_add_f32_e32 v72, v80, v72
	v_add_f32_e32 v73, v81, v73
	v_max3_f32 v74, v74, v68, v69
	v_cndmask_b32_e64 v72, v72, v230, s[66:67]
	v_cndmask_b32_e64 v73, v73, v230, s[68:69]
	v_max3_f32 v74, v74, v70, v71
	v_max3_f32 v74, v74, v72, v73
	ds_bpermute_b32 v75, v208, v74
	v_pk_mul_f32 v[62:63], v[62:63], v[134:135] op_sel_hi:[1,0]
	v_pk_mul_f32 v[60:61], v[60:61], v[134:135] op_sel_hi:[1,0]
	v_pk_mul_f32 v[58:59], v[58:59], v[134:135] op_sel_hi:[1,0]
	v_pk_mul_f32 v[56:57], v[56:57], v[134:135] op_sel_hi:[1,0]
	s_waitcnt lgkmcnt(0)
; #define LAS __attribute__((address_space(3)))
; #define LDS_WAIT() asm volatile("s_waitcnt lgkmcnt(0)" ::: "memory")
; __device__ __forceinline__ s16x4 vtr(const LAS unsigned char* p) { return __builtin_bit_cast(s16x4, __builtin_amdgcn_ds_read_tr16_b64_v4i16((LAS v4i16_t*)p)); }
; __device__ __forceinline__ bf16x8 cat8(s16x4 a, s16x4 b) { return (bf16x8){a[0], a[1], a[2], a[3], b[0], b[1], b[2], b[3]}; }
; #define MFMA32(a, b, c) __builtin_amdgcn_mfma_f32_32x32x16_bf16((a), (b), (c), 0, 0, 0)
; template <int DELTA> ...
;     ...
;         mx = fmaxf(mx, __shfl_xor(mx, 32));
;         const float m_new = fmaxf(m_run[qh], mx); const float alpha = __builtin_amdgcn_exp2f(m_run[qh] - m_new); m_run[qh] = m_new;
;         float ls = 0.f;
; #pragma unroll
;         for (int kvh = 0; kvh < 2; ++kvh) { const int toff = 64 * DELTA + 32 * (kvh - qh);
;             if (toff > 64 || toff < -64) continue;
; #pragma unroll
;             for (int rr = 0; rr < 16; ++rr) { const float e = __builtin_amdgcn_exp2f(s[kvh][rr] - m_new); s[kvh][rr] = e; ls += e; }
;             pb[qh][2 * kvh] = packp(s[kvh], 0); pb[qh][2 * kvh + 1] = packp(s[kvh], 8); }
;         l_run[qh] = l_run[qh] * alpha + ls;
; #pragma unroll
;         for (int i = 0; i < 16; ++i) { o[qh][0][i] *= alpha; o[qh][1][i] *= alpha; }
;     }
;     LDS_WAIT();
; #pragma unroll
;     for (int j = 0; j < 4; ++j) { const LAS unsigned char* vj = wl + voff + 16 * j * VP;
;         const bf16x8 a0 = cat8(vtr(vj), vtr(vj + 8 * VP)); const bf16x8 a1 = cat8(vtr(vj + 64), vtr(vj + 8 * VP + 64));
; #pragma unroll
;         for (int qh = 0; qh < 2; ++qh) { const int toff = 64 * DELTA + 32 * ((j >> 1) - qh);
;             if (toff > 64 || toff < -64) continue;
;             o[qh][0] = MFMA32(a0, pb[qh][j], o[qh][0]); o[qh][1] = MFMA32(a1, pb[qh][j], o[qh][1]); } }
	v_max3_f32 v130, v223, v74, v75
	v_sub_f32_e32 v74, v135, v130
	v_sub_f32_e32 v66, v66, v130
	v_exp_f32_e32 v171, v74
	v_sub_f32_e32 v74, v136, v130
	v_exp_f32_e32 v187, v66
	v_sub_f32_e32 v66, v67, v130
	v_exp_f32_e32 v175, v74
	v_sub_f32_e32 v74, v137, v130
	v_exp_f32_e32 v189, v66
	v_sub_f32_e32 v66, v68, v130
	v_exp_f32_e32 v179, v74
	v_sub_f32_e32 v74, v131, v130
	v_exp_f32_e32 v143, v66
	v_sub_f32_e32 v66, v69, v130
	v_exp_f32_e32 v173, v74
	v_sub_f32_e32 v74, v132, v130
	v_exp_f32_e32 v145, v66
	v_sub_f32_e32 v66, v70, v130
	v_exp_f32_e32 v177, v74
	v_sub_f32_e32 v74, v133, v130
	v_exp_f32_e32 v191, v66
	v_sub_f32_e32 v66, v71, v130
	v_exp_f32_e32 v181, v74
	v_sub_f32_e32 v74, v139, v130
	v_exp_f32_e32 v193, v66
	v_sub_f32_e32 v66, v72, v130
	v_exp_f32_e32 v183, v74
	v_sub_f32_e32 v74, v141, v130
	v_exp_f32_e32 v139, v66
	v_sub_f32_e32 v66, v73, v130
	v_exp_f32_e32 v185, v74
	v_exp_f32_e32 v141, v66
	v_cvt_pk_bf16_f32 v70, v171, v175
	v_cvt_pk_bf16_f32 v71, v179, v173
	v_cvt_pk_bf16_f32 v72, v177, v181
	v_cvt_pk_bf16_f32 v73, v183, v185
	v_cvt_pk_bf16_f32 v66, v187, v189
	v_cvt_pk_bf16_f32 v67, v143, v145
	v_cvt_pk_bf16_f32 v68, v191, v193
	v_cvt_pk_bf16_f32 v69, v139, v141
	s_waitcnt lgkmcnt(0)
	ds_read_b64_tr_b16 v[74:75], v222
	ds_read_b64_tr_b16 v[76:77], v222 offset:1536
	ds_read_b64_tr_b16 v[80:81], v222 offset:1600
	ds_read_b64_tr_b16 v[78:79], v222 offset:64
	v_pk_mul_f32 v[54:55], v[54:55], v[134:135] op_sel_hi:[1,0]
	v_pk_mul_f32 v[52:53], v[52:53], v[134:135] op_sel_hi:[1,0]
	v_pk_mul_f32 v[50:51], v[50:51], v[134:135] op_sel_hi:[1,0]
	v_pk_mul_f32 v[48:49], v[48:49], v[134:135] op_sel_hi:[1,0]
	v_pk_mul_f32 v[46:47], v[46:47], v[134:135] op_sel_hi:[1,0]
	s_waitcnt lgkmcnt(2)
	v_mfma_f32_32x32x16_bf16 v[50:65], v[74:77], v[86:89], v[50:65]
	v_mul_f32_e64 v44, v44, v134
	v_mul_f32_e64 v45, v45, v134
	v_mul_f32_e64 v42, v42, v134
	v_mul_f32_e64 v43, v43, v134
	v_mul_f32_e64 v40, v40, v134
	v_mul_f32_e64 v41, v41, v134
	v_pk_mul_f32 v[38:39], v[38:39], v[134:135] op_sel_hi:[1,0]
	v_pk_mul_f32 v[36:37], v[36:37], v[134:135] op_sel_hi:[1,0]
	v_pk_mul_f32 v[34:35], v[34:35], v[134:135] op_sel_hi:[1,0]
	s_waitcnt lgkmcnt(0)
	s_nop 0
	v_mfma_f32_32x32x16_bf16 v[34:49], v[78:81], v[86:89], v[34:49]
	ds_read_b64_tr_b16 v[74:75], v222 offset:3072
	ds_read_b64_tr_b16 v[76:77], v222 offset:4608
	ds_read_b64_tr_b16 v[80:81], v222 offset:4672
	ds_read_b64_tr_b16 v[78:79], v222 offset:3136
	s_waitcnt lgkmcnt(2)
	v_mfma_f32_32x32x16_bf16 v[50:65], v[74:77], v[82:85], v[50:65]
	v_add_f32_e32 v74, 0, v169
	v_add_f32_e32 v74, v235, v74
	v_add_f32_e32 v86, v237, v74
	ds_read_b64_tr_b16 v[74:75], v222 offset:6144
	ds_read_b64_tr_b16 v[76:77], v222 offset:7680
	s_waitcnt lgkmcnt(2)
	v_mfma_f32_32x32x16_bf16 v[34:49], v[78:81], v[82:85], v[34:49]
	v_add_f32_e32 v78, v225, v86
	v_add_f32_e32 v78, v236, v78
	v_add_f32_e32 v82, v238, v78
	v_sub_f32_e32 v78, v223, v130
	v_exp_f32_e32 v135, v78
	ds_read_b64_tr_b16 v[80:81], v222 offset:7744
	ds_read_b64_tr_b16 v[78:79], v222 offset:6208
	v_add_f32_e32 v82, v165, v82
	v_add_f32_e32 v83, v167, v82
	v_mov_b32_e32 v82, v135
	v_pk_mul_f32 v[32:33], v[32:33], v[82:83] op_sel_hi:[1,0]
	v_pk_mul_f32 v[30:31], v[30:31], v[82:83] op_sel_hi:[1,0]
	v_pk_mul_f32 v[28:29], v[28:29], v[82:83] op_sel_hi:[1,0]
	v_pk_mul_f32 v[26:27], v[26:27], v[82:83] op_sel_hi:[1,0]
	v_pk_mul_f32 v[24:25], v[24:25], v[82:83] op_sel_hi:[1,0]
	v_pk_mul_f32 v[22:23], v[22:23], v[82:83] op_sel_hi:[1,0]
	v_pk_mul_f32 v[20:21], v[20:21], v[82:83] op_sel_hi:[1,0]
	v_pk_mul_f32 v[18:19], v[18:19], v[82:83] op_sel_hi:[1,0]
	v_pk_mul_f32 v[16:17], v[16:17], v[82:83] op_sel_hi:[1,0]
	v_pk_mul_f32 v[14:15], v[14:15], v[82:83] op_sel_hi:[1,0]
	v_pk_mul_f32 v[12:13], v[12:13], v[82:83] op_sel_hi:[1,0]
	v_pk_mul_f32 v[10:11], v[10:11], v[82:83] op_sel_hi:[1,0]
	v_pk_mul_f32 v[8:9], v[8:9], v[82:83] op_sel_hi:[1,0]
	v_pk_mul_f32 v[6:7], v[6:7], v[82:83] op_sel_hi:[1,0]
	v_pk_mul_f32 v[4:5], v[4:5], v[82:83] op_sel_hi:[1,0]
	v_pk_mul_f32 v[2:3], v[2:3], v[82:83] op_sel_hi:[1,0]
	s_waitcnt lgkmcnt(2)
	v_mfma_f32_32x32x16_bf16 v[18:33], v[74:77], v[70:73], v[18:33]
	v_mov_b32_e32 v223, v130
	s_waitcnt lgkmcnt(0)
	v_mfma_f32_32x32x16_bf16 v[2:17], v[78:81], v[70:73], v[2:17]
	v_add_f32_e32 v70, v151, v83
	v_add_f32_e32 v70, v157, v70
	v_add_f32_e32 v70, v159, v70
	v_add_f32_e32 v70, v161, v70
	v_mfma_f32_32x32x16_bf16 v[34:49], v[78:81], v[94:97], v[34:49]
	v_add_f32_e32 v78, v163, v70
	v_add_f32_e32 v78, v147, v78
	v_add_f32_e32 v78, v149, v78
	v_add_f32_e32 v78, v153, v78
	v_mov_b32_e32 v79, v1
	v_pk_add_f32 v[78:79], v[170:171], v[78:79]
	v_mov_b32_e32 v170, v233
	v_mfma_f32_32x32x16_bf16 v[50:65], v[74:77], v[94:97], v[50:65]
	v_add_f32_e64 v78, v174, v78
	v_add_f32_e64 v79, v175, v79
	ds_read_b64_tr_b16 v[74:75], v222 offset:9216
	ds_read_b64_tr_b16 v[76:77], v222 offset:10752
	v_add_f32_e64 v78, v178, v78
	v_add_f32_e64 v79, v179, v79
	ds_read_b64_tr_b16 v[72:73], v222 offset:10816
	ds_read_b64_tr_b16 v[70:71], v222 offset:9280
	v_pk_add_f32 v[78:79], v[172:173], v[78:79]
	s_waitcnt lgkmcnt(0)
	s_nop 0
	v_pk_add_f32 v[78:79], v[176:177], v[78:79]
	s_waitcnt lgkmcnt(2)
	v_mfma_f32_32x32x16_bf16 v[50:65], v[74:77], v[90:93], v[50:65]
	v_add_f32_e64 v78, v180, v78
	v_add_f32_e64 v79, v181, v79
	v_add_f32_e64 v78, v182, v78
	v_add_f32_e64 v79, v183, v79
	v_add_f32_e64 v78, v184, v78
	v_add_f32_e64 v79, v185, v79
	v_pk_add_f32 v[78:79], v[186:187], v[78:79]
	s_waitcnt lgkmcnt(0)
	v_mfma_f32_32x32x16_bf16 v[34:49], v[70:73], v[90:93], v[34:49]
	v_add_f32_e64 v78, v188, v78
	v_add_f32_e64 v79, v189, v79
	v_mfma_f32_32x32x16_bf16 v[18:33], v[74:77], v[66:69], v[18:33]
	v_add_f32_e64 v74, v142, v78
	v_add_f32_e64 v75, v143, v79
	v_add_f32_e64 v74, v144, v74
	v_add_f32_e64 v75, v145, v75
	v_add_f32_e64 v74, v190, v74
	v_add_f32_e64 v75, v191, v75
	v_pk_add_f32 v[74:75], v[192:193], v[74:75]
	v_mfma_f32_32x32x16_bf16 v[2:17], v[70:73], v[66:69], v[2:17]
	v_add_f32_e64 v74, v138, v74
	v_add_f32_e64 v75, v139, v75
	v_add_f32_e64 v74, v140, v74
	v_add_f32_e64 v75, v141, v75
	v_fma_f32 v154, v154, v134, v74
	v_fma_f32 v155, v155, v135, v75
	s_andn2_b64 vcc, exec, s[38:39]
	s_cbranch_vccz .LBB0_455
	s_branch .LBB0_456

; #define LAS __attribute__((address_space(3)))
; #define MFMA32(a, b, c) __builtin_amdgcn_mfma_f32_32x32x16_bf16((a), (b), (c), 0, 0, 0)
; #define SBAR0() __builtin_amdgcn_sched_barrier(0)
; template <int DELTA> ...
;     u32x4 vv[8]; bf16x8 kf[2][4];
; #pragma unroll
;     for (int i = 0; i < 8; ++i) { const int idx = lane + 64 * i, row = idx >> 3, ch = idx & 7; vv[i] = *(const u32x4*)(vbase + (size_t)row * rstride + ch * 8); }
; #pragma unroll
;     for (int kvh = 0; kvh < 2; ++kvh)
; #pragma unroll
;         for (int d0 = 0; d0 < 4; ++d0) kf[kvh][d0] = *(const bf16x8*)(kbase + (size_t)(32 * kvh + r32) * rstride + d0 * 16);
;     SBAR0();
; #pragma unroll
;     for (int i = 0; i < 8; ++i) { const int idx = lane + 64 * i, row = idx >> 3, ch = idx & 7; *(LAS u32x4*)(wl + row * VP + ch * 16) = vv[i]; }
;     bf16x8 pb[2][4];
; #pragma unroll
;     for (int qh = 0; qh < 2; ++qh) {
;         f32x16 s[2]; float mx = -1e30f;
; #pragma unroll
;         for (int kvh = 0; kvh < 2; ++kvh) {
;             constexpr int dummy = 0; (void)dummy;
;             const int toff = 64 * DELTA + 32 * (kvh - qh);
;             if (toff > 64 || toff < -64) continue;
; #pragma unroll
;             for (int i = 0; i < 16; ++i) s[kvh][i] = 0.f;
; #pragma unroll
;             for (int d0 = 0; d0 < 4; ++d0) s[kvh] = MFMA32(kf[kvh][d0], qf[qh][d0], s[kvh]);
; #pragma unroll
;             for (int rr = 0; rr < 16; ++rr) { const int c4 = 4 * ((rr & 3) + 8 * (rr >> 2)); const float bias = *(const LAS float*)(wl + bvar + (VT_B + c4 + toff * 4));
;                 float v = s[kvh][rr] + bias;
;                 if (toff == 64) v = (bvar <= btb - c4) ? v : -1e30f;
;                 if (toff == -64) v = (bvar >= btb - c4) ? v : -1e30f;
;                 s[kvh][rr] = v; mx = fmaxf(mx, v); }
.LBB0_455:
	v_mov_b32_e32 v157, v1
	v_lshl_add_u64 v[66:67], s[34:35], 0, v[156:157]
	s_mov_b64 s[38:39], 0x4008000
	v_mov_b32_e32 v147, v1
	v_lshl_add_u64 v[90:91], v[66:67], 0, s[38:39]
	v_lshl_add_u64 v[66:67], s[34:35], 0, v[146:147]
	s_mov_b64 s[34:35], 0x8008000
	v_lshl_add_u64 v[92:93], v[66:67], 0, s[34:35]
	v_mov_b32_e32 v169, v1
	v_mov_b32_e32 v167, v1
	v_mov_b32_e32 v165, v1
	v_mov_b32_e32 v163, v1
	v_mov_b32_e32 v161, v1
	v_mov_b32_e32 v159, v1
	v_mov_b32_e32 v153, v1
	v_mov_b32_e32 v151, v1
	v_lshl_add_u64 v[66:67], v[92:93], 0, v[168:169]
	v_lshl_add_u64 v[70:71], v[92:93], 0, v[166:167]
	v_lshl_add_u64 v[74:75], v[92:93], 0, v[164:165]
	v_lshl_add_u64 v[78:79], v[92:93], 0, v[162:163]
	v_lshl_add_u64 v[82:83], v[92:93], 0, v[160:161]
	v_lshl_add_u64 v[86:87], v[92:93], 0, v[158:159]
	v_lshl_add_u64 v[94:95], v[92:93], 0, v[152:153]
	v_lshl_add_u64 v[92:93], v[92:93], 0, v[150:151]
	v_mov_b32_e32 v149, v1
	global_load_dwordx4 v[66:69], v[66:67], off
	s_nop 0
	global_load_dwordx4 v[70:73], v[70:71], off
	s_nop 0
	global_load_dwordx4 v[74:77], v[74:75], off
	s_nop 0
	global_load_dwordx4 v[78:81], v[78:79], off
	s_nop 0
	global_load_dwordx4 v[82:85], v[82:83], off
	s_nop 0
	global_load_dwordx4 v[86:89], v[86:87], off
	s_nop 0
	global_load_dwordx4 v[158:161], v[94:95], off
	global_load_dwordx4 v[162:165], v[92:93], off
	v_lshl_add_u64 v[92:93], v[90:91], 0, v[148:149]
	v_lshl_add_u64 v[94:95], v[90:91], 0, v[0:1]
	global_load_dwordx4 v[150:153], v[92:93], off
	global_load_dwordx4 v[146:149], v[92:93], off offset:32
	global_load_dwordx4 v[138:141], v[92:93], off offset:64
	global_load_dwordx4 v[142:145], v[92:93], off offset:96
	global_load_dwordx4 v[134:137], v[94:95], off
	global_load_dwordx4 v[130:133], v[94:95], off offset:32
	s_nop 0
	global_load_dwordx4 v[90:93], v[94:95], off offset:64
	s_nop 0
	global_load_dwordx4 v[94:97], v[94:95], off offset:96
	s_waitcnt vmcnt(15)
	ds_write_b128 v234, v[66:69]
	s_waitcnt vmcnt(14)
	ds_write_b128 v234, v[70:73] offset:1536
	s_waitcnt vmcnt(13)
	ds_write_b128 v234, v[74:77] offset:3072
	s_waitcnt vmcnt(12)
	ds_write_b128 v234, v[78:81] offset:4608
	s_waitcnt vmcnt(11)
	ds_write_b128 v234, v[82:85] offset:6144
	s_waitcnt vmcnt(10)
	ds_write_b128 v234, v[86:89] offset:7680
	s_waitcnt vmcnt(9)
	ds_write_b128 v234, v[158:161] offset:9216
	s_waitcnt vmcnt(8)
	ds_write_b128 v234, v[162:165] offset:10752
	s_waitcnt vmcnt(7)
	v_mfma_f32_32x32x16_bf16 v[66:81], v[150:153], v[126:129], 0
	v_add_u32_e32 v0, 0x3300, v212
	ds_read2_b32 v[82:83], v0 offset1:1
	v_cmp_lt_u32_e32 vcc, s87, v211
	v_cmp_lt_u32_e64 s[40:41], s74, v211
	v_cmp_lt_u32_e64 s[42:43], s24, v211
	v_cmp_lt_u32_e64 s[44:45], s25, v211
	v_cmp_lt_u32_e64 s[46:47], s26, v211
	s_waitcnt vmcnt(6)
	v_mfma_f32_32x32x16_bf16 v[66:81], v[146:149], v[114:117], v[66:81]
	v_add_u32_e32 v115, 0x3308, v212
	v_add_u32_e32 v117, 0x3320, v212
	v_cmp_lt_u32_e64 s[48:49], s20, v211
	v_cmp_lt_u32_e64 s[50:51], s28, v211
	v_cmp_lt_u32_e64 s[52:53], s90, v211
	v_cmp_lt_u32_e64 s[54:55], s91, v211
	v_cmp_lt_u32_e64 s[56:57], s76, v211
	s_waitcnt vmcnt(5)
	v_mfma_f32_32x32x16_bf16 v[66:81], v[138:141], v[118:121], v[66:81]
	v_add_u32_e32 v119, 0x3328, v212
	v_add_u32_e32 v121, 0x3340, v212
	v_cmp_lt_u32_e64 s[58:59], s80, v211
	v_cmp_lt_u32_e64 s[60:61], s81, v211
	v_cmp_lt_u32_e64 s[62:63], s27, v211
	v_cmp_lt_u32_e64 s[64:65], s78, v211
	v_add_u32_e32 v127, 0x3368, v212
	s_waitcnt vmcnt(4)
	v_mfma_f32_32x32x16_bf16 v[66:81], v[142:145], v[122:125], v[66:81]
	v_add_u32_e32 v123, 0x3348, v212
	v_add_u32_e32 v125, 0x3360, v212
	v_cmp_lt_u32_e64 s[66:67], s77, v211
	v_cmp_lt_u32_e64 s[68:69], s36, v211
	s_waitcnt lgkmcnt(0)
	s_nop 6
	v_add_f32_e32 v66, v66, v82
	v_cndmask_b32_e32 v82, v66, v230, vcc
	v_add_f32_e32 v66, v67, v83
	v_cndmask_b32_e64 v83, v66, v230, s[40:41]
	ds_read2_b32 v[240:241], v115 offset1:1
	ds_read2_b32 v[242:243], v117 offset1:1
	ds_read2_b32 v[244:245], v119 offset1:1
	ds_read2_b32 v[246:247], v121 offset1:1
	ds_read2_b32 v[248:249], v123 offset1:1
	ds_read2_b32 v[250:251], v125 offset1:1
	ds_read2_b32 v[252:253], v127 offset1:1
	v_max3_f32 v84, v82, s79, v83
	s_waitcnt lgkmcnt(0)
	v_add_f32_e32 v66, v68, v240
	v_cndmask_b32_e64 v68, v66, v230, s[42:43]
	v_add_f32_e32 v66, v69, v241
	v_cndmask_b32_e64 v69, v66, v230, s[44:45]
	v_max3_f32 v84, v84, v68, v69
	s_waitcnt lgkmcnt(0)
	v_add_f32_e32 v66, v70, v242
	v_cndmask_b32_e64 v70, v66, v230, s[46:47]
	v_add_f32_e32 v66, v71, v243
	v_cndmask_b32_e64 v71, v66, v230, s[48:49]
	v_max3_f32 v84, v84, v70, v71
	s_waitcnt lgkmcnt(0)
	v_add_f32_e32 v66, v72, v244
	v_cndmask_b32_e64 v72, v66, v230, s[50:51]
	v_add_f32_e32 v66, v73, v245
	v_cndmask_b32_e64 v73, v66, v230, s[52:53]
	v_max3_f32 v84, v84, v72, v73
	s_waitcnt lgkmcnt(0)
	v_add_f32_e32 v66, v74, v246
	v_cndmask_b32_e64 v74, v66, v230, s[54:55]
	v_add_f32_e32 v66, v75, v247
	v_cndmask_b32_e64 v75, v66, v230, s[56:57]
	v_max3_f32 v84, v84, v74, v75
	s_waitcnt lgkmcnt(0)
	v_add_f32_e32 v66, v76, v248
	v_cndmask_b32_e64 v76, v66, v230, s[58:59]
	v_add_f32_e32 v66, v77, v249
	v_cndmask_b32_e64 v77, v66, v230, s[60:61]
	v_max3_f32 v84, v84, v76, v77
	s_waitcnt lgkmcnt(0)
	v_add_f32_e32 v66, v78, v250
	v_cndmask_b32_e64 v78, v66, v230, s[62:63]
	v_add_f32_e32 v66, v79, v251
	v_cndmask_b32_e64 v79, v66, v230, s[64:65]
	v_max3_f32 v84, v84, v78, v79
	s_waitcnt lgkmcnt(0)
	v_add_f32_e32 v66, v80, v252
	v_add_f32_e32 v67, v81, v253
	v_cndmask_b32_e64 v66, v66, v230, s[66:67]
	v_cndmask_b32_e64 v67, v67, v230, s[68:69]
	v_max3_f32 v80, v84, v66, v67
	ds_bpermute_b32 v81, v208, v80
	s_waitcnt lgkmcnt(0)
; #define LAS __attribute__((address_space(3)))
; #define MFMA32(a, b, c) __builtin_amdgcn_mfma_f32_32x32x16_bf16((a), (b), (c), 0, 0, 0)
; template <int DELTA> ...
;     ...
;             for (int d0 = 0; d0 < 4; ++d0) s[kvh] = MFMA32(kf[kvh][d0], qf[qh][d0], s[kvh]);
; #pragma unroll
;             for (int rr = 0; rr < 16; ++rr) { const int c4 = 4 * ((rr & 3) + 8 * (rr >> 2)); const float bias = *(const LAS float*)(wl + bvar + (VT_B + c4 + toff * 4));
;                 float v = s[kvh][rr] + bias;
;                 if (toff == 64) v = (bvar <= btb - c4) ? v : -1e30f;
;                 if (toff == -64) v = (bvar >= btb - c4) ? v : -1e30f;
;                 s[kvh][rr] = v; mx = fmaxf(mx, v); }
;         }
;         mx = fmaxf(mx, __shfl_xor(mx, 32));
;         const float m_new = fmaxf(m_run[qh], mx); const float alpha = __builtin_amdgcn_exp2f(m_run[qh] - m_new); m_run[qh] = m_new;
;         float ls = 0.f;
; #pragma unroll
;         for (int kvh = 0; kvh < 2; ++kvh) { const int toff = 64 * DELTA + 32 * (kvh - qh);
;             if (toff > 64 || toff < -64) continue;
; #pragma unroll
;             for (int rr = 0; rr < 16; ++rr) { const float e = __builtin_amdgcn_exp2f(s[kvh][rr] - m_new); s[kvh][rr] = e; ls += e; }
;             pb[qh][2 * kvh] = packp(s[kvh], 0); pb[qh][2 * kvh + 1] = packp(s[kvh], 8); }
;         l_run[qh] = l_run[qh] * alpha + ls;
; #pragma unroll
;         for (int i = 0; i < 16; ++i) { o[qh][0][i] *= alpha; o[qh][1][i] *= alpha; }
	v_max3_f32 v233, v170, v80, v81
	v_sub_f32_e32 v68, v68, v233
	v_exp_f32_e32 v118, v68
	v_sub_f32_e32 v68, v69, v233
	v_exp_f32_e32 v120, v68
	v_sub_f32_e32 v68, v70, v233
	v_exp_f32_e32 v122, v68
	v_sub_f32_e32 v68, v71, v233
	v_exp_f32_e32 v126, v68
	v_sub_f32_e32 v68, v72, v233
	v_exp_f32_e32 v124, v68
	v_sub_f32_e32 v68, v73, v233
	v_exp_f32_e32 v128, v68
	v_sub_f32_e32 v68, v74, v233
	v_exp_f32_e32 v158, v68
	v_sub_f32_e32 v68, v75, v233
	v_exp_f32_e32 v160, v68
	v_sub_f32_e32 v68, v76, v233
	v_exp_f32_e32 v162, v68
	v_sub_f32_e32 v68, v77, v233
	v_sub_f32_e32 v81, v82, v233
	v_exp_f32_e32 v164, v68
	v_sub_f32_e32 v68, v78, v233
	v_sub_f32_e32 v66, v66, v233
	v_sub_f32_e32 v80, v170, v233
	v_exp_f32_e32 v114, v81
	v_sub_f32_e32 v81, v83, v233
	v_exp_f32_e32 v166, v68
	v_sub_f32_e32 v68, v79, v233
	v_exp_f32_e32 v170, v66
	v_sub_f32_e32 v66, v67, v233
	v_exp_f32_e32 v116, v81
	v_exp_f32_e32 v168, v68
	v_exp_f32_e32 v172, v66
	v_exp_f32_e32 v174, v80
	v_mfma_f32_32x32x16_bf16 v[66:81], v[150:153], v[110:113], 0
	v_cvt_pk_bf16_f32 v86, v114, v116
	v_cvt_pk_bf16_f32 v87, v118, v120
	v_cvt_pk_bf16_f32 v88, v122, v126
	v_cvt_pk_bf16_f32 v89, v124, v128
	v_cvt_pk_bf16_f32 v82, v158, v160
	v_cvt_pk_bf16_f32 v83, v162, v164
	v_cvt_pk_bf16_f32 v84, v166, v168
	v_mfma_f32_32x32x16_bf16 v[66:81], v[146:149], v[106:109], v[66:81]
	v_cvt_pk_bf16_f32 v85, v170, v172
	v_mul_f32_e64 v64, v64, v174
	v_mul_f32_e64 v65, v65, v174
	v_mul_f32_e64 v62, v62, v174
	v_mul_f32_e64 v63, v63, v174
	v_mul_f32_e64 v60, v60, v174
	v_mul_f32_e64 v61, v61, v174
	v_pk_mul_f32 v[58:59], v[58:59], v[174:175] op_sel_hi:[1,0]
	v_pk_mul_f32 v[56:57], v[56:57], v[174:175] op_sel_hi:[1,0]
	v_pk_mul_f32 v[54:55], v[54:55], v[174:175] op_sel_hi:[1,0]
	v_mfma_f32_32x32x16_bf16 v[66:81], v[138:141], v[98:101], v[66:81]
	ds_read2_b32 v[138:139], v213 offset1:1
	v_mul_f32_e64 v52, v52, v174
	v_mul_f32_e64 v53, v53, v174
	v_mul_f32_e64 v50, v50, v174
	v_mul_f32_e64 v51, v51, v174
	v_pk_mul_f32 v[48:49], v[48:49], v[174:175] op_sel_hi:[1,0]
	v_pk_mul_f32 v[46:47], v[46:47], v[174:175] op_sel_hi:[1,0]
	v_pk_mul_f32 v[44:45], v[44:45], v[174:175] op_sel_hi:[1,0]
	v_pk_mul_f32 v[42:43], v[42:43], v[174:175] op_sel_hi:[1,0]
	v_mfma_f32_32x32x16_bf16 v[66:81], v[142:145], v[102:105], v[66:81]
	v_mul_f32_e64 v40, v40, v174
	v_mul_f32_e64 v41, v41, v174
	v_mul_f32_e64 v38, v38, v174
	v_mul_f32_e64 v39, v39, v174
	v_mul_f32_e64 v36, v36, v174
	v_mul_f32_e64 v37, v37, v174
	v_pk_mul_f32 v[34:35], v[34:35], v[174:175] op_sel_hi:[1,0]
	s_waitcnt lgkmcnt(0)
	s_nop 3
	v_add_f32_e32 v145, v66, v138
	v_add_f32_e32 v142, v67, v139
	ds_read2_b32 v[240:241], v214 offset1:1
	ds_read2_b32 v[242:243], v215 offset1:1
	ds_read2_b32 v[244:245], v216 offset1:1
	ds_read2_b32 v[246:247], v217 offset1:1
	ds_read2_b32 v[248:249], v218 offset1:1
	ds_read2_b32 v[250:251], v219 offset1:1
	ds_read2_b32 v[252:253], v220 offset1:1
	v_max3_f32 v129, v145, s79, v142
	s_waitcnt lgkmcnt(0)
	v_add_f32_e32 v149, v68, v240
	v_add_f32_e32 v146, v69, v241
	v_max3_f32 v68, v129, v149, v146
	s_waitcnt lgkmcnt(0)
	v_add_f32_e32 v151, v70, v242
	v_add_f32_e32 v147, v71, v243
	v_max3_f32 v68, v68, v151, v147
	s_waitcnt lgkmcnt(0)
	v_add_f32_e32 v152, v72, v244
	v_add_f32_e32 v150, v73, v245
	v_max3_f32 v68, v68, v152, v150
	s_waitcnt lgkmcnt(0)
	v_add_f32_e32 v148, v74, v246
	v_add_f32_e32 v144, v75, v247
	v_max3_f32 v68, v68, v148, v144
	s_waitcnt lgkmcnt(0)
	v_add_f32_e32 v143, v76, v248
	v_add_f32_e32 v141, v77, v249
	v_max3_f32 v68, v68, v143, v141
	s_waitcnt lgkmcnt(0)
	v_add_f32_e32 v140, v78, v250
	v_add_f32_e32 v139, v79, v251
	v_max3_f32 v68, v68, v140, v139
	s_waitcnt lgkmcnt(0)
	v_add_f32_e32 v138, v80, v252
	v_add_f32_e32 v129, v81, v253
	v_max3_f32 v153, v68, v138, v129
	s_waitcnt vmcnt(3)
	v_mfma_f32_32x32x16_bf16 v[66:81], v[134:137], v[110:113], 0
	s_waitcnt vmcnt(2)
	v_mfma_f32_32x32x16_bf16 v[66:81], v[130:133], v[106:109], v[66:81]
	s_waitcnt vmcnt(1)
	v_mfma_f32_32x32x16_bf16 v[66:81], v[90:93], v[98:101], v[66:81]
	ds_read2_b32 v[90:91], v0 offset1:1
	s_waitcnt vmcnt(0)
	v_mfma_f32_32x32x16_bf16 v[66:81], v[94:97], v[102:105], v[66:81]
	s_waitcnt lgkmcnt(0)
	s_nop 10
	v_add_f32_e32 v0, v66, v90
	v_add_f32_e32 v66, v67, v91
	v_cndmask_b32_e64 v90, v66, v230, s[40:41]
	ds_read2_b32 v[240:241], v115 offset1:1
	ds_read2_b32 v[242:243], v117 offset1:1
	ds_read2_b32 v[244:245], v119 offset1:1
	ds_read2_b32 v[246:247], v121 offset1:1
	ds_read2_b32 v[248:249], v123 offset1:1
	ds_read2_b32 v[250:251], v125 offset1:1
	ds_read2_b32 v[252:253], v127 offset1:1
	v_cndmask_b32_e32 v0, v0, v230, vcc
	s_waitcnt lgkmcnt(0)
	v_add_f32_e32 v66, v68, v240
	v_cndmask_b32_e64 v68, v66, v230, s[42:43]
	v_add_f32_e32 v66, v69, v241
	v_cndmask_b32_e64 v69, v66, v230, s[44:45]
	s_waitcnt lgkmcnt(0)
	v_add_f32_e32 v66, v70, v242
	v_cndmask_b32_e64 v70, v66, v230, s[46:47]
	v_add_f32_e32 v66, v71, v243
	v_cndmask_b32_e64 v71, v66, v230, s[48:49]
	s_waitcnt lgkmcnt(0)
	v_add_f32_e32 v66, v72, v244
	v_cndmask_b32_e64 v72, v66, v230, s[50:51]
	v_add_f32_e32 v66, v73, v245
	v_cndmask_b32_e64 v73, v66, v230, s[52:53]
	s_waitcnt lgkmcnt(0)
	v_add_f32_e32 v66, v74, v246
	v_cndmask_b32_e64 v92, v66, v230, s[54:55]
	v_add_f32_e32 v66, v75, v247
	v_cndmask_b32_e64 v93, v66, v230, s[56:57]
	v_max3_f32 v74, v153, v0, v90
	v_max3_f32 v74, v74, v68, v69
	v_max3_f32 v74, v74, v70, v71
	v_max3_f32 v74, v74, v72, v73
	s_waitcnt lgkmcnt(0)
	v_add_f32_e32 v66, v76, v248
	v_cndmask_b32_e64 v94, v66, v230, s[58:59]
	v_add_f32_e32 v66, v77, v249
	v_cndmask_b32_e64 v95, v66, v230, s[60:61]
	v_max3_f32 v74, v74, v92, v93
	v_max3_f32 v74, v74, v94, v95
	s_waitcnt lgkmcnt(0)
; #define LAS __attribute__((address_space(3)))
; #define LDS_WAIT() asm volatile("s_waitcnt lgkmcnt(0)" ::: "memory")
; __device__ __forceinline__ s16x4 vtr(const LAS unsigned char* p) { return __builtin_bit_cast(s16x4, __builtin_amdgcn_ds_read_tr16_b64_v4i16((LAS v4i16_t*)p)); }
; __device__ __forceinline__ bf16x8 cat8(s16x4 a, s16x4 b) { return (bf16x8){a[0], a[1], a[2], a[3], b[0], b[1], b[2], b[3]}; }
; #define MFMA32(a, b, c) __builtin_amdgcn_mfma_f32_32x32x16_bf16((a), (b), (c), 0, 0, 0)
; template <int DELTA> ...
;     ...
;         mx = fmaxf(mx, __shfl_xor(mx, 32));
;         const float m_new = fmaxf(m_run[qh], mx); const float alpha = __builtin_amdgcn_exp2f(m_run[qh] - m_new); m_run[qh] = m_new;
;         float ls = 0.f;
; #pragma unroll
;         for (int kvh = 0; kvh < 2; ++kvh) { const int toff = 64 * DELTA + 32 * (kvh - qh);
;             if (toff > 64 || toff < -64) continue;
; #pragma unroll
;             for (int rr = 0; rr < 16; ++rr) { const float e = __builtin_amdgcn_exp2f(s[kvh][rr] - m_new); s[kvh][rr] = e; ls += e; }
;             pb[qh][2 * kvh] = packp(s[kvh], 0); pb[qh][2 * kvh + 1] = packp(s[kvh], 8); }
;         l_run[qh] = l_run[qh] * alpha + ls;
; #pragma unroll
;         for (int i = 0; i < 16; ++i) { o[qh][0][i] *= alpha; o[qh][1][i] *= alpha; }
;     }
;     LDS_WAIT();
; #pragma unroll
;     for (int j = 0; j < 4; ++j) { const LAS unsigned char* vj = wl + voff + 16 * j * VP;
;         const bf16x8 a0 = cat8(vtr(vj), vtr(vj + 8 * VP)); const bf16x8 a1 = cat8(vtr(vj + 64), vtr(vj + 8 * VP + 64));
; #pragma unroll
;         for (int qh = 0; qh < 2; ++qh) { const int toff = 64 * DELTA + 32 * ((j >> 1) - qh);
;             if (toff > 64 || toff < -64) continue;
;             o[qh][0] = MFMA32(a0, pb[qh][j], o[qh][0]); o[qh][1] = MFMA32(a1, pb[qh][j], o[qh][1]); } }
	v_add_f32_e32 v66, v78, v250
	v_cndmask_b32_e64 v96, v66, v230, s[62:63]
	v_add_f32_e32 v66, v79, v251
	v_cndmask_b32_e64 v97, v66, v230, s[64:65]
	v_max3_f32 v74, v74, v96, v97
	s_waitcnt lgkmcnt(0)
	v_add_f32_e32 v66, v80, v252
	v_add_f32_e32 v67, v81, v253
	v_cndmask_b32_e64 v66, v66, v230, s[66:67]
	v_cndmask_b32_e64 v67, v67, v230, s[68:69]
	v_max3_f32 v74, v74, v66, v67
	ds_bpermute_b32 v75, v208, v74
	s_waitcnt lgkmcnt(0)
	v_max3_f32 v130, v223, v74, v75
	v_sub_f32_e32 v74, v145, v130
	v_exp_f32_e32 v74, v74
	v_sub_f32_e32 v76, v142, v130
	v_exp_f32_e32 v76, v76
	v_sub_f32_e32 v77, v149, v130
	v_exp_f32_e32 v77, v77
	v_sub_f32_e32 v78, v146, v130
	v_exp_f32_e32 v79, v78
	v_sub_f32_e32 v78, v151, v130
	v_add_f32_e32 v75, 0, v74
	v_exp_f32_e32 v80, v78
	v_sub_f32_e32 v78, v147, v130
	v_add_f32_e32 v75, v76, v75
	v_exp_f32_e32 v81, v78
	v_sub_f32_e32 v78, v152, v130
	v_add_f32_e32 v75, v77, v75
	v_exp_f32_e32 v99, v78
	v_sub_f32_e32 v78, v150, v130
	v_add_f32_e32 v75, v79, v75
	v_exp_f32_e32 v100, v78
	v_sub_f32_e32 v78, v148, v130
	v_add_f32_e32 v75, v80, v75
	v_exp_f32_e32 v101, v78
	v_sub_f32_e32 v78, v144, v130
	v_add_f32_e32 v75, v81, v75
	v_exp_f32_e32 v102, v78
	v_sub_f32_e32 v78, v143, v130
	v_add_f32_e32 v75, v99, v75
	v_exp_f32_e32 v103, v78
	v_sub_f32_e32 v78, v141, v130
	v_add_f32_e32 v75, v100, v75
	v_exp_f32_e32 v104, v78
	v_sub_f32_e32 v78, v140, v130
	v_add_f32_e32 v75, v101, v75
	v_exp_f32_e32 v105, v78
	v_sub_f32_e32 v78, v139, v130
	v_add_f32_e32 v75, v102, v75
	v_exp_f32_e32 v106, v78
	v_sub_f32_e32 v78, v138, v130
	v_add_f32_e32 v75, v103, v75
	v_exp_f32_e32 v107, v78
	v_sub_f32_e32 v78, v129, v130
	v_add_f32_e32 v75, v104, v75
	v_exp_f32_e32 v108, v78
	v_sub_f32_e32 v0, v0, v130
	v_add_f32_e32 v75, v105, v75
	v_exp_f32_e32 v115, v0
	v_sub_f32_e32 v0, v90, v130
	v_add_f32_e32 v75, v106, v75
	v_exp_f32_e32 v117, v0
	v_sub_f32_e32 v0, v68, v130
	v_add_f32_e32 v75, v107, v75
	v_exp_f32_e32 v119, v0
	v_sub_f32_e32 v0, v69, v130
	v_add_f32_e32 v91, v108, v75
	v_exp_f32_e32 v121, v0
	v_sub_f32_e32 v0, v70, v130
	v_mov_b32_e32 v90, v1
	v_exp_f32_e32 v123, v0
	v_sub_f32_e32 v0, v71, v130
	v_pk_add_f32 v[90:91], v[114:115], v[90:91]
	v_exp_f32_e32 v127, v0
	v_sub_f32_e32 v0, v72, v130
	v_pk_add_f32 v[90:91], v[116:117], v[90:91]
	v_exp_f32_e32 v125, v0
	v_sub_f32_e32 v0, v73, v130
	v_pk_add_f32 v[90:91], v[118:119], v[90:91]
	v_exp_f32_e32 v129, v0
	v_sub_f32_e32 v0, v92, v130
	v_pk_add_f32 v[90:91], v[120:121], v[90:91]
	v_exp_f32_e32 v159, v0
	v_sub_f32_e32 v0, v93, v130
	v_pk_add_f32 v[90:91], v[122:123], v[90:91]
	v_exp_f32_e32 v161, v0
	v_sub_f32_e32 v0, v94, v130
	v_pk_add_f32 v[90:91], v[126:127], v[90:91]
	v_exp_f32_e32 v163, v0
	v_sub_f32_e32 v0, v95, v130
	v_pk_add_f32 v[90:91], v[124:125], v[90:91]
	v_exp_f32_e32 v165, v0
	v_sub_f32_e32 v0, v96, v130
	v_pk_add_f32 v[90:91], v[128:129], v[90:91]
	v_exp_f32_e32 v167, v0
	v_sub_f32_e32 v0, v97, v130
	v_pk_add_f32 v[90:91], v[158:159], v[90:91]
	v_exp_f32_e32 v169, v0
	v_sub_f32_e32 v0, v66, v130
	v_pk_add_f32 v[90:91], v[160:161], v[90:91]
	v_exp_f32_e32 v171, v0
	v_sub_f32_e32 v0, v67, v130
	v_pk_add_f32 v[90:91], v[162:163], v[90:91]
	v_sub_f32_e32 v98, v223, v130
	v_exp_f32_e32 v173, v0
	v_pk_add_f32 v[90:91], v[164:165], v[90:91]
	v_exp_f32_e32 v175, v98
	v_pk_add_f32 v[90:91], v[166:167], v[90:91]
	v_cvt_pk_bf16_f32 v78, v74, v76
	v_cvt_pk_bf16_f32 v79, v77, v79
	v_cvt_pk_bf16_f32 v80, v80, v81
	v_cvt_pk_bf16_f32 v81, v99, v100
	v_cvt_pk_bf16_f32 v74, v101, v102
	s_nop 0
	v_pk_add_f32 v[90:91], v[168:169], v[90:91]
	v_cvt_pk_bf16_f32 v75, v103, v104
	v_cvt_pk_bf16_f32 v76, v105, v106
	v_cvt_pk_bf16_f32 v77, v107, v108
	v_cvt_pk_bf16_f32 v70, v115, v117
	v_cvt_pk_bf16_f32 v71, v119, v121
	s_nop 0
	v_pk_add_f32 v[90:91], v[170:171], v[90:91]
	v_cvt_pk_bf16_f32 v72, v123, v127
	v_cvt_pk_bf16_f32 v73, v125, v129
	v_cvt_pk_bf16_f32 v66, v159, v161
	v_cvt_pk_bf16_f32 v67, v163, v165
	v_cvt_pk_bf16_f32 v68, v167, v169
	v_cvt_pk_bf16_f32 v69, v171, v173
	s_nop 0
	v_pk_add_f32 v[90:91], v[172:173], v[90:91]
	s_waitcnt lgkmcnt(0)
	v_mov_b32_e32 v0, v175
	v_pk_fma_f32 v[154:155], v[154:155], v[174:175], v[90:91]
	ds_read_b64_tr_b16 v[90:91], v222
	ds_read_b64_tr_b16 v[92:93], v222 offset:1536
	ds_read_b64_tr_b16 v[94:95], v222 offset:64
	ds_read_b64_tr_b16 v[96:97], v222 offset:1600
	v_pk_mul_f32 v[32:33], v[32:33], v[0:1] op_sel_hi:[1,0]
	v_pk_mul_f32 v[30:31], v[30:31], v[0:1] op_sel_hi:[1,0]
	v_pk_mul_f32 v[28:29], v[28:29], v[0:1] op_sel_hi:[1,0]
	v_pk_mul_f32 v[26:27], v[26:27], v[0:1] op_sel_hi:[1,0]
	v_pk_mul_f32 v[24:25], v[24:25], v[0:1] op_sel_hi:[1,0]
	v_pk_mul_f32 v[22:23], v[22:23], v[0:1] op_sel_hi:[1,0]
	v_pk_mul_f32 v[20:21], v[20:21], v[0:1] op_sel_hi:[1,0]
	v_pk_mul_f32 v[18:19], v[18:19], v[0:1] op_sel_hi:[1,0]
	v_pk_mul_f32 v[16:17], v[16:17], v[0:1] op_sel_hi:[1,0]
	v_pk_mul_f32 v[14:15], v[14:15], v[0:1] op_sel_hi:[1,0]
	v_pk_mul_f32 v[12:13], v[12:13], v[0:1] op_sel_hi:[1,0]
	v_pk_mul_f32 v[10:11], v[10:11], v[0:1] op_sel_hi:[1,0]
	v_pk_mul_f32 v[8:9], v[8:9], v[0:1] op_sel_hi:[1,0]
	v_pk_mul_f32 v[6:7], v[6:7], v[0:1] op_sel_hi:[1,0]
	v_pk_mul_f32 v[4:5], v[4:5], v[0:1] op_sel_hi:[1,0]
	v_pk_mul_f32 v[2:3], v[2:3], v[0:1] op_sel_hi:[1,0]
	s_waitcnt lgkmcnt(2)
	v_mfma_f32_32x32x16_bf16 v[18:33], v[90:93], v[78:81], v[18:33]
	s_waitcnt lgkmcnt(0)
	v_mfma_f32_32x32x16_bf16 v[2:17], v[94:97], v[78:81], v[2:17]
	v_mfma_f32_32x32x16_bf16 v[50:65], v[90:93], v[86:89], v[50:65]
	v_mfma_f32_32x32x16_bf16 v[34:49], v[94:97], v[86:89], v[34:49]
	ds_read_b64_tr_b16 v[78:79], v222 offset:3072
	ds_read_b64_tr_b16 v[80:81], v222 offset:4608
	ds_read_b64_tr_b16 v[86:87], v222 offset:3136
	ds_read_b64_tr_b16 v[88:89], v222 offset:4672
	s_waitcnt lgkmcnt(2)
	v_mfma_f32_32x32x16_bf16 v[18:33], v[78:81], v[74:77], v[18:33]
	s_waitcnt lgkmcnt(0)
	v_mfma_f32_32x32x16_bf16 v[2:17], v[86:89], v[74:77], v[2:17]
	v_mfma_f32_32x32x16_bf16 v[50:65], v[78:81], v[82:85], v[50:65]
	ds_read_b64_tr_b16 v[74:75], v222 offset:6144
	ds_read_b64_tr_b16 v[76:77], v222 offset:7680
	ds_read_b64_tr_b16 v[78:79], v222 offset:6208
	ds_read_b64_tr_b16 v[80:81], v222 offset:7744
	s_waitcnt lgkmcnt(2)
	v_mfma_f32_32x32x16_bf16 v[18:33], v[74:77], v[70:73], v[18:33]
	s_waitcnt lgkmcnt(0)
	v_mfma_f32_32x32x16_bf16 v[2:17], v[78:81], v[70:73], v[2:17]
	ds_read_b64_tr_b16 v[70:71], v222 offset:9216
	ds_read_b64_tr_b16 v[72:73], v222 offset:10752
	ds_read_b64_tr_b16 v[74:75], v222 offset:9280
	ds_read_b64_tr_b16 v[76:77], v222 offset:10816
	s_waitcnt lgkmcnt(0)
	v_mfma_f32_32x32x16_bf16 v[34:49], v[86:89], v[82:85], v[34:49]
	s_waitcnt lgkmcnt(2)
	v_mfma_f32_32x32x16_bf16 v[18:33], v[70:73], v[66:69], v[18:33]
	s_waitcnt lgkmcnt(0)
	v_mfma_f32_32x32x16_bf16 v[2:17], v[74:77], v[66:69], v[2:17]

; #define LAS __attribute__((address_space(3)))
; #define MFMA32(a, b, c) __builtin_amdgcn_mfma_f32_32x32x16_bf16((a), (b), (c), 0, 0, 0)
; #define SBAR0() __builtin_amdgcn_sched_barrier(0)
; template <int DELTA> ...
;     u32x4 vv[8]; bf16x8 kf[2][4];
; #pragma unroll
;     for (int i = 0; i < 8; ++i) { const int idx = lane + 64 * i, row = idx >> 3, ch = idx & 7; vv[i] = *(const u32x4*)(vbase + (size_t)row * rstride + ch * 8); }
; #pragma unroll
;     for (int kvh = 0; kvh < 2; ++kvh)
; #pragma unroll
;         for (int d0 = 0; d0 < 4; ++d0) kf[kvh][d0] = *(const bf16x8*)(kbase + (size_t)(32 * kvh + r32) * rstride + d0 * 16);
;     SBAR0();
; #pragma unroll
;     for (int i = 0; i < 8; ++i) { const int idx = lane + 64 * i, row = idx >> 3, ch = idx & 7; *(LAS u32x4*)(wl + row * VP + ch * 16) = vv[i]; }
;     bf16x8 pb[2][4];
; #pragma unroll
;     for (int qh = 0; qh < 2; ++qh) {
;         f32x16 s[2]; float mx = -1e30f;
; #pragma unroll
;         for (int kvh = 0; kvh < 2; ++kvh) {
;             constexpr int dummy = 0; (void)dummy;
;             const int toff = 64 * DELTA + 32 * (kvh - qh);
;             if (toff > 64 || toff < -64) continue;
; #pragma unroll
;             for (int i = 0; i < 16; ++i) s[kvh][i] = 0.f;
; #pragma unroll
;             for (int d0 = 0; d0 < 4; ++d0) s[kvh] = MFMA32(kf[kvh][d0], qf[qh][d0], s[kvh]);
; #pragma unroll
;             for (int rr = 0; rr < 16; ++rr) { const int c4 = 4 * ((rr & 3) + 8 * (rr >> 2)); const float bias = *(const LAS float*)(wl + bvar + (VT_B + c4 + toff * 4));
;                 float v = s[kvh][rr] + bias;
;                 if (toff == 64) v = (bvar <= btb - c4) ? v : -1e30f;
;                 if (toff == -64) v = (bvar >= btb - c4) ? v : -1e30f;
;                 s[kvh][rr] = v; mx = fmaxf(mx, v); }
.LBB0_461:
	v_mov_b32_e32 v157, v1
	v_lshl_add_u64 v[66:67], s[72:73], 0, v[156:157]
	s_mov_b64 s[40:41], 0x4020000
	v_mov_b32_e32 v147, v1
	v_lshl_add_u64 v[90:91], v[66:67], 0, s[40:41]
	v_lshl_add_u64 v[66:67], s[72:73], 0, v[146:147]
	s_mov_b64 s[40:41], 0x8020000
	v_lshl_add_u64 v[92:93], v[66:67], 0, s[40:41]
	v_mov_b32_e32 v169, v1
	v_mov_b32_e32 v167, v1
	v_mov_b32_e32 v165, v1
	v_mov_b32_e32 v163, v1
	v_mov_b32_e32 v161, v1
	v_mov_b32_e32 v159, v1
	v_mov_b32_e32 v153, v1
	v_mov_b32_e32 v151, v1
	v_lshl_add_u64 v[66:67], v[92:93], 0, v[168:169]
	v_lshl_add_u64 v[70:71], v[92:93], 0, v[166:167]
	v_lshl_add_u64 v[74:75], v[92:93], 0, v[164:165]
	v_lshl_add_u64 v[78:79], v[92:93], 0, v[162:163]
	v_lshl_add_u64 v[82:83], v[92:93], 0, v[160:161]
	v_lshl_add_u64 v[86:87], v[92:93], 0, v[158:159]
	v_lshl_add_u64 v[94:95], v[92:93], 0, v[152:153]
	v_lshl_add_u64 v[92:93], v[92:93], 0, v[150:151]
	v_mov_b32_e32 v149, v1
	global_load_dwordx4 v[66:69], v[66:67], off
	s_nop 0
	global_load_dwordx4 v[70:73], v[70:71], off
	s_nop 0
	global_load_dwordx4 v[74:77], v[74:75], off
	s_nop 0
	global_load_dwordx4 v[78:81], v[78:79], off
	s_nop 0
	global_load_dwordx4 v[82:85], v[82:83], off
	s_nop 0
	global_load_dwordx4 v[86:89], v[86:87], off
	s_nop 0
	global_load_dwordx4 v[158:161], v[94:95], off
	global_load_dwordx4 v[162:165], v[92:93], off
	v_lshl_add_u64 v[92:93], v[90:91], 0, v[148:149]
	v_lshl_add_u64 v[94:95], v[90:91], 0, v[0:1]
	global_load_dwordx4 v[150:153], v[92:93], off
	global_load_dwordx4 v[146:149], v[92:93], off offset:32
	global_load_dwordx4 v[138:141], v[92:93], off offset:64
	global_load_dwordx4 v[142:145], v[92:93], off offset:96
	global_load_dwordx4 v[134:137], v[94:95], off
	global_load_dwordx4 v[130:133], v[94:95], off offset:32
	s_nop 0
	global_load_dwordx4 v[90:93], v[94:95], off offset:64
	s_nop 0
	global_load_dwordx4 v[94:97], v[94:95], off offset:96
	s_waitcnt vmcnt(15)
	ds_write_b128 v234, v[66:69]
	s_waitcnt vmcnt(14)
	ds_write_b128 v234, v[70:73] offset:1536
	s_waitcnt vmcnt(13)
	ds_write_b128 v234, v[74:77] offset:3072
	s_waitcnt vmcnt(12)
	ds_write_b128 v234, v[78:81] offset:4608
	s_waitcnt vmcnt(11)
	ds_write_b128 v234, v[82:85] offset:6144
	s_waitcnt vmcnt(10)
	ds_write_b128 v234, v[86:89] offset:7680
	s_waitcnt vmcnt(9)
	ds_write_b128 v234, v[158:161] offset:9216
	s_waitcnt vmcnt(8)
	ds_write_b128 v234, v[162:165] offset:10752
	s_waitcnt vmcnt(7)
	v_mfma_f32_32x32x16_bf16 v[66:81], v[150:153], v[126:129], 0
	v_add_u32_e32 v0, 0x3300, v216
	ds_read2_b32 v[82:83], v0 offset1:1
	v_cmp_lt_u32_e32 vcc, s84, v211
	v_cmp_lt_u32_e64 s[40:41], s74, v211
	v_cmp_lt_u32_e64 s[42:43], s24, v211
	v_cmp_lt_u32_e64 s[44:45], s25, v211
	v_cmp_lt_u32_e64 s[46:47], s26, v211
	s_waitcnt vmcnt(6)
	v_mfma_f32_32x32x16_bf16 v[66:81], v[146:149], v[114:117], v[66:81]
	v_add_u32_e32 v114, 0x3308, v216
	v_add_u32_e32 v116, 0x3320, v216
	v_cmp_lt_u32_e64 s[48:49], s20, v211
	v_cmp_lt_u32_e64 s[50:51], s28, v211
	v_cmp_lt_u32_e64 s[52:53], s90, v211
	v_cmp_lt_u32_e64 s[54:55], s91, v211
	v_cmp_lt_u32_e64 s[56:57], s76, v211
	s_waitcnt vmcnt(5)
	v_mfma_f32_32x32x16_bf16 v[66:81], v[138:141], v[118:121], v[66:81]
	v_add_u32_e32 v118, 0x3328, v216
	v_add_u32_e32 v120, 0x3340, v216
	v_cmp_lt_u32_e64 s[58:59], s80, v211
	v_cmp_lt_u32_e64 s[60:61], s81, v211
	v_cmp_lt_u32_e64 s[62:63], s27, v211
	v_cmp_lt_u32_e64 s[64:65], s78, v211
	v_add_u32_e32 v126, 0x3368, v216
	s_waitcnt vmcnt(4)
	v_mfma_f32_32x32x16_bf16 v[66:81], v[142:145], v[122:125], v[66:81]
	v_add_u32_e32 v122, 0x3348, v216
	v_add_u32_e32 v124, 0x3360, v216
	v_cmp_lt_u32_e64 s[66:67], s77, v211
	v_cmp_lt_u32_e64 s[68:69], s36, v211
	s_waitcnt lgkmcnt(0)
	s_nop 6
	v_add_f32_e32 v66, v66, v82
	v_cndmask_b32_e32 v82, v66, v230, vcc
	v_add_f32_e32 v66, v67, v83
	v_cndmask_b32_e64 v83, v66, v230, s[40:41]
	ds_read2_b32 v[240:241], v114 offset1:1
	ds_read2_b32 v[242:243], v116 offset1:1
	ds_read2_b32 v[244:245], v118 offset1:1
	ds_read2_b32 v[246:247], v120 offset1:1
	ds_read2_b32 v[248:249], v122 offset1:1
	ds_read2_b32 v[250:251], v124 offset1:1
	ds_read2_b32 v[252:253], v126 offset1:1
	v_max3_f32 v84, v82, s79, v83
	s_waitcnt lgkmcnt(0)
	v_add_f32_e32 v66, v68, v240
	v_cndmask_b32_e64 v68, v66, v230, s[42:43]
	v_add_f32_e32 v66, v69, v241
	v_cndmask_b32_e64 v69, v66, v230, s[44:45]
	v_max3_f32 v84, v84, v68, v69
	s_waitcnt lgkmcnt(0)
	v_add_f32_e32 v66, v70, v242
	v_cndmask_b32_e64 v70, v66, v230, s[46:47]
	v_add_f32_e32 v66, v71, v243
	v_cndmask_b32_e64 v71, v66, v230, s[48:49]
	v_max3_f32 v84, v84, v70, v71
	s_waitcnt lgkmcnt(0)
	v_add_f32_e32 v66, v72, v244
	v_cndmask_b32_e64 v72, v66, v230, s[50:51]
	v_add_f32_e32 v66, v73, v245
	v_cndmask_b32_e64 v73, v66, v230, s[52:53]
	v_max3_f32 v84, v84, v72, v73
	s_waitcnt lgkmcnt(0)
	v_add_f32_e32 v66, v74, v246
	v_cndmask_b32_e64 v74, v66, v230, s[54:55]
	v_add_f32_e32 v66, v75, v247
	v_cndmask_b32_e64 v75, v66, v230, s[56:57]
	v_max3_f32 v84, v84, v74, v75
	s_waitcnt lgkmcnt(0)
	v_add_f32_e32 v66, v76, v248
	v_cndmask_b32_e64 v76, v66, v230, s[58:59]
	v_add_f32_e32 v66, v77, v249
	v_cndmask_b32_e64 v77, v66, v230, s[60:61]
	v_max3_f32 v84, v84, v76, v77
	s_waitcnt lgkmcnt(0)
	v_add_f32_e32 v66, v78, v250
	v_cndmask_b32_e64 v78, v66, v230, s[62:63]
	v_add_f32_e32 v66, v79, v251
	v_cndmask_b32_e64 v79, v66, v230, s[64:65]
	v_max3_f32 v84, v84, v78, v79
	s_waitcnt lgkmcnt(0)
	v_add_f32_e32 v66, v80, v252
	v_add_f32_e32 v67, v81, v253
	v_cndmask_b32_e64 v66, v66, v230, s[66:67]
	v_cndmask_b32_e64 v67, v67, v230, s[68:69]
	v_max3_f32 v80, v84, v66, v67
	ds_bpermute_b32 v81, v208, v80
	s_waitcnt lgkmcnt(0)
; #define LAS __attribute__((address_space(3)))
; #define MFMA32(a, b, c) __builtin_amdgcn_mfma_f32_32x32x16_bf16((a), (b), (c), 0, 0, 0)
; template <int DELTA> ...
;     ...
;             for (int d0 = 0; d0 < 4; ++d0) s[kvh] = MFMA32(kf[kvh][d0], qf[qh][d0], s[kvh]);
; #pragma unroll
;             for (int rr = 0; rr < 16; ++rr) { const int c4 = 4 * ((rr & 3) + 8 * (rr >> 2)); const float bias = *(const LAS float*)(wl + bvar + (VT_B + c4 + toff * 4));
;                 float v = s[kvh][rr] + bias;
;                 if (toff == 64) v = (bvar <= btb - c4) ? v : -1e30f;
;                 if (toff == -64) v = (bvar >= btb - c4) ? v : -1e30f;
;                 s[kvh][rr] = v; mx = fmaxf(mx, v); }
;         }
;         mx = fmaxf(mx, __shfl_xor(mx, 32));
;         const float m_new = fmaxf(m_run[qh], mx); const float alpha = __builtin_amdgcn_exp2f(m_run[qh] - m_new); m_run[qh] = m_new;
;         float ls = 0.f;
; #pragma unroll
;         for (int kvh = 0; kvh < 2; ++kvh) { const int toff = 64 * DELTA + 32 * (kvh - qh);
;             if (toff > 64 || toff < -64) continue;
; #pragma unroll
;             for (int rr = 0; rr < 16; ++rr) { const float e = __builtin_amdgcn_exp2f(s[kvh][rr] - m_new); s[kvh][rr] = e; ls += e; }
;             pb[qh][2 * kvh] = packp(s[kvh], 0); pb[qh][2 * kvh + 1] = packp(s[kvh], 8); }
;         l_run[qh] = l_run[qh] * alpha + ls;
; #pragma unroll
;         for (int i = 0; i < 16; ++i) { o[qh][0][i] *= alpha; o[qh][1][i] *= alpha; }
	v_max3_f32 v233, v170, v80, v81
	v_sub_f32_e32 v68, v68, v233
	v_exp_f32_e32 v119, v68
	v_sub_f32_e32 v68, v69, v233
	v_exp_f32_e32 v121, v68
	v_sub_f32_e32 v68, v70, v233
	v_exp_f32_e32 v123, v68
	v_sub_f32_e32 v68, v71, v233
	v_exp_f32_e32 v127, v68
	v_sub_f32_e32 v68, v72, v233
	v_exp_f32_e32 v125, v68
	v_sub_f32_e32 v68, v73, v233
	v_exp_f32_e32 v129, v68
	v_sub_f32_e32 v68, v74, v233
	v_exp_f32_e32 v159, v68
	v_sub_f32_e32 v68, v75, v233
	v_exp_f32_e32 v161, v68
	v_sub_f32_e32 v68, v76, v233
	v_exp_f32_e32 v163, v68
	v_sub_f32_e32 v68, v77, v233
	v_sub_f32_e32 v81, v82, v233
	v_exp_f32_e32 v165, v68
	v_sub_f32_e32 v68, v78, v233
	v_sub_f32_e32 v66, v66, v233
	v_sub_f32_e32 v80, v170, v233
	v_exp_f32_e32 v115, v81
	v_sub_f32_e32 v81, v83, v233
	v_exp_f32_e32 v167, v68
	v_sub_f32_e32 v68, v79, v233
	v_exp_f32_e32 v171, v66
	v_sub_f32_e32 v66, v67, v233
	v_exp_f32_e32 v117, v81
	v_exp_f32_e32 v169, v68
	v_exp_f32_e32 v173, v66
	v_exp_f32_e32 v174, v80
	v_mfma_f32_32x32x16_bf16 v[66:81], v[150:153], v[110:113], 0
	v_cvt_pk_bf16_f32 v86, v115, v117
	v_cvt_pk_bf16_f32 v87, v119, v121
	v_cvt_pk_bf16_f32 v88, v123, v127
	v_cvt_pk_bf16_f32 v89, v125, v129
	v_cvt_pk_bf16_f32 v82, v159, v161
	v_cvt_pk_bf16_f32 v83, v163, v165
	v_cvt_pk_bf16_f32 v84, v167, v169
	v_mfma_f32_32x32x16_bf16 v[66:81], v[146:149], v[106:109], v[66:81]
	v_cvt_pk_bf16_f32 v85, v171, v173
	v_mul_f32_e64 v64, v64, v174
	v_mul_f32_e64 v65, v65, v174
	v_mul_f32_e64 v62, v62, v174
	v_mul_f32_e64 v63, v63, v174
	v_mul_f32_e64 v60, v60, v174
	v_mul_f32_e64 v61, v61, v174
	v_pk_mul_f32 v[58:59], v[58:59], v[174:175] op_sel_hi:[1,0]
	v_pk_mul_f32 v[56:57], v[56:57], v[174:175] op_sel_hi:[1,0]
	v_pk_mul_f32 v[54:55], v[54:55], v[174:175] op_sel_hi:[1,0]
	v_mfma_f32_32x32x16_bf16 v[66:81], v[138:141], v[98:101], v[66:81]
	ds_read2_b32 v[138:139], v212 offset1:1
	v_mul_f32_e64 v52, v52, v174
	v_mul_f32_e64 v53, v53, v174
	v_mul_f32_e64 v50, v50, v174
	v_mul_f32_e64 v51, v51, v174
	v_pk_mul_f32 v[48:49], v[48:49], v[174:175] op_sel_hi:[1,0]
	v_pk_mul_f32 v[46:47], v[46:47], v[174:175] op_sel_hi:[1,0]
	v_pk_mul_f32 v[44:45], v[44:45], v[174:175] op_sel_hi:[1,0]
	v_pk_mul_f32 v[42:43], v[42:43], v[174:175] op_sel_hi:[1,0]
	v_mfma_f32_32x32x16_bf16 v[66:81], v[142:145], v[102:105], v[66:81]
	v_mul_f32_e64 v40, v40, v174
	v_mul_f32_e64 v41, v41, v174
	v_mul_f32_e64 v38, v38, v174
	v_mul_f32_e64 v39, v39, v174
	v_mul_f32_e64 v36, v36, v174
	v_mul_f32_e64 v37, v37, v174
	v_pk_mul_f32 v[34:35], v[34:35], v[174:175] op_sel_hi:[1,0]
	s_waitcnt lgkmcnt(0)
	s_nop 3
	v_add_f32_e32 v145, v66, v138
	v_add_f32_e32 v142, v67, v139
	ds_read2_b32 v[240:241], v213 offset1:1
	ds_read2_b32 v[242:243], v214 offset1:1
	ds_read2_b32 v[244:245], v215 offset1:1
	ds_read2_b32 v[246:247], v217 offset1:1
	ds_read2_b32 v[248:249], v218 offset1:1
	ds_read2_b32 v[250:251], v219 offset1:1
	ds_read2_b32 v[252:253], v220 offset1:1
	v_max3_f32 v128, v145, s79, v142
	s_waitcnt lgkmcnt(0)
	v_add_f32_e32 v149, v68, v240
	v_add_f32_e32 v146, v69, v241
	v_max3_f32 v68, v128, v149, v146
	s_waitcnt lgkmcnt(0)
	v_add_f32_e32 v151, v70, v242
	v_add_f32_e32 v147, v71, v243
	v_max3_f32 v68, v68, v151, v147
	s_waitcnt lgkmcnt(0)
	v_add_f32_e32 v152, v72, v244
	v_add_f32_e32 v150, v73, v245
	v_max3_f32 v68, v68, v152, v150
	s_waitcnt lgkmcnt(0)
	v_add_f32_e32 v148, v74, v246
	v_add_f32_e32 v144, v75, v247
	v_max3_f32 v68, v68, v148, v144
	s_waitcnt lgkmcnt(0)
	v_add_f32_e32 v143, v76, v248
	v_add_f32_e32 v141, v77, v249
	v_max3_f32 v68, v68, v143, v141
	s_waitcnt lgkmcnt(0)
	v_add_f32_e32 v140, v78, v250
	v_add_f32_e32 v139, v79, v251
	v_max3_f32 v68, v68, v140, v139
	s_waitcnt lgkmcnt(0)
	v_add_f32_e32 v138, v80, v252
	v_add_f32_e32 v128, v81, v253
	v_max3_f32 v153, v68, v138, v128
	s_waitcnt vmcnt(3)
	v_mfma_f32_32x32x16_bf16 v[66:81], v[134:137], v[110:113], 0
	s_waitcnt vmcnt(2)
	v_mfma_f32_32x32x16_bf16 v[66:81], v[130:133], v[106:109], v[66:81]
	s_waitcnt vmcnt(1)
	v_mfma_f32_32x32x16_bf16 v[66:81], v[90:93], v[98:101], v[66:81]
	ds_read2_b32 v[90:91], v0 offset1:1
	s_waitcnt vmcnt(0)
	v_mfma_f32_32x32x16_bf16 v[66:81], v[94:97], v[102:105], v[66:81]
	s_waitcnt lgkmcnt(0)
	s_nop 10
	v_add_f32_e32 v0, v66, v90
	v_cndmask_b32_e32 v90, v0, v230, vcc
	v_add_f32_e32 v0, v67, v91
	ds_read2_b32 v[240:241], v114 offset1:1
	ds_read2_b32 v[242:243], v116 offset1:1
	ds_read2_b32 v[244:245], v118 offset1:1
	ds_read2_b32 v[246:247], v120 offset1:1
	ds_read2_b32 v[248:249], v122 offset1:1
	ds_read2_b32 v[250:251], v124 offset1:1
	ds_read2_b32 v[252:253], v126 offset1:1
	v_cndmask_b32_e64 v91, v0, v230, s[40:41]
	s_waitcnt lgkmcnt(0)
	v_add_f32_e32 v0, v68, v240
	v_cndmask_b32_e64 v68, v0, v230, s[42:43]
	v_add_f32_e32 v0, v69, v241
	v_cndmask_b32_e64 v69, v0, v230, s[44:45]
	s_waitcnt lgkmcnt(0)
	v_add_f32_e32 v0, v70, v242
	v_cndmask_b32_e64 v70, v0, v230, s[46:47]
	v_add_f32_e32 v0, v71, v243
	v_cndmask_b32_e64 v71, v0, v230, s[48:49]
	s_waitcnt lgkmcnt(0)
	v_add_f32_e32 v0, v72, v244
	v_cndmask_b32_e64 v72, v0, v230, s[50:51]
	v_add_f32_e32 v0, v73, v245
	v_cndmask_b32_e64 v73, v0, v230, s[52:53]
	s_waitcnt lgkmcnt(0)
	v_add_f32_e32 v0, v74, v246
	v_cndmask_b32_e64 v92, v0, v230, s[54:55]
	v_add_f32_e32 v0, v75, v247
	v_cndmask_b32_e64 v93, v0, v230, s[56:57]
	s_waitcnt lgkmcnt(0)
	v_add_f32_e32 v0, v76, v248
	v_cndmask_b32_e64 v94, v0, v230, s[58:59]
	v_add_f32_e32 v0, v77, v249
	v_cndmask_b32_e64 v95, v0, v230, s[60:61]
	s_waitcnt lgkmcnt(0)
	v_add_f32_e32 v0, v78, v250
	v_cndmask_b32_e64 v96, v0, v230, s[62:63]
	v_add_f32_e32 v0, v79, v251
	v_cndmask_b32_e64 v97, v0, v230, s[64:65]
	s_waitcnt lgkmcnt(0)
; #define LAS __attribute__((address_space(3)))
; #define LDS_WAIT() asm volatile("s_waitcnt lgkmcnt(0)" ::: "memory")
; __device__ __forceinline__ s16x4 vtr(const LAS unsigned char* p) { return __builtin_bit_cast(s16x4, __builtin_amdgcn_ds_read_tr16_b64_v4i16((LAS v4i16_t*)p)); }
; __device__ __forceinline__ bf16x8 cat8(s16x4 a, s16x4 b) { return (bf16x8){a[0], a[1], a[2], a[3], b[0], b[1], b[2], b[3]}; }
; #define MFMA32(a, b, c) __builtin_amdgcn_mfma_f32_32x32x16_bf16((a), (b), (c), 0, 0, 0)
; template <int DELTA> ...
;     ...
;         mx = fmaxf(mx, __shfl_xor(mx, 32));
;         const float m_new = fmaxf(m_run[qh], mx); const float alpha = __builtin_amdgcn_exp2f(m_run[qh] - m_new); m_run[qh] = m_new;
;         float ls = 0.f;
; #pragma unroll
;         for (int kvh = 0; kvh < 2; ++kvh) { const int toff = 64 * DELTA + 32 * (kvh - qh);
;             if (toff > 64 || toff < -64) continue;
; #pragma unroll
;             for (int rr = 0; rr < 16; ++rr) { const float e = __builtin_amdgcn_exp2f(s[kvh][rr] - m_new); s[kvh][rr] = e; ls += e; }
;             pb[qh][2 * kvh] = packp(s[kvh], 0); pb[qh][2 * kvh + 1] = packp(s[kvh], 8); }
;         l_run[qh] = l_run[qh] * alpha + ls;
; #pragma unroll
;         for (int i = 0; i < 16; ++i) { o[qh][0][i] *= alpha; o[qh][1][i] *= alpha; }
;     }
;     LDS_WAIT();
; #pragma unroll
;     for (int j = 0; j < 4; ++j) { const LAS unsigned char* vj = wl + voff + 16 * j * VP;
;         const bf16x8 a0 = cat8(vtr(vj), vtr(vj + 8 * VP)); const bf16x8 a1 = cat8(vtr(vj + 64), vtr(vj + 8 * VP + 64));
; #pragma unroll
;         for (int qh = 0; qh < 2; ++qh) { const int toff = 64 * DELTA + 32 * ((j >> 1) - qh);
;             if (toff > 64 || toff < -64) continue;
;             o[qh][0] = MFMA32(a0, pb[qh][j], o[qh][0]); o[qh][1] = MFMA32(a1, pb[qh][j], o[qh][1]); } }
	v_add_f32_e32 v0, v80, v252
	v_cndmask_b32_e64 v66, v0, v230, s[66:67]
	v_add_f32_e32 v0, v81, v253
	v_cndmask_b32_e64 v67, v0, v230, s[68:69]
	v_max3_f32 v0, v153, v90, v91
	v_max3_f32 v0, v0, v68, v69
	v_max3_f32 v0, v0, v70, v71
	v_max3_f32 v0, v0, v72, v73
	v_max3_f32 v0, v0, v92, v93
	v_max3_f32 v0, v0, v94, v95
	v_max3_f32 v0, v0, v96, v97
	v_max3_f32 v0, v0, v66, v67
	ds_bpermute_b32 v74, v208, v0
	s_waitcnt lgkmcnt(0)
	v_max3_f32 v130, v223, v0, v74
	v_sub_f32_e32 v0, v145, v130
	v_exp_f32_e32 v74, v0
	v_sub_f32_e32 v75, v142, v130
	v_exp_f32_e32 v75, v75
	v_sub_f32_e32 v76, v149, v130
	v_exp_f32_e32 v76, v76
	v_sub_f32_e32 v77, v146, v130
	v_exp_f32_e32 v77, v77
	v_sub_f32_e32 v78, v151, v130
	v_add_f32_e32 v0, 0, v74
	v_exp_f32_e32 v80, v78
	v_sub_f32_e32 v78, v147, v130
	v_add_f32_e32 v0, v75, v0
	v_exp_f32_e32 v81, v78
	v_sub_f32_e32 v78, v152, v130
	v_add_f32_e32 v0, v76, v0
	v_exp_f32_e32 v99, v78
	v_sub_f32_e32 v78, v150, v130
	v_add_f32_e32 v0, v77, v0
	v_exp_f32_e32 v100, v78
	v_sub_f32_e32 v78, v148, v130
	v_add_f32_e32 v0, v80, v0
	v_exp_f32_e32 v101, v78
	v_sub_f32_e32 v78, v144, v130
	v_add_f32_e32 v0, v81, v0
	v_exp_f32_e32 v102, v78
	v_sub_f32_e32 v78, v143, v130
	v_add_f32_e32 v0, v99, v0
	v_exp_f32_e32 v103, v78
	v_sub_f32_e32 v78, v141, v130
	v_add_f32_e32 v0, v100, v0
	v_exp_f32_e32 v104, v78
	v_sub_f32_e32 v78, v140, v130
	v_add_f32_e32 v0, v101, v0
	v_exp_f32_e32 v105, v78
	v_sub_f32_e32 v78, v139, v130
	v_add_f32_e32 v0, v102, v0
	v_exp_f32_e32 v106, v78
	v_sub_f32_e32 v78, v138, v130
	v_add_f32_e32 v0, v103, v0
	v_exp_f32_e32 v107, v78
	v_sub_f32_e32 v78, v128, v130
	v_add_f32_e32 v0, v104, v0
	v_exp_f32_e32 v108, v78
	v_sub_f32_e32 v90, v90, v130
	v_add_f32_e32 v0, v105, v0
	v_exp_f32_e32 v114, v90
	v_sub_f32_e32 v90, v91, v130
	v_add_f32_e32 v0, v106, v0
	v_exp_f32_e32 v116, v90
	v_sub_f32_e32 v68, v68, v130
	v_add_f32_e32 v0, v107, v0
	v_exp_f32_e32 v118, v68
	v_sub_f32_e32 v68, v69, v130
	v_add_f32_e32 v0, v108, v0
	v_exp_f32_e32 v120, v68
	v_sub_f32_e32 v68, v70, v130
	v_exp_f32_e32 v122, v68
	v_sub_f32_e32 v68, v71, v130
	v_pk_add_f32 v[90:91], v[114:115], v[0:1]
	v_exp_f32_e32 v126, v68
	v_sub_f32_e32 v68, v72, v130
	v_pk_add_f32 v[90:91], v[116:117], v[90:91]
	v_exp_f32_e32 v124, v68
	v_sub_f32_e32 v68, v73, v130
	v_pk_add_f32 v[90:91], v[118:119], v[90:91]
	v_exp_f32_e32 v128, v68
	v_sub_f32_e32 v68, v92, v130
	v_pk_add_f32 v[90:91], v[120:121], v[90:91]
	v_exp_f32_e32 v158, v68
	v_sub_f32_e32 v68, v93, v130
	v_pk_add_f32 v[90:91], v[122:123], v[90:91]
	v_exp_f32_e32 v160, v68
	v_sub_f32_e32 v68, v94, v130
	v_pk_add_f32 v[90:91], v[126:127], v[90:91]
	v_exp_f32_e32 v162, v68
	v_sub_f32_e32 v68, v95, v130
	v_pk_add_f32 v[90:91], v[124:125], v[90:91]
	v_exp_f32_e32 v164, v68
	v_sub_f32_e32 v68, v96, v130
	v_pk_add_f32 v[90:91], v[128:129], v[90:91]
	v_exp_f32_e32 v166, v68
	v_sub_f32_e32 v68, v97, v130
	v_pk_add_f32 v[90:91], v[158:159], v[90:91]
	v_exp_f32_e32 v168, v68
	v_sub_f32_e32 v66, v66, v130
	v_pk_add_f32 v[90:91], v[160:161], v[90:91]
	v_exp_f32_e32 v170, v66
	v_sub_f32_e32 v66, v67, v130
	v_pk_add_f32 v[90:91], v[162:163], v[90:91]
	v_sub_f32_e32 v98, v223, v130
	v_exp_f32_e32 v172, v66
	v_pk_add_f32 v[90:91], v[164:165], v[90:91]
	v_exp_f32_e32 v92, v98
	v_pk_add_f32 v[90:91], v[166:167], v[90:91]
	v_cvt_pk_bf16_f32 v78, v74, v75
	v_cvt_pk_bf16_f32 v79, v76, v77
	v_cvt_pk_bf16_f32 v80, v80, v81
	v_cvt_pk_bf16_f32 v81, v99, v100
	v_cvt_pk_bf16_f32 v74, v101, v102
	s_nop 0
	v_pk_add_f32 v[90:91], v[168:169], v[90:91]
	v_cvt_pk_bf16_f32 v75, v103, v104
	v_cvt_pk_bf16_f32 v76, v105, v106
	v_cvt_pk_bf16_f32 v77, v107, v108
	v_cvt_pk_bf16_f32 v70, v114, v116
	v_cvt_pk_bf16_f32 v71, v118, v120
	s_nop 0
	v_pk_add_f32 v[90:91], v[170:171], v[90:91]
	v_cvt_pk_bf16_f32 v72, v122, v126
	v_cvt_pk_bf16_f32 v73, v124, v128
	v_cvt_pk_bf16_f32 v66, v158, v160
	v_cvt_pk_bf16_f32 v67, v162, v164
	v_cvt_pk_bf16_f32 v68, v166, v168
	v_cvt_pk_bf16_f32 v69, v170, v172
	s_nop 0
	v_pk_add_f32 v[90:91], v[172:173], v[90:91]
	v_mov_b32_e32 v93, v174
	s_waitcnt lgkmcnt(0)
	v_pk_fma_f32 v[154:155], v[154:155], v[92:93], v[90:91]
	v_pk_mul_f32 v[32:33], v[32:33], v[92:93] op_sel_hi:[1,0]
	v_pk_mul_f32 v[30:31], v[30:31], v[92:93] op_sel_hi:[1,0]
	v_pk_mul_f32 v[28:29], v[28:29], v[92:93] op_sel_hi:[1,0]
	v_pk_mul_f32 v[26:27], v[26:27], v[92:93] op_sel_hi:[1,0]
	v_pk_mul_f32 v[24:25], v[24:25], v[92:93] op_sel_hi:[1,0]
	v_pk_mul_f32 v[22:23], v[22:23], v[92:93] op_sel_hi:[1,0]
	v_pk_mul_f32 v[20:21], v[20:21], v[92:93] op_sel_hi:[1,0]
	v_pk_mul_f32 v[18:19], v[18:19], v[92:93] op_sel_hi:[1,0]
	v_pk_mul_f32 v[16:17], v[16:17], v[92:93] op_sel_hi:[1,0]
	v_pk_mul_f32 v[14:15], v[14:15], v[92:93] op_sel_hi:[1,0]
	v_pk_mul_f32 v[12:13], v[12:13], v[92:93] op_sel_hi:[1,0]
	v_pk_mul_f32 v[10:11], v[10:11], v[92:93] op_sel_hi:[1,0]
	v_pk_mul_f32 v[8:9], v[8:9], v[92:93] op_sel_hi:[1,0]
	v_pk_mul_f32 v[6:7], v[6:7], v[92:93] op_sel_hi:[1,0]
	v_pk_mul_f32 v[4:5], v[4:5], v[92:93] op_sel_hi:[1,0]
	v_pk_mul_f32 v[2:3], v[2:3], v[92:93] op_sel_hi:[1,0]
	ds_read_b64_tr_b16 v[90:91], v222
	ds_read_b64_tr_b16 v[92:93], v222 offset:1536
	ds_read_b64_tr_b16 v[94:95], v222 offset:64
	ds_read_b64_tr_b16 v[96:97], v222 offset:1600
	s_waitcnt lgkmcnt(2)
	v_mfma_f32_32x32x16_bf16 v[18:33], v[90:93], v[78:81], v[18:33]
	s_waitcnt lgkmcnt(0)
	v_mfma_f32_32x32x16_bf16 v[2:17], v[94:97], v[78:81], v[2:17]
	v_mfma_f32_32x32x16_bf16 v[50:65], v[90:93], v[86:89], v[50:65]
	v_mfma_f32_32x32x16_bf16 v[34:49], v[94:97], v[86:89], v[34:49]
	ds_read_b64_tr_b16 v[78:79], v222 offset:3072
	ds_read_b64_tr_b16 v[80:81], v222 offset:4608
	ds_read_b64_tr_b16 v[86:87], v222 offset:3136
	ds_read_b64_tr_b16 v[88:89], v222 offset:4672
	s_waitcnt lgkmcnt(2)
	v_mfma_f32_32x32x16_bf16 v[18:33], v[78:81], v[74:77], v[18:33]
	s_waitcnt lgkmcnt(0)
	v_mfma_f32_32x32x16_bf16 v[2:17], v[86:89], v[74:77], v[2:17]
	v_mfma_f32_32x32x16_bf16 v[50:65], v[78:81], v[82:85], v[50:65]
	ds_read_b64_tr_b16 v[74:75], v222 offset:6144
	ds_read_b64_tr_b16 v[76:77], v222 offset:7680
	ds_read_b64_tr_b16 v[78:79], v222 offset:6208
	ds_read_b64_tr_b16 v[80:81], v222 offset:7744
	s_waitcnt lgkmcnt(2)
	v_mfma_f32_32x32x16_bf16 v[18:33], v[74:77], v[70:73], v[18:33]
	s_waitcnt lgkmcnt(0)
	v_mfma_f32_32x32x16_bf16 v[2:17], v[78:81], v[70:73], v[2:17]
	ds_read_b64_tr_b16 v[70:71], v222 offset:9216
	ds_read_b64_tr_b16 v[72:73], v222 offset:10752
	ds_read_b64_tr_b16 v[74:75], v222 offset:9280
	ds_read_b64_tr_b16 v[76:77], v222 offset:10816
	s_waitcnt lgkmcnt(0)
	v_mfma_f32_32x32x16_bf16 v[34:49], v[86:89], v[82:85], v[34:49]
	s_waitcnt lgkmcnt(2)
	v_mfma_f32_32x32x16_bf16 v[18:33], v[70:73], v[66:69], v[18:33]
	s_waitcnt lgkmcnt(0)
	v_mfma_f32_32x32x16_bf16 v[2:17], v[74:77], v[66:69], v[2:17]

; template <int DELTA> ...
;     u32x4 vv[8]; bf16x8 kf[2][4];
; #pragma unroll
;     for (int i = 0; i < 8; ++i) { const int idx = lane + 64 * i, row = idx >> 3, ch = idx & 7; vv[i] = *(const u32x4*)(vbase + (size_t)row * rstride + ch * 8); }
; #pragma unroll
;     for (int kvh = 0; kvh < 2; ++kvh)
; #pragma unroll
;         for (int d0 = 0; d0 < 4; ++d0) kf[kvh][d0] = *(const bf16x8*)(kbase + (size_t)(32 * kvh + r32) * rstride + d0 * 16);
;     SBAR0();
; #pragma unroll
;     for (int i = 0; i < 8; ++i) { const int idx = lane + 64 * i, row = idx >> 3, ch = idx & 7; *(LAS u32x4*)(wl + row * VP + ch * 16) = vv[i]; }
;     bf16x8 pb[2][4];
; #pragma unroll
;     for (int qh = 0; qh < 2; ++qh) {
;         f32x16 s[2]; float mx = -1e30f;
; #pragma unroll
;         for (int kvh = 0; kvh < 2; ++kvh) {
;             constexpr int dummy = 0; (void)dummy;
;             const int toff = 64 * DELTA + 32 * (kvh - qh);
; template <int P_>
; __device__ __forceinline__ void dil_wave_unit(LAS unsigned char* wl, const bf16_t* DIL, bf16_t* Y, bf16_t* ST, float* LSE, const float* BT, int b, int h, int r, int nb) {
;     ...
;     const size_t tok0 = (size_t)b * SEQ; const size_t rstride = (size_t)dil * 64;
;     LAS float* bt = (LAS float*)(wl + VT_B);
;     for (int i = lane; i < 257; i += 64) { int j = i - 64; j = j < 0 ? 0 : (j > 128 ? 128 : j); bt[i] = BT[(P_ * 8 + h) * 129 + j]; }
;     const int btb = 128 * 4;
;     const int bvar = btb + 4 * (4 * hi - r32);
;     bf16x8 qf[2][4];
;     const bf16_t* rowb = DIL + ((size_t)(b * 8 + h) * SEQ + (size_t)(64 * nb) * dil + r) * 64;
;     constexpr size_t KOFF = pg8::DPLANE, VOFF = 2 * pg8::DPLANE;
; #pragma unroll
;     for (int qh = 0; qh < 2; ++qh)
; #pragma unroll
;         for (int d0 = 0; d0 < 4; ++d0) qf[qh][d0] = *(const bf16x8*)(rowb + (size_t)(32 * qh + r32) * rstride + hi * 8 + d0 * 16);
;     f32x16 o[2][2];
; #pragma unroll
;     for (int a = 0; a < 2; ++a)
; #pragma unroll
;         for (int c = 0; c < 2; ++c)
; #pragma unroll
;             for (int i = 0; i < 16; ++i) o[a][c][i] = 0.f;
;     float m_run[2] = {-1e30f, -1e30f}, l_run[2] = {0.f, 0.f};
;     const int voff = (4 * hi + ((lane & 15) >> 2)) * VP + (16 * ((lane >> 4) & 1) + 4 * (lane & 3)) * 2;
;     LDS_WAIT();
;     dil_block<0>(wl, rowb + KOFF + hi * 8, rowb + VOFF, rstride, qf, o, m_run, l_run, bvar, voff, lane, r32, hi, btb);
.LBB0_467:
	s_or_b64 exec, exec, s[34:35]
	s_or_b32 s34, s44, s11
	s_ashr_i32 s35, s34, 31
	s_add_u32 s40, s82, s34
	s_addc_u32 s41, s83, s35
	s_lshl_b64 s[40:41], s[40:41], 7
	v_lshrrev_b32_e32 v3, 5, v209
	v_and_b32_e32 v210, 31, v2
	s_add_u32 s72, s4, s40
	s_addc_u32 s73, s5, s41
	v_lshlrev_b32_e32 v171, 10, v210
	s_waitcnt vmcnt(0)
	v_lshlrev_b32_e32 v0, 4, v3
	v_lshl_add_u64 v[4:5], s[72:73], 0, v[0:1]
	v_lshlrev_b32_e32 v20, 11, v210
	v_mov_b32_e32 v21, v1
	v_or_b32_e32 v0, 0x8000, v171
	v_lshl_add_u64 v[6:7], v[4:5], 0, v[20:21]
	v_lshlrev_b32_e32 v0, 1, v0
	s_mov_b64 s[40:41], 0x4000000
	global_load_dwordx4 v[126:129], v[6:7], off
	global_load_dwordx4 v[114:117], v[6:7], off offset:32
	global_load_dwordx4 v[118:121], v[6:7], off offset:64
	global_load_dwordx4 v[122:125], v[6:7], off offset:96
	v_lshl_add_u64 v[6:7], v[4:5], 0, v[0:1]
	v_lshl_add_u64 v[22:23], v[4:5], 0, s[40:41]
	v_lshlrev_b32_e32 v4, 3, v209
	v_and_b32_e32 v4, 56, v4
	v_lshlrev_b32_e32 v146, 1, v4
	v_mov_b32_e32 v147, v1
	v_lshrrev_b32_e32 v70, 3, v209
	v_lshl_add_u64 v[94:95], s[72:73], 0, v[146:147]
	s_mov_b64 s[40:41], 0x8000000
	v_or_b32_e32 v71, 8, v70
	v_or_b32_e32 v72, 16, v70
	v_or_b32_e32 v73, 24, v70
	v_or_b32_e32 v74, 32, v70
	global_load_dwordx4 v[110:113], v[6:7], off
	global_load_dwordx4 v[106:109], v[6:7], off offset:32
	global_load_dwordx4 v[98:101], v[6:7], off offset:64
	global_load_dwordx4 v[102:105], v[6:7], off offset:96
	v_lshl_add_u64 v[24:25], v[94:95], 0, s[40:41]
	v_lshlrev_b32_e32 v4, 11, v70
	v_mov_b32_e32 v5, v1
	v_lshlrev_b32_e32 v6, 11, v71
	v_mov_b32_e32 v7, v1
	v_lshlrev_b32_e32 v12, 11, v72
	v_mov_b32_e32 v13, v1
	v_lshlrev_b32_e32 v14, 11, v73
	v_mov_b32_e32 v15, v1
	v_lshlrev_b32_e32 v26, 11, v74
	v_mov_b32_e32 v27, v1
	v_or_b32_e32 v75, 40, v70
	s_waitcnt lgkmcnt(0)
	v_lshl_add_u64 v[4:5], v[24:25], 0, v[4:5]
	v_lshl_add_u64 v[8:9], v[24:25], 0, v[6:7]
	v_lshl_add_u64 v[12:13], v[24:25], 0, v[12:13]
	v_lshl_add_u64 v[16:17], v[24:25], 0, v[14:15]
	v_lshl_add_u64 v[26:27], v[24:25], 0, v[26:27]
	v_lshlrev_b32_e32 v28, 11, v75
	v_mov_b32_e32 v29, v1
	v_or_b32_e32 v76, 48, v70
	global_load_dwordx4 v[4:7], v[4:5], off
	s_nop 0
	global_load_dwordx4 v[8:11], v[8:9], off
	s_nop 0
	global_load_dwordx4 v[12:15], v[12:13], off
	s_nop 0
	global_load_dwordx4 v[16:19], v[16:17], off
	v_lshl_add_u64 v[28:29], v[24:25], 0, v[28:29]
	global_load_dwordx4 v[54:57], v[26:27], off
	global_load_dwordx4 v[58:61], v[28:29], off
	v_lshlrev_b32_e32 v26, 11, v76
	v_mov_b32_e32 v27, v1
	v_or_b32_e32 v77, 56, v70
	v_lshl_add_u64 v[26:27], v[24:25], 0, v[26:27]
	v_lshlrev_b32_e32 v28, 11, v77
	v_mov_b32_e32 v29, v1
	v_lshl_add_u64 v[20:21], v[22:23], 0, v[20:21]
	v_lshl_add_u64 v[24:25], v[24:25], 0, v[28:29]
	global_load_dwordx4 v[62:65], v[26:27], off
	global_load_dwordx4 v[66:69], v[24:25], off
	global_load_dwordx4 v[50:53], v[20:21], off
	global_load_dwordx4 v[46:49], v[20:21], off offset:32
	global_load_dwordx4 v[42:45], v[20:21], off offset:64
	global_load_dwordx4 v[38:41], v[20:21], off offset:96
	v_lshl_add_u64 v[20:21], v[22:23], 0, v[0:1]
	global_load_dwordx4 v[34:37], v[20:21], off
	global_load_dwordx4 v[30:33], v[20:21], off offset:32
	global_load_dwordx4 v[22:25], v[20:21], off offset:64
	global_load_dwordx4 v[26:29], v[20:21], off offset:96
	v_lshlrev_b32_e32 v20, 2, v3
	v_sub_u32_e32 v21, v20, v210
	v_lshlrev_b32_e32 v172, 3, v3
	v_lshrrev_b32_e32 v3, 2, v2
	v_lshlrev_b32_e32 v147, 2, v21
	v_and_or_b32 v183, v3, 3, v20
	v_and_b32_e32 v3, 16, v2
	v_lshlrev_b32_e32 v2, 2, v2
	v_add_u32_e32 v211, 0x200, v147
	v_and_or_b32 v2, v2, 12, v3
	v_lshlrev_b32_e32 v184, 1, v2
	v_lshlrev_b32_e32 v173, 10, v70
	v_lshlrev_b32_e32 v174, 10, v71
	v_lshlrev_b32_e32 v175, 10, v72
	v_lshlrev_b32_e32 v176, 10, v73
	v_lshlrev_b32_e32 v177, 10, v74
	v_lshlrev_b32_e32 v178, 10, v75
	v_lshlrev_b32_e32 v179, 10, v76
	v_lshlrev_b32_e32 v180, 10, v77
	v_lshlrev_b32_e32 v2, 4, v209
	v_and_b32_e32 v2, 0x70, v2
	v_add_u32_e32 v181, s10, v2
	v_mad_u32_u24 v2, v70, s33, v181
	s_waitcnt vmcnt(15)
	ds_write_b128 v2, v[4:7]
	s_waitcnt vmcnt(14)
	ds_write_b128 v2, v[8:11] offset:1536
	s_waitcnt vmcnt(13)
	ds_write_b128 v2, v[12:15] offset:3072
	s_waitcnt vmcnt(12)
	ds_write_b128 v2, v[16:19] offset:4608
	s_waitcnt vmcnt(11)
	ds_write_b128 v2, v[54:57] offset:6144
	s_waitcnt vmcnt(10)
	ds_write_b128 v2, v[58:61] offset:7680
	s_waitcnt vmcnt(9)
	ds_write_b128 v2, v[62:65] offset:9216
	s_waitcnt vmcnt(8)
	ds_write_b128 v2, v[66:69] offset:10752
	s_waitcnt vmcnt(7)
	v_mfma_f32_32x32x16_bf16 v[2:17], v[50:53], v[126:129], 0
	v_add_u32_e32 v216, s10, v147
	v_add_u32_e32 v54, 0x3200, v216
	ds_read2_b32 v[20:21], v54 offset1:1
	v_add_u32_e32 v60, 0x3208, v216
	v_add_u32_e32 v64, 0x3220, v216
	v_add_u32_e32 v78, 0x3228, v216
	v_add_u32_e32 v80, 0x3240, v216
	s_waitcnt vmcnt(6)
	v_mfma_f32_32x32x16_bf16 v[2:17], v[46:49], v[114:117], v[2:17]
	v_add_u32_e32 v62, 0x3248, v216
	v_add_u32_e32 v58, 0x3260, v216
	v_add_u32_e32 v56, 0x3268, v216
	v_mul_u32_u24_e32 v182, 0xc0, v70
	v_add_u32_e32 v212, 0x3280, v216
	v_add_u32_e32 v213, 0x3288, v216
	v_add_u32_e32 v214, 0x32a0, v216
	s_waitcnt vmcnt(5)
	v_mfma_f32_32x32x16_bf16 v[2:17], v[42:45], v[118:121], v[2:17]
	v_add_u32_e32 v215, 0x32a8, v216
	v_add_u32_e32 v217, 0x32c0, v216
	v_add_u32_e32 v218, 0x32c8, v216
	v_add_u32_e32 v219, 0x32e0, v216
	v_add_u32_e32 v220, 0x32e8, v216
	v_add_u32_e32 v185, 0x3180, v216
	v_add_u32_e32 v186, 0x3188, v216
	s_waitcnt vmcnt(4)
	v_mfma_f32_32x32x16_bf16 v[2:17], v[38:41], v[122:125], v[2:17]
	v_add_u32_e32 v187, 0x31a0, v216
	v_add_u32_e32 v188, 0x31a8, v216
	v_add_u32_e32 v189, 0x31c0, v216
	v_add_u32_e32 v190, 0x31c8, v216
	v_add_u32_e32 v191, 0x31e0, v216
	v_add_u32_e32 v192, 0x31e8, v216
	s_andn2_b64 vcc, exec, s[96:97]
	s_waitcnt lgkmcnt(0)
; #define LAS __attribute__((address_space(3)))
; #define MFMA32(a, b, c) __builtin_amdgcn_mfma_f32_32x32x16_bf16((a), (b), (c), 0, 0, 0)
; template <int DELTA> ...
;     ...
;             for (int d0 = 0; d0 < 4; ++d0) s[kvh] = MFMA32(kf[kvh][d0], qf[qh][d0], s[kvh]);
; #pragma unroll
;             for (int rr = 0; rr < 16; ++rr) { const int c4 = 4 * ((rr & 3) + 8 * (rr >> 2)); const float bias = *(const LAS float*)(wl + bvar + (VT_B + c4 + toff * 4));
;                 float v = s[kvh][rr] + bias;
;                 if (toff == 64) v = (bvar <= btb - c4) ? v : -1e30f;
;                 if (toff == -64) v = (bvar >= btb - c4) ? v : -1e30f;
;                 s[kvh][rr] = v; mx = fmaxf(mx, v); }
;         }
;         mx = fmaxf(mx, __shfl_xor(mx, 32));
;         const float m_new = fmaxf(m_run[qh], mx); const float alpha = __builtin_amdgcn_exp2f(m_run[qh] - m_new); m_run[qh] = m_new;
;         float ls = 0.f;
; #pragma unroll
;         for (int kvh = 0; kvh < 2; ++kvh) { const int toff = 64 * DELTA + 32 * (kvh - qh);
;             if (toff > 64 || toff < -64) continue;
; #pragma unroll
;             for (int rr = 0; rr < 16; ++rr) { const float e = __builtin_amdgcn_exp2f(s[kvh][rr] - m_new); s[kvh][rr] = e; ls += e; }
;             pb[qh][2 * kvh] = packp(s[kvh], 0); pb[qh][2 * kvh + 1] = packp(s[kvh], 8); }
;         l_run[qh] = l_run[qh] * alpha + ls;
; #pragma unroll
;         for (int i = 0; i < 16; ++i) { o[qh][0][i] *= alpha; o[qh][1][i] *= alpha; }
	s_nop 3
	v_add_f32_e32 v19, v2, v20
	v_add_f32_e32 v18, v3, v21
	ds_read2_b32 v[240:241], v60 offset1:1
	ds_read2_b32 v[242:243], v64 offset1:1
	ds_read2_b32 v[244:245], v78 offset1:1
	ds_read2_b32 v[246:247], v80 offset1:1
	ds_read2_b32 v[248:249], v62 offset1:1
	ds_read2_b32 v[250:251], v58 offset1:1
	ds_read2_b32 v[252:253], v56 offset1:1
	v_max3_f32 v20, v19, s79, v18
	v_add_u32_e32 v234, v181, v182
	s_waitcnt lgkmcnt(0)
	v_add_f32_e32 v55, v4, v240
	v_add_f32_e32 v57, v5, v241
	v_max3_f32 v4, v20, v55, v57
	ds_read2_b32 v[20:21], v212 offset1:1
	s_waitcnt lgkmcnt(1)
	v_add_f32_e32 v59, v6, v242
	v_add_f32_e32 v61, v7, v243
	v_max3_f32 v4, v4, v59, v61
	s_waitcnt lgkmcnt(0)
	v_add_f32_e32 v63, v8, v244
	v_add_f32_e32 v65, v9, v245
	v_max3_f32 v4, v4, v63, v65
	s_waitcnt lgkmcnt(0)
	v_add_f32_e32 v66, v10, v246
	v_add_f32_e32 v67, v11, v247
	v_max3_f32 v4, v4, v66, v67
	s_waitcnt lgkmcnt(0)
	v_add_f32_e32 v68, v12, v248
	v_add_f32_e32 v69, v13, v249
	v_max3_f32 v4, v4, v68, v69
	s_waitcnt lgkmcnt(0)
	v_add_f32_e32 v70, v14, v250
	v_add_f32_e32 v71, v15, v251
	v_max3_f32 v4, v4, v70, v71
	s_waitcnt lgkmcnt(0)
	v_add_f32_e32 v72, v16, v252
	v_add_f32_e32 v73, v17, v253
	v_max3_f32 v74, v4, v72, v73
	s_waitcnt vmcnt(3)
	v_mfma_f32_32x32x16_bf16 v[2:17], v[34:37], v[126:129], 0
	s_waitcnt vmcnt(2)
	v_mfma_f32_32x32x16_bf16 v[2:17], v[30:33], v[114:117], v[2:17]
	s_waitcnt vmcnt(1)
	v_mfma_f32_32x32x16_bf16 v[2:17], v[22:25], v[118:121], v[2:17]
	s_waitcnt vmcnt(0)
	v_mfma_f32_32x32x16_bf16 v[2:17], v[26:29], v[122:125], v[2:17]
	s_nop 11
	v_add_f32_e32 v75, v2, v20
	v_add_f32_e32 v76, v3, v21
	ds_read2_b32 v[240:241], v213 offset1:1
	ds_read2_b32 v[242:243], v214 offset1:1
	ds_read2_b32 v[244:245], v215 offset1:1
	ds_read2_b32 v[246:247], v217 offset1:1
	ds_read2_b32 v[248:249], v218 offset1:1
	ds_read2_b32 v[250:251], v219 offset1:1
	ds_read2_b32 v[252:253], v220 offset1:1
	v_max3_f32 v20, v74, v75, v76
	s_waitcnt lgkmcnt(0)
	v_add_f32_e32 v4, v4, v240
	v_add_f32_e32 v5, v5, v241
	v_max3_f32 v20, v20, v4, v5
	s_waitcnt lgkmcnt(0)
	v_add_f32_e32 v6, v6, v242
	v_add_f32_e32 v7, v7, v243
	v_max3_f32 v20, v20, v6, v7
	s_waitcnt lgkmcnt(0)
	v_add_f32_e32 v8, v8, v244
	v_add_f32_e32 v9, v9, v245
	v_max3_f32 v20, v20, v8, v9
	s_waitcnt lgkmcnt(0)
	v_add_f32_e32 v10, v10, v246
	v_add_f32_e32 v11, v11, v247
	v_max3_f32 v20, v20, v10, v11
	s_waitcnt lgkmcnt(0)
	v_add_f32_e32 v12, v12, v248
	v_add_f32_e32 v13, v13, v249
	v_max3_f32 v20, v20, v12, v13
	s_waitcnt lgkmcnt(0)
	v_add_f32_e32 v14, v14, v250
	v_add_f32_e32 v15, v15, v251
	v_max3_f32 v20, v20, v14, v15
	s_waitcnt lgkmcnt(0)
	v_add_f32_e32 v2, v16, v252
	v_add_f32_e32 v3, v17, v253
	v_max3_f32 v16, v20, v2, v3
	ds_bpermute_b32 v17, v208, v16
	s_waitcnt lgkmcnt(0)
	v_max3_f32 v170, v16, v17, s79
	v_sub_f32_e32 v17, v19, v170
	v_exp_f32_e32 v83, v17
	v_sub_f32_e32 v17, v18, v170
	v_exp_f32_e32 v85, v17
	v_sub_f32_e32 v17, v55, v170
	v_exp_f32_e32 v89, v17
	v_sub_f32_e32 v17, v57, v170
	v_exp_f32_e32 v149, v17
	v_sub_f32_e32 v17, v59, v170
	v_exp_f32_e32 v151, v17
	v_sub_f32_e32 v17, v61, v170
	v_exp_f32_e32 v155, v17
	v_sub_f32_e32 v17, v63, v170
	v_sub_f32_e32 v4, v4, v170
	v_exp_f32_e32 v157, v17
	v_sub_f32_e32 v17, v65, v170
	v_exp_f32_e32 v93, v4
	v_sub_f32_e32 v4, v5, v170
	v_exp_f32_e32 v163, v17
	v_sub_f32_e32 v17, v66, v170
	v_exp_f32_e32 v133, v4
	v_sub_f32_e32 v4, v6, v170
	v_exp_f32_e32 v153, v17
	v_sub_f32_e32 v17, v67, v170
	v_exp_f32_e32 v135, v4
	v_sub_f32_e32 v4, v7, v170
	v_exp_f32_e32 v159, v17
	v_sub_f32_e32 v17, v68, v170
	v_exp_f32_e32 v139, v4
	v_sub_f32_e32 v4, v8, v170
	v_exp_f32_e32 v161, v17
	v_sub_f32_e32 v17, v69, v170
	v_exp_f32_e32 v141, v4
	v_sub_f32_e32 v4, v9, v170
	v_exp_f32_e32 v165, v17
	v_sub_f32_e32 v17, v70, v170
	v_exp_f32_e32 v143, v4
	v_sub_f32_e32 v4, v10, v170
	v_exp_f32_e32 v167, v17
	v_sub_f32_e32 v17, v71, v170
	v_exp_f32_e32 v137, v4
	v_sub_f32_e32 v4, v11, v170
	v_exp_f32_e32 v169, v17
	v_sub_f32_e32 v17, v72, v170
	v_exp_f32_e32 v57, v4
	v_sub_f32_e32 v4, v12, v170
	v_exp_f32_e32 v91, v17
	v_sub_f32_e32 v17, v73, v170
	v_exp_f32_e32 v59, v4
	v_sub_f32_e32 v4, v13, v170
	v_exp_f32_e32 v145, v17
	v_sub_f32_e32 v17, v75, v170
	v_exp_f32_e32 v61, v4
	v_sub_f32_e32 v4, v14, v170
	v_sub_f32_e32 v2, v2, v170
	v_sub_f32_e32 v16, 0xf149f2ca, v170
	v_exp_f32_e32 v79, v17
	v_sub_f32_e32 v17, v76, v170
	v_exp_f32_e32 v63, v4
	v_sub_f32_e32 v4, v15, v170
	v_exp_f32_e32 v97, v2
	v_sub_f32_e32 v2, v3, v170
	v_exp_f32_e32 v81, v17
	v_exp_f32_e32 v65, v4
	v_exp_f32_e32 v131, v2
	v_exp_f32_e32 v55, v16
	v_mfma_f32_32x32x16_bf16 v[2:17], v[50:53], v[110:113], 0
	v_cvt_pk_bf16_f32 v18, v83, v85
	v_cvt_pk_bf16_f32 v19, v89, v149
	v_cvt_pk_bf16_f32 v20, v151, v155
	v_cvt_pk_bf16_f32 v21, v157, v163
	v_cvt_pk_bf16_f32 v70, v153, v159
	v_cvt_pk_bf16_f32 v71, v161, v165
	v_cvt_pk_bf16_f32 v72, v167, v169
	v_mfma_f32_32x32x16_bf16 v[2:17], v[46:49], v[106:109], v[2:17]
	v_cvt_pk_bf16_f32 v73, v91, v145
	v_cvt_pk_bf16_f32 v74, v79, v81
	v_cvt_pk_bf16_f32 v75, v93, v133
	v_cvt_pk_bf16_f32 v76, v135, v139
	v_cvt_pk_bf16_f32 v77, v141, v143
	v_cvt_pk_bf16_f32 v66, v137, v57
	v_cvt_pk_bf16_f32 v67, v59, v61
	v_mfma_f32_32x32x16_bf16 v[2:17], v[42:45], v[98:101], v[2:17]
	v_cvt_pk_bf16_f32 v68, v63, v65
	v_cvt_pk_bf16_f32 v69, v97, v131
	v_mfma_f32_32x32x16_bf16 v[2:17], v[38:41], v[102:105], v[2:17]
	ds_read2_b32 v[38:39], v185 offset1:1
	s_waitcnt lgkmcnt(0)
	s_nop 9
	v_add_f32_e32 v41, v2, v38
	v_add_f32_e32 v42, v3, v39
	ds_read2_b32 v[240:241], v186 offset1:1
	ds_read2_b32 v[242:243], v187 offset1:1
	ds_read2_b32 v[244:245], v188 offset1:1
	ds_read2_b32 v[246:247], v189 offset1:1
	ds_read2_b32 v[248:249], v190 offset1:1
	ds_read2_b32 v[250:251], v191 offset1:1
	ds_read2_b32 v[252:253], v192 offset1:1
	v_max3_f32 v39, v41, s79, v42
	s_waitcnt lgkmcnt(0)
; #define LAS __attribute__((address_space(3)))
; #define MFMA32(a, b, c) __builtin_amdgcn_mfma_f32_32x32x16_bf16((a), (b), (c), 0, 0, 0)
; template <int DELTA> ...
;     ...
;             for (int d0 = 0; d0 < 4; ++d0) s[kvh] = MFMA32(kf[kvh][d0], qf[qh][d0], s[kvh]);
; #pragma unroll
;             for (int rr = 0; rr < 16; ++rr) { const int c4 = 4 * ((rr & 3) + 8 * (rr >> 2)); const float bias = *(const LAS float*)(wl + bvar + (VT_B + c4 + toff * 4));
;                 float v = s[kvh][rr] + bias;
;                 if (toff == 64) v = (bvar <= btb - c4) ? v : -1e30f;
;                 if (toff == -64) v = (bvar >= btb - c4) ? v : -1e30f;
;                 s[kvh][rr] = v; mx = fmaxf(mx, v); }
;         }
;         mx = fmaxf(mx, __shfl_xor(mx, 32));
;         const float m_new = fmaxf(m_run[qh], mx); const float alpha = __builtin_amdgcn_exp2f(m_run[qh] - m_new); m_run[qh] = m_new;
;         float ls = 0.f;
; #pragma unroll
;         for (int kvh = 0; kvh < 2; ++kvh) { const int toff = 64 * DELTA + 32 * (kvh - qh);
;             if (toff > 64 || toff < -64) continue;
; #pragma unroll
;             for (int rr = 0; rr < 16; ++rr) { const float e = __builtin_amdgcn_exp2f(s[kvh][rr] - m_new); s[kvh][rr] = e; ls += e; }
;             pb[qh][2 * kvh] = packp(s[kvh], 0); pb[qh][2 * kvh + 1] = packp(s[kvh], 8); }
;         l_run[qh] = l_run[qh] * alpha + ls;
; #pragma unroll
;         for (int i = 0; i < 16; ++i) { o[qh][0][i] *= alpha; o[qh][1][i] *= alpha; }
	v_add_f32_e32 v43, v4, v240
	v_add_f32_e32 v38, v5, v241
	v_max3_f32 v4, v39, v43, v38
	s_waitcnt lgkmcnt(0)
	v_add_f32_e32 v44, v6, v242
	v_add_f32_e32 v45, v7, v243
	v_max3_f32 v4, v4, v44, v45
	s_waitcnt lgkmcnt(0)
	v_add_f32_e32 v46, v8, v244
	v_add_f32_e32 v47, v9, v245
	v_max3_f32 v4, v4, v46, v47
	s_waitcnt lgkmcnt(0)
	v_add_f32_e32 v48, v10, v246
	v_add_f32_e32 v49, v11, v247
	v_max3_f32 v4, v4, v48, v49
	s_waitcnt lgkmcnt(0)
	v_add_f32_e32 v50, v12, v248
	v_add_f32_e32 v51, v13, v249
	v_max3_f32 v4, v4, v50, v51
	s_waitcnt lgkmcnt(0)
	v_add_f32_e32 v52, v14, v250
	v_add_f32_e32 v53, v15, v251
	v_max3_f32 v4, v4, v52, v53
	s_waitcnt lgkmcnt(0)
	v_add_f32_e32 v40, v16, v252
	v_add_f32_e32 v39, v17, v253
	v_max3_f32 v82, v4, v40, v39
	v_mfma_f32_32x32x16_bf16 v[2:17], v[34:37], v[110:113], 0
	v_mfma_f32_32x32x16_bf16 v[2:17], v[30:33], v[106:109], v[2:17]
	v_mfma_f32_32x32x16_bf16 v[2:17], v[22:25], v[98:101], v[2:17]
	ds_read2_b32 v[22:23], v54 offset1:1
	v_mfma_f32_32x32x16_bf16 v[2:17], v[26:29], v[102:105], v[2:17]
	s_waitcnt lgkmcnt(0)
	s_nop 10
	v_add_f32_e32 v22, v2, v22
	v_add_f32_e32 v23, v3, v23
	ds_read2_b32 v[240:241], v60 offset1:1
	ds_read2_b32 v[242:243], v64 offset1:1
	ds_read2_b32 v[244:245], v78 offset1:1
	ds_read2_b32 v[246:247], v80 offset1:1
	ds_read2_b32 v[248:249], v62 offset1:1
	ds_read2_b32 v[250:251], v58 offset1:1
	ds_read2_b32 v[252:253], v56 offset1:1
	v_max3_f32 v24, v82, v22, v23
	s_waitcnt lgkmcnt(0)
	v_add_f32_e32 v4, v4, v240
	v_add_f32_e32 v5, v5, v241
	v_max3_f32 v24, v24, v4, v5
	s_waitcnt lgkmcnt(0)
	v_add_f32_e32 v6, v6, v242
	v_add_f32_e32 v7, v7, v243
	v_max3_f32 v24, v24, v6, v7
	s_waitcnt lgkmcnt(0)
	v_add_f32_e32 v8, v8, v244
	v_add_f32_e32 v9, v9, v245
	v_max3_f32 v24, v24, v8, v9
	s_waitcnt lgkmcnt(0)
	v_add_f32_e32 v10, v10, v246
	v_add_f32_e32 v11, v11, v247
	v_max3_f32 v24, v24, v10, v11
	s_waitcnt lgkmcnt(0)
	v_add_f32_e32 v12, v12, v248
	v_add_f32_e32 v13, v13, v249
	v_max3_f32 v24, v24, v12, v13
	s_waitcnt lgkmcnt(0)
	v_add_f32_e32 v14, v14, v250
	v_add_f32_e32 v15, v15, v251
	v_max3_f32 v24, v24, v14, v15
	s_waitcnt lgkmcnt(0)
	v_add_f32_e32 v16, v16, v252
	v_add_f32_e32 v17, v17, v253
	v_max3_f32 v2, v24, v16, v17
	ds_bpermute_b32 v3, v208, v2
	s_waitcnt lgkmcnt(0)
	v_max3_f32 v223, v2, v3, s79
	v_sub_f32_e32 v2, v41, v223
	v_exp_f32_e32 v82, v2
	v_sub_f32_e32 v2, v42, v223
	v_exp_f32_e32 v84, v2
	v_sub_f32_e32 v2, v43, v223
	v_exp_f32_e32 v88, v2
	v_sub_f32_e32 v25, v38, v223
	v_exp_f32_e32 v148, v25
	v_sub_f32_e32 v25, v44, v223
	v_pk_add_f32 v[2:3], v[82:83], 0 op_sel_hi:[1,0]
	v_exp_f32_e32 v150, v25
	v_sub_f32_e32 v25, v45, v223
	v_pk_add_f32 v[2:3], v[84:85], v[2:3]
	v_exp_f32_e32 v154, v25
	v_sub_f32_e32 v25, v46, v223
	v_pk_add_f32 v[2:3], v[88:89], v[2:3]
	v_exp_f32_e32 v156, v25
	v_sub_f32_e32 v25, v47, v223
	v_exp_f32_e32 v162, v25
	v_sub_f32_e32 v25, v48, v223
	v_pk_add_f32 v[2:3], v[148:149], v[2:3]
	v_exp_f32_e32 v152, v25
	v_sub_f32_e32 v25, v49, v223
	v_pk_add_f32 v[2:3], v[150:151], v[2:3]
	v_exp_f32_e32 v158, v25
	v_sub_f32_e32 v25, v50, v223
	v_pk_add_f32 v[2:3], v[154:155], v[2:3]
	v_exp_f32_e32 v160, v25
	v_sub_f32_e32 v25, v51, v223
	v_pk_add_f32 v[2:3], v[156:157], v[2:3]
	v_exp_f32_e32 v164, v25
	v_sub_f32_e32 v25, v52, v223
	v_pk_add_f32 v[2:3], v[162:163], v[2:3]
	v_exp_f32_e32 v166, v25
	v_sub_f32_e32 v25, v53, v223
	v_pk_add_f32 v[2:3], v[152:153], v[2:3]
	v_exp_f32_e32 v168, v25
	v_pk_add_f32 v[2:3], v[158:159], v[2:3]
	v_sub_f32_e32 v25, v40, v223
	v_pk_add_f32 v[2:3], v[160:161], v[2:3]
	v_exp_f32_e32 v90, v25
	v_sub_f32_e32 v25, v39, v223
	v_pk_add_f32 v[2:3], v[164:165], v[2:3]
	v_exp_f32_e32 v144, v25
	v_sub_f32_e32 v22, v22, v223
	v_pk_add_f32 v[2:3], v[166:167], v[2:3]
	v_exp_f32_e32 v78, v22
	v_sub_f32_e32 v22, v23, v223
	v_pk_add_f32 v[2:3], v[168:169], v[2:3]
	v_exp_f32_e32 v80, v22
	v_sub_f32_e32 v4, v4, v223
	v_exp_f32_e32 v92, v4
	v_sub_f32_e32 v4, v5, v223
	v_pk_add_f32 v[2:3], v[90:91], v[2:3]
	v_exp_f32_e32 v132, v4
	v_sub_f32_e32 v4, v6, v223
	v_pk_add_f32 v[2:3], v[144:145], v[2:3]
	v_exp_f32_e32 v134, v4
	v_sub_f32_e32 v4, v7, v223
	v_pk_add_f32 v[2:3], v[78:79], v[2:3]
	v_exp_f32_e32 v138, v4
	v_sub_f32_e32 v4, v8, v223
	v_pk_add_f32 v[2:3], v[80:81], v[2:3]
	v_exp_f32_e32 v140, v4
	v_sub_f32_e32 v4, v9, v223
	v_pk_add_f32 v[2:3], v[92:93], v[2:3]
	v_exp_f32_e32 v142, v4
	v_sub_f32_e32 v4, v10, v223
	v_pk_add_f32 v[2:3], v[132:133], v[2:3]
	v_exp_f32_e32 v136, v4
	v_pk_add_f32 v[2:3], v[134:135], v[2:3]
	v_sub_f32_e32 v4, v11, v223
	v_pk_add_f32 v[2:3], v[138:139], v[2:3]
	v_exp_f32_e32 v56, v4
	v_sub_f32_e32 v4, v12, v223
	v_pk_add_f32 v[2:3], v[140:141], v[2:3]
	v_exp_f32_e32 v58, v4
	v_sub_f32_e32 v4, v13, v223
	v_pk_add_f32 v[2:3], v[142:143], v[2:3]
	v_exp_f32_e32 v60, v4
	v_sub_f32_e32 v4, v14, v223
	v_pk_add_f32 v[2:3], v[136:137], v[2:3]
	v_exp_f32_e32 v62, v4
	v_sub_f32_e32 v4, v15, v223
	v_exp_f32_e32 v64, v4
	v_sub_f32_e32 v4, v16, v223
	v_pk_add_f32 v[2:3], v[56:57], v[2:3]
	v_exp_f32_e32 v96, v4
	v_sub_f32_e32 v4, v17, v223
	v_pk_add_f32 v[2:3], v[58:59], v[2:3]
	v_exp_f32_e32 v130, v4
	v_pk_add_f32 v[2:3], v[60:61], v[2:3]
	v_mov_b32_e32 v22, s10
	v_pk_add_f32 v[2:3], v[62:63], v[2:3]
	v_sub_f32_e32 v24, 0xf149f2ca, v223
	v_pk_add_f32 v[2:3], v[64:65], v[2:3]
	v_mad_u32_u24 v22, v183, s33, v22
	v_cvt_pk_bf16_f32 v86, v82, v84
	v_cvt_pk_bf16_f32 v87, v88, v148
	v_cvt_pk_bf16_f32 v88, v150, v154
	v_cvt_pk_bf16_f32 v89, v156, v162
	v_cvt_pk_bf16_f32 v82, v152, v158
	v_cvt_pk_bf16_f32 v83, v160, v164
	v_cvt_pk_bf16_f32 v84, v166, v168
	v_cvt_pk_bf16_f32 v85, v90, v144
	v_cvt_pk_bf16_f32 v90, v78, v80
	v_cvt_pk_bf16_f32 v91, v92, v132
	v_cvt_pk_bf16_f32 v92, v134, v138
	v_cvt_pk_bf16_f32 v93, v140, v142
	v_cvt_pk_bf16_f32 v78, v136, v56
	v_cvt_pk_bf16_f32 v79, v58, v60
	v_cvt_pk_bf16_f32 v80, v62, v64
	v_cvt_pk_bf16_f32 v81, v96, v130
	v_exp_f32_e32 v54, v24
	v_pk_add_f32 v[2:3], v[96:97], v[2:3]
	s_waitcnt lgkmcnt(0)
; #define LAS __attribute__((address_space(3)))
; #define LDS_WAIT() asm volatile("s_waitcnt lgkmcnt(0)" ::: "memory")
; __device__ __forceinline__ s16x4 vtr(const LAS unsigned char* p) { return __builtin_bit_cast(s16x4, __builtin_amdgcn_ds_read_tr16_b64_v4i16((LAS v4i16_t*)p)); }
; __device__ __forceinline__ bf16x8 cat8(s16x4 a, s16x4 b) { return (bf16x8){a[0], a[1], a[2], a[3], b[0], b[1], b[2], b[3]}; }
; #define MFMA32(a, b, c) __builtin_amdgcn_mfma_f32_32x32x16_bf16((a), (b), (c), 0, 0, 0)
; #define SBAR0() __builtin_amdgcn_sched_barrier(0)
; template <int DELTA> ...
;     u32x4 vv[8]; bf16x8 kf[2][4];
; #pragma unroll
;     for (int i = 0; i < 8; ++i) { const int idx = lane + 64 * i, row = idx >> 3, ch = idx & 7; vv[i] = *(const u32x4*)(vbase + (size_t)row * rstride + ch * 8); }
; #pragma unroll
;     for (int kvh = 0; kvh < 2; ++kvh)
; #pragma unroll
;         for (int d0 = 0; d0 < 4; ++d0) kf[kvh][d0] = *(const bf16x8*)(kbase + (size_t)(32 * kvh + r32) * rstride + d0 * 16);
;     SBAR0();
; #pragma unroll
;     for (int i = 0; i < 8; ++i) { const int idx = lane + 64 * i, row = idx >> 3, ch = idx & 7; *(LAS u32x4*)(wl + row * VP + ch * 16) = vv[i]; }
;     ...
;     LDS_WAIT();
; #pragma unroll
;     for (int j = 0; j < 4; ++j) { const LAS unsigned char* vj = wl + voff + 16 * j * VP;
;         const bf16x8 a0 = cat8(vtr(vj), vtr(vj + 8 * VP)); const bf16x8 a1 = cat8(vtr(vj + 64), vtr(vj + 8 * VP + 64));
; #pragma unroll
;         for (int qh = 0; qh < 2; ++qh) { const int toff = 64 * DELTA + 32 * ((j >> 1) - qh);
;             if (toff > 64 || toff < -64) continue;
;             o[qh][0] = MFMA32(a0, pb[qh][j], o[qh][0]); o[qh][1] = MFMA32(a1, pb[qh][j], o[qh][1]); } }
	v_add_u32_e32 v222, v22, v184
	v_pk_add_f32 v[4:5], v[130:131], v[2:3]
	ds_read_b64_tr_b16 v[130:131], v222
	ds_read_b64_tr_b16 v[132:133], v222 offset:1536
	ds_read_b64_tr_b16 v[134:135], v222 offset:64
	ds_read_b64_tr_b16 v[136:137], v222 offset:1600
	v_pk_mul_f32 v[2:3], v[54:55], 0 op_sel_hi:[1,0]
	v_pk_fma_f32 v[154:155], v[54:55], 0, v[4:5] op_sel_hi:[1,0,1]
	v_mov_b32_e32 v34, v3
	v_mov_b32_e32 v35, v3
	v_mov_b32_e32 v36, v3
	v_mov_b32_e32 v37, v3
	v_mov_b32_e32 v38, v3
	v_mov_b32_e32 v39, v3
	v_mov_b32_e32 v40, v3
	v_mov_b32_e32 v41, v3
	v_mov_b32_e32 v42, v3
	v_mov_b32_e32 v43, v3
	v_mov_b32_e32 v44, v3
	v_mov_b32_e32 v45, v3
	v_mov_b32_e32 v46, v3
	v_mov_b32_e32 v47, v3
	v_mov_b32_e32 v48, v3
	v_mov_b32_e32 v49, v3
	v_mov_b32_e32 v3, v2
	v_mov_b32_e32 v4, v2
	v_mov_b32_e32 v5, v2
	v_mov_b32_e32 v6, v2
	v_mov_b32_e32 v7, v2
	v_mov_b32_e32 v8, v2
	v_mov_b32_e32 v9, v2
	v_mov_b32_e32 v10, v2
	v_mov_b32_e32 v11, v2
	v_mov_b32_e32 v12, v2
	v_mov_b32_e32 v13, v2
	v_mov_b32_e32 v14, v2
	v_mov_b32_e32 v15, v2
	v_mov_b32_e32 v16, v2
	v_mov_b32_e32 v17, v2
	s_waitcnt lgkmcnt(2)
	v_mfma_f32_32x32x16_bf16 v[50:65], v[130:133], v[18:21], v[34:49]
	v_lshlrev_b32_e32 v156, 1, v172
	v_lshlrev_b32_e32 v168, 1, v173
	v_lshlrev_b32_e32 v166, 1, v174
	v_lshlrev_b32_e32 v164, 1, v175
	v_lshlrev_b32_e32 v162, 1, v176
	v_lshlrev_b32_e32 v160, 1, v177
	v_lshlrev_b32_e32 v158, 1, v178
	s_waitcnt lgkmcnt(0)
	v_mfma_f32_32x32x16_bf16 v[34:49], v[134:137], v[18:21], v[34:49]
	v_lshlrev_b32_e32 v152, 1, v179
	v_lshlrev_b32_e32 v150, 1, v180
	v_lshlrev_b32_e32 v148, 1, v171
	v_mfma_f32_32x32x16_bf16 v[18:33], v[130:133], v[86:89], v[2:17]
	v_mfma_f32_32x32x16_bf16 v[2:17], v[134:137], v[86:89], v[2:17]
	ds_read_b64_tr_b16 v[86:87], v222 offset:3072
	ds_read_b64_tr_b16 v[88:89], v222 offset:4608
	ds_read_b64_tr_b16 v[130:131], v222 offset:3136
	ds_read_b64_tr_b16 v[132:133], v222 offset:4672
	s_waitcnt lgkmcnt(2)
	v_mfma_f32_32x32x16_bf16 v[50:65], v[86:89], v[70:73], v[50:65]
	s_waitcnt lgkmcnt(0)
	v_mfma_f32_32x32x16_bf16 v[34:49], v[130:133], v[70:73], v[34:49]
	v_mfma_f32_32x32x16_bf16 v[18:33], v[86:89], v[82:85], v[18:33]
	v_mfma_f32_32x32x16_bf16 v[2:17], v[130:133], v[82:85], v[2:17]
	ds_read_b64_tr_b16 v[70:71], v222 offset:6144
	ds_read_b64_tr_b16 v[72:73], v222 offset:7680
	ds_read_b64_tr_b16 v[82:83], v222 offset:6208
	ds_read_b64_tr_b16 v[84:85], v222 offset:7744
	s_waitcnt lgkmcnt(2)
	v_mfma_f32_32x32x16_bf16 v[50:65], v[70:73], v[74:77], v[50:65]
	s_waitcnt lgkmcnt(0)
	v_mfma_f32_32x32x16_bf16 v[34:49], v[82:85], v[74:77], v[34:49]
	v_mfma_f32_32x32x16_bf16 v[18:33], v[70:73], v[90:93], v[18:33]
	ds_read_b64_tr_b16 v[70:71], v222 offset:9216
	ds_read_b64_tr_b16 v[72:73], v222 offset:10752
	ds_read_b64_tr_b16 v[74:75], v222 offset:9280
	ds_read_b64_tr_b16 v[76:77], v222 offset:10816
	s_waitcnt lgkmcnt(0)
	v_mfma_f32_32x32x16_bf16 v[2:17], v[82:85], v[90:93], v[2:17]
	s_waitcnt lgkmcnt(2)
	v_mfma_f32_32x32x16_bf16 v[50:65], v[70:73], v[66:69], v[50:65]
	s_waitcnt lgkmcnt(0)
	v_mfma_f32_32x32x16_bf16 v[34:49], v[74:77], v[66:69], v[34:49]
	v_mfma_f32_32x32x16_bf16 v[18:33], v[70:73], v[78:81], v[18:33]
	v_mfma_f32_32x32x16_bf16 v[2:17], v[74:77], v[78:81], v[2:17]
	s_cbranch_vccnz .LBB0_469
	v_mov_b32_e32 v157, v1
	v_lshl_add_u64 v[66:67], s[72:73], 0, v[156:157]
	s_mov_b64 s[40:41], 0x3fe0000
	v_lshl_add_u64 v[70:71], v[66:67], 0, s[40:41]
	s_mov_b64 s[40:41], 0x7fe0000
	v_lshl_add_u64 v[66:67], v[94:95], 0, s[40:41]
	v_mov_b32_e32 v169, v1
	v_mov_b32_e32 v167, v1
	v_lshl_add_u64 v[68:69], v[66:67], 0, v[168:169]
	v_lshl_add_u64 v[72:73], v[66:67], 0, v[166:167]
	v_mov_b32_e32 v165, v1
	v_mov_b32_e32 v163, v1
	global_load_dwordx4 v[82:85], v[68:69], off
	global_load_dwordx4 v[86:89], v[72:73], off
	v_lshl_add_u64 v[68:69], v[66:67], 0, v[164:165]
	v_lshl_add_u64 v[72:73], v[66:67], 0, v[162:163]
	v_mov_b32_e32 v161, v1
	v_mov_b32_e32 v159, v1
	global_load_dwordx4 v[90:93], v[68:69], off
	global_load_dwordx4 v[94:97], v[72:73], off
	v_lshl_add_u64 v[68:69], v[66:67], 0, v[160:161]
	v_lshl_add_u64 v[72:73], v[66:67], 0, v[158:159]
	v_mov_b32_e32 v153, v1
	v_mov_b32_e32 v151, v1
	v_mov_b32_e32 v149, v1
	global_load_dwordx4 v[172:175], v[68:69], off
	global_load_dwordx4 v[176:179], v[72:73], off
	v_lshl_add_u64 v[68:69], v[66:67], 0, v[152:153]
	v_lshl_add_u64 v[66:67], v[66:67], 0, v[150:151]
	v_lshl_add_u64 v[72:73], v[70:71], 0, v[148:149]
	v_lshl_add_u64 v[70:71], v[70:71], 0, v[0:1]
	global_load_dwordx4 v[180:183], v[68:69], off
	global_load_dwordx4 v[194:197], v[66:67], off
	s_nop 0
	global_load_dwordx4 v[66:69], v[72:73], off
	global_load_dwordx4 v[198:201], v[72:73], off offset:32
	global_load_dwordx4 v[202:205], v[72:73], off offset:64
	global_load_dwordx4 v[236:239], v[72:73], off offset:96
	global_load_dwordx4 v[142:145], v[70:71], off
	global_load_dwordx4 v[138:141], v[70:71], off offset:32
	global_load_dwordx4 v[134:137], v[70:71], off offset:64
	global_load_dwordx4 v[130:133], v[70:71], off offset:96
	s_waitcnt vmcnt(7)
	v_mfma_f32_32x32x16_bf16 v[66:81], v[66:69], v[126:129], 0
	ds_write_b128 v234, v[82:85]
	ds_write_b128 v234, v[86:89] offset:1536
	ds_write_b128 v234, v[90:93] offset:3072
	ds_write_b128 v234, v[94:97] offset:4608
	ds_write_b128 v234, v[172:175] offset:6144
	ds_write_b128 v234, v[176:179] offset:7680
	ds_write_b128 v234, v[180:183] offset:9216
	ds_write_b128 v234, v[194:197] offset:10752
	v_add_u32_e32 v172, 0x3100, v216
	v_add_u32_e32 v174, 0x3108, v216
	v_add_u32_e32 v176, 0x3120, v216
	v_add_u32_e32 v178, 0x3128, v216
	ds_read2_b32 v[82:83], v172 offset1:1
	ds_read2_b32 v[84:85], v174 offset1:1
	ds_read2_b32 v[86:87], v176 offset1:1
	ds_read2_b32 v[88:89], v178 offset1:1
	s_waitcnt vmcnt(6)
; #define LAS __attribute__((address_space(3)))
; #define MFMA32(a, b, c) __builtin_amdgcn_mfma_f32_32x32x16_bf16((a), (b), (c), 0, 0, 0)
; template <int DELTA> ...
;     ...
;         for (int kvh = 0; kvh < 2; ++kvh) {
;             constexpr int dummy = 0; (void)dummy;
;             const int toff = 64 * DELTA + 32 * (kvh - qh);
;             if (toff > 64 || toff < -64) continue;
; #pragma unroll
;             for (int i = 0; i < 16; ++i) s[kvh][i] = 0.f;
; #pragma unroll
;             for (int d0 = 0; d0 < 4; ++d0) s[kvh] = MFMA32(kf[kvh][d0], qf[qh][d0], s[kvh]);
; #pragma unroll
;             for (int rr = 0; rr < 16; ++rr) { const int c4 = 4 * ((rr & 3) + 8 * (rr >> 2)); const float bias = *(const LAS float*)(wl + bvar + (VT_B + c4 + toff * 4));
;                 float v = s[kvh][rr] + bias;
;                 if (toff == 64) v = (bvar <= btb - c4) ? v : -1e30f;
;                 if (toff == -64) v = (bvar >= btb - c4) ? v : -1e30f;
;                 s[kvh][rr] = v; mx = fmaxf(mx, v); }
;         }
;         mx = fmaxf(mx, __shfl_xor(mx, 32));
	v_mfma_f32_32x32x16_bf16 v[66:81], v[198:201], v[114:117], v[66:81]
	v_cmp_lt_u32_e32 vcc, s85, v147
	v_cmp_gt_u32_e64 s[40:41], s74, v211
	v_cmp_gt_u32_e64 s[42:43], s24, v211
	v_cmp_gt_u32_e64 s[44:45], s25, v211
	v_cmp_gt_u32_e64 s[48:49], s20, v211
	v_cmp_gt_u32_e64 s[46:47], s26, v211
	v_cmp_gt_u32_e64 s[52:53], s28, v211
	s_waitcnt vmcnt(5)
	v_mfma_f32_32x32x16_bf16 v[66:81], v[202:205], v[118:121], v[66:81]
	v_cmp_gt_u32_e64 s[50:51], s90, v211
	v_add_u32_e32 v180, 0x3140, v216
	v_cmp_gt_u32_e64 s[54:55], s91, v211
	v_cmp_gt_u32_e64 s[56:57], s76, v211
	v_add_u32_e32 v182, 0x3148, v216
	v_add_u32_e32 v184, 0x3160, v216
	v_add_u32_e32 v196, 0x3168, v216
	s_waitcnt vmcnt(4)
	v_mfma_f32_32x32x16_bf16 v[66:81], v[236:239], v[122:125], v[66:81]
	v_cmp_gt_u32_e64 s[58:59], s80, v211
	v_cmp_gt_u32_e64 s[60:61], s81, v211
	v_cmp_gt_u32_e64 s[62:63], s27, v211
	v_cmp_gt_u32_e64 s[64:65], s78, v211
	v_cmp_gt_u32_e64 s[66:67], s77, v211
	v_cmp_gt_u32_e64 s[68:69], s36, v211
	s_waitcnt lgkmcnt(3)
	s_nop 4
	v_add_f32_e32 v66, v66, v82
	v_add_f32_e32 v67, v67, v83
	s_waitcnt lgkmcnt(2)
	v_add_f32_e32 v68, v68, v84
	v_add_f32_e32 v69, v69, v85
	v_cndmask_b32_e32 v147, v66, v230, vcc
	v_cndmask_b32_e64 v149, v67, v230, s[40:41]
	s_waitcnt lgkmcnt(1)
	v_add_f32_e32 v67, v71, v87
	v_add_f32_e32 v70, v70, v86
	v_cndmask_b32_e64 v151, v68, v230, s[42:43]
	v_cndmask_b32_e64 v153, v69, v230, s[44:45]
	v_max3_f32 v66, v147, s79, v149
	v_cndmask_b32_e64 v159, v67, v230, s[48:49]
	s_waitcnt lgkmcnt(0)
	v_add_f32_e32 v67, v72, v88
	v_max3_f32 v66, v66, v151, v153
	v_cndmask_b32_e64 v157, v70, v230, s[46:47]
	v_cndmask_b32_e64 v161, v67, v230, s[52:53]
	v_add_f32_e32 v67, v73, v89
	v_max3_f32 v66, v66, v157, v159
	v_cndmask_b32_e64 v163, v67, v230, s[50:51]
	v_max3_f32 v82, v66, v161, v163
	ds_read2_b32 v[66:67], v180 offset1:1
	ds_read2_b32 v[68:69], v182 offset1:1
	ds_read2_b32 v[70:71], v184 offset1:1
	ds_read2_b32 v[72:73], v196 offset1:1
	s_waitcnt lgkmcnt(3)
	v_add_f32_e32 v66, v74, v66
	v_cndmask_b32_e64 v74, v66, v230, s[54:55]
	v_add_f32_e32 v66, v75, v67
	v_cndmask_b32_e64 v75, v66, v230, s[56:57]
	v_max3_f32 v66, v82, v74, v75
	s_waitcnt vmcnt(3)
	v_mfma_f32_32x32x16_bf16 v[82:97], v[142:145], v[126:129], 0
	s_waitcnt lgkmcnt(2)
	v_add_f32_e32 v67, v76, v68
	v_cndmask_b32_e64 v76, v67, v230, s[58:59]
	v_add_f32_e32 v67, v77, v69
	v_cndmask_b32_e64 v77, v67, v230, s[60:61]
	s_waitcnt lgkmcnt(1)
	v_add_f32_e32 v67, v78, v70
	v_cndmask_b32_e64 v78, v67, v230, s[62:63]
	v_add_f32_e32 v67, v79, v71
	s_waitcnt vmcnt(2)
	v_mfma_f32_32x32x16_bf16 v[82:97], v[138:141], v[114:117], v[82:97]
	v_cndmask_b32_e64 v79, v67, v230, s[64:65]
	s_waitcnt lgkmcnt(0)
	v_add_f32_e32 v67, v80, v72
	v_max3_f32 v66, v66, v76, v77
	v_cndmask_b32_e64 v80, v67, v230, s[66:67]
	v_add_f32_e32 v67, v81, v73
	v_max3_f32 v66, v66, v78, v79
	v_cndmask_b32_e64 v81, v67, v230, s[68:69]
	s_waitcnt vmcnt(1)
	v_mfma_f32_32x32x16_bf16 v[82:97], v[134:137], v[118:121], v[82:97]
	v_max3_f32 v165, v66, v80, v81
	ds_read2_b32 v[66:67], v185 offset1:1
	ds_read2_b32 v[68:69], v186 offset1:1
	ds_read2_b32 v[70:71], v187 offset1:1
	ds_read2_b32 v[72:73], v188 offset1:1
	s_waitcnt vmcnt(0)
	v_mfma_f32_32x32x16_bf16 v[82:97], v[130:133], v[122:125], v[82:97]
	s_waitcnt lgkmcnt(3)
	s_nop 10
	v_add_f32_e32 v171, v82, v66
	v_add_f32_e32 v173, v83, v67
	ds_read2_b32 v[66:67], v189 offset1:1
	s_waitcnt lgkmcnt(3)
	v_add_f32_e32 v177, v84, v68
	v_add_f32_e32 v181, v85, v69
	s_waitcnt lgkmcnt(2)
	v_add_f32_e32 v183, v86, v70
	v_add_f32_e32 v185, v87, v71
	s_waitcnt lgkmcnt(1)
	v_add_f32_e32 v186, v88, v72
	v_add_f32_e32 v187, v89, v73
	ds_read2_b32 v[68:69], v190 offset1:1
	ds_read2_b32 v[70:71], v191 offset1:1
	ds_read2_b32 v[72:73], v192 offset1:1
	s_waitcnt lgkmcnt(3)
	v_add_f32_e32 v66, v90, v66
	v_add_f32_e32 v67, v91, v67
	s_waitcnt lgkmcnt(2)
	v_add_f32_e32 v90, v93, v69
	v_max3_f32 v69, v165, v171, v173
	v_max3_f32 v69, v69, v177, v181
	v_max3_f32 v69, v69, v183, v185
	v_max3_f32 v69, v69, v186, v187
	v_add_f32_e32 v68, v92, v68
	v_max3_f32 v69, v69, v66, v67
	s_waitcnt lgkmcnt(1)
	v_add_f32_e32 v91, v94, v70
	v_add_f32_e32 v92, v95, v71
	v_max3_f32 v69, v69, v68, v90
	s_waitcnt lgkmcnt(0)
	v_add_f32_e32 v93, v96, v72
	v_add_f32_e32 v94, v97, v73
	v_max3_f32 v69, v69, v91, v92
	v_max3_f32 v69, v69, v93, v94
	ds_bpermute_b32 v70, v208, v69
	s_waitcnt lgkmcnt(0)
; #define LAS __attribute__((address_space(3)))
; #define MFMA32(a, b, c) __builtin_amdgcn_mfma_f32_32x32x16_bf16((a), (b), (c), 0, 0, 0)
; template <int DELTA> ...
;     ...
;             for (int d0 = 0; d0 < 4; ++d0) s[kvh] = MFMA32(kf[kvh][d0], qf[qh][d0], s[kvh]);
; #pragma unroll
;             for (int rr = 0; rr < 16; ++rr) { const int c4 = 4 * ((rr & 3) + 8 * (rr >> 2)); const float bias = *(const LAS float*)(wl + bvar + (VT_B + c4 + toff * 4));
;                 float v = s[kvh][rr] + bias;
;                 if (toff == 64) v = (bvar <= btb - c4) ? v : -1e30f;
;                 if (toff == -64) v = (bvar >= btb - c4) ? v : -1e30f;
;                 s[kvh][rr] = v; mx = fmaxf(mx, v); }
;         }
;         mx = fmaxf(mx, __shfl_xor(mx, 32));
;         const float m_new = fmaxf(m_run[qh], mx); const float alpha = __builtin_amdgcn_exp2f(m_run[qh] - m_new); m_run[qh] = m_new;
;         float ls = 0.f;
; #pragma unroll
;         for (int kvh = 0; kvh < 2; ++kvh) { const int toff = 64 * DELTA + 32 * (kvh - qh);
;             if (toff > 64 || toff < -64) continue;
; #pragma unroll
;             for (int rr = 0; rr < 16; ++rr) { const float e = __builtin_amdgcn_exp2f(s[kvh][rr] - m_new); s[kvh][rr] = e; ls += e; }
;             pb[qh][2 * kvh] = packp(s[kvh], 0); pb[qh][2 * kvh + 1] = packp(s[kvh], 8); }
;         l_run[qh] = l_run[qh] * alpha + ls;
; #pragma unroll
;         for (int i = 0; i < 16; ++i) { o[qh][0][i] *= alpha; o[qh][1][i] *= alpha; }
	v_max3_f32 v233, v170, v69, v70
	v_sub_f32_e32 v69, v147, v233
	v_exp_f32_e32 v169, v69
	v_sub_f32_e32 v69, v149, v233
	v_exp_f32_e32 v235, v69
	v_sub_f32_e32 v69, v151, v233
	v_exp_f32_e32 v237, v69
	v_sub_f32_e32 v69, v153, v233
	v_exp_f32_e32 v225, v69
	v_sub_f32_e32 v69, v157, v233
	v_exp_f32_e32 v236, v69
	v_sub_f32_e32 v69, v159, v233
	v_exp_f32_e32 v238, v69
	v_sub_f32_e32 v69, v161, v233
	v_exp_f32_e32 v165, v69
	v_sub_f32_e32 v69, v163, v233
	v_exp_f32_e32 v167, v69
	v_sub_f32_e32 v69, v74, v233
	v_exp_f32_e32 v151, v69
	v_sub_f32_e32 v69, v75, v233
	v_exp_f32_e32 v157, v69
	v_sub_f32_e32 v69, v76, v233
	v_exp_f32_e32 v159, v69
	v_sub_f32_e32 v69, v77, v233
	v_exp_f32_e32 v161, v69
	v_sub_f32_e32 v69, v78, v233
	v_exp_f32_e32 v163, v69
	v_sub_f32_e32 v69, v79, v233
	v_exp_f32_e32 v147, v69
	v_sub_f32_e32 v69, v80, v233
	v_exp_f32_e32 v149, v69
	v_sub_f32_e32 v69, v81, v233
	v_exp_f32_e32 v153, v69
	v_sub_f32_e32 v69, v171, v233
	v_exp_f32_e32 v171, v69
	v_sub_f32_e32 v69, v173, v233
	v_exp_f32_e32 v175, v69
	v_sub_f32_e32 v69, v177, v233
	v_exp_f32_e32 v179, v69
	v_sub_f32_e32 v69, v181, v233
	v_exp_f32_e32 v173, v69
	v_sub_f32_e32 v69, v183, v233
	v_exp_f32_e32 v177, v69
	v_sub_f32_e32 v69, v185, v233
	v_exp_f32_e32 v181, v69
	v_sub_f32_e32 v69, v186, v233
	v_sub_f32_e32 v66, v66, v233
	v_exp_f32_e32 v183, v69
	v_sub_f32_e32 v69, v187, v233
	v_exp_f32_e32 v187, v66
	v_sub_f32_e32 v66, v67, v233
	v_exp_f32_e32 v185, v69
	v_exp_f32_e32 v189, v66
	v_sub_f32_e32 v95, v68, v233
	v_mfma_f32_32x32x16_bf16 v[66:81], v[142:145], v[110:113], 0
	v_sub_f32_e32 v90, v90, v233
	v_exp_f32_e32 v145, v90
	v_sub_f32_e32 v90, v91, v233
	v_exp_f32_e32 v191, v90
	v_sub_f32_e32 v90, v92, v233
	v_exp_f32_e32 v193, v90
	v_sub_f32_e32 v90, v93, v233
	v_mfma_f32_32x32x16_bf16 v[66:81], v[138:141], v[106:109], v[66:81]
	v_exp_f32_e32 v139, v90
	v_sub_f32_e32 v90, v94, v233
	v_cvt_pk_bf16_f32 v86, v169, v235
	v_cvt_pk_bf16_f32 v87, v237, v225
	v_cvt_pk_bf16_f32 v88, v236, v238
	v_cvt_pk_bf16_f32 v89, v165, v167
	v_cvt_pk_bf16_f32 v82, v151, v157
	v_mfma_f32_32x32x16_bf16 v[66:81], v[134:137], v[98:101], v[66:81]
	v_cvt_pk_bf16_f32 v83, v159, v161
	v_cvt_pk_bf16_f32 v84, v163, v147
	v_cvt_pk_bf16_f32 v85, v149, v153
	v_exp_f32_e32 v143, v95
	v_exp_f32_e32 v141, v90
	v_cvt_pk_bf16_f32 v94, v171, v175
	v_cvt_pk_bf16_f32 v95, v179, v173
	v_mfma_f32_32x32x16_bf16 v[66:81], v[130:133], v[102:105], v[66:81]
	v_cvt_pk_bf16_f32 v96, v177, v181
	v_cvt_pk_bf16_f32 v97, v183, v185
	v_cvt_pk_bf16_f32 v90, v187, v189
	v_cvt_pk_bf16_f32 v91, v143, v145
	v_cvt_pk_bf16_f32 v92, v191, v193
	v_cvt_pk_bf16_f32 v93, v139, v141
	ds_read2_b32 v[136:137], v172 offset1:1
	ds_read2_b32 v[130:131], v174 offset1:1
	ds_read2_b32 v[132:133], v176 offset1:1
	ds_read2_b32 v[194:195], v178 offset1:1
	v_sub_f32_e32 v170, v170, v233
	v_exp_f32_e32 v134, v170
	s_waitcnt lgkmcnt(3)
	s_nop 4
	v_add_f32_e32 v66, v66, v136
	v_cndmask_b32_e32 v135, v66, v230, vcc
	v_add_f32_e32 v66, v67, v137
	v_cndmask_b32_e64 v136, v66, v230, s[40:41]
	s_waitcnt lgkmcnt(2)
	v_add_f32_e32 v66, v68, v130
	v_cndmask_b32_e64 v137, v66, v230, s[42:43]
	v_add_f32_e32 v66, v69, v131
	v_cndmask_b32_e64 v131, v66, v230, s[44:45]
	s_waitcnt lgkmcnt(1)
	v_add_f32_e32 v66, v70, v132
	v_cndmask_b32_e64 v132, v66, v230, s[46:47]
	v_add_f32_e32 v66, v71, v133
	v_cndmask_b32_e64 v133, v66, v230, s[48:49]
	s_waitcnt lgkmcnt(0)
	v_add_f32_e32 v66, v72, v194
	v_cndmask_b32_e64 v138, v66, v230, s[52:53]
	ds_read2_b32 v[66:67], v180 offset1:1
	v_add_f32_e32 v68, v73, v195
	v_cndmask_b32_e64 v140, v68, v230, s[50:51]
	ds_read2_b32 v[68:69], v182 offset1:1
	ds_read2_b32 v[70:71], v184 offset1:1
	ds_read2_b32 v[72:73], v196 offset1:1
	v_pk_mul_f32 v[64:65], v[64:65], v[134:135] op_sel_hi:[1,0]
	s_waitcnt lgkmcnt(3)
	v_add_f32_e32 v66, v74, v66
	v_max3_f32 v74, v135, s79, v136
	v_max3_f32 v74, v74, v137, v131
	v_add_f32_e32 v67, v75, v67
	v_max3_f32 v74, v74, v132, v133
	v_cndmask_b32_e64 v66, v66, v230, s[54:55]
	v_cndmask_b32_e64 v67, v67, v230, s[56:57]
	s_waitcnt lgkmcnt(2)
	v_add_f32_e32 v68, v76, v68
	v_add_f32_e32 v69, v77, v69
	v_max3_f32 v74, v74, v138, v140
	v_cndmask_b32_e64 v68, v68, v230, s[58:59]
	v_cndmask_b32_e64 v69, v69, v230, s[60:61]
	s_waitcnt lgkmcnt(1)
	v_add_f32_e32 v70, v78, v70
	v_add_f32_e32 v71, v79, v71
	v_max3_f32 v74, v74, v66, v67
	v_cndmask_b32_e64 v70, v70, v230, s[62:63]
	v_cndmask_b32_e64 v71, v71, v230, s[64:65]
	s_waitcnt lgkmcnt(0)
	v_add_f32_e32 v72, v80, v72
	v_add_f32_e32 v73, v81, v73
	v_max3_f32 v74, v74, v68, v69
	v_cndmask_b32_e64 v72, v72, v230, s[66:67]
	v_cndmask_b32_e64 v73, v73, v230, s[68:69]
	v_max3_f32 v74, v74, v70, v71
	v_max3_f32 v74, v74, v72, v73
	ds_bpermute_b32 v75, v208, v74
	v_pk_mul_f32 v[62:63], v[62:63], v[134:135] op_sel_hi:[1,0]
	v_pk_mul_f32 v[60:61], v[60:61], v[134:135] op_sel_hi:[1,0]
	v_pk_mul_f32 v[58:59], v[58:59], v[134:135] op_sel_hi:[1,0]
	v_pk_mul_f32 v[56:57], v[56:57], v[134:135] op_sel_hi:[1,0]
	s_waitcnt lgkmcnt(0)
	v_max3_f32 v130, v223, v74, v75
	v_sub_f32_e32 v74, v135, v130
	v_sub_f32_e32 v66, v66, v130
	v_exp_f32_e32 v170, v74
	v_sub_f32_e32 v74, v136, v130
	v_exp_f32_e32 v186, v66
	v_sub_f32_e32 v66, v67, v130
	v_exp_f32_e32 v174, v74
	v_sub_f32_e32 v74, v137, v130
	v_exp_f32_e32 v188, v66
	v_sub_f32_e32 v66, v68, v130
	v_exp_f32_e32 v178, v74
	v_sub_f32_e32 v74, v131, v130
	v_exp_f32_e32 v142, v66
	v_sub_f32_e32 v66, v69, v130
	v_exp_f32_e32 v172, v74
	v_sub_f32_e32 v74, v132, v130
	v_exp_f32_e32 v144, v66
	v_sub_f32_e32 v66, v70, v130
	v_exp_f32_e32 v176, v74
	v_sub_f32_e32 v74, v133, v130
	v_exp_f32_e32 v190, v66
	v_sub_f32_e32 v66, v71, v130
	v_exp_f32_e32 v180, v74
	v_sub_f32_e32 v74, v138, v130
	v_exp_f32_e32 v192, v66
	v_sub_f32_e32 v66, v72, v130
	v_exp_f32_e32 v182, v74
	v_sub_f32_e32 v74, v140, v130
	v_exp_f32_e32 v138, v66
	v_sub_f32_e32 v66, v73, v130
	v_exp_f32_e32 v184, v74
	v_exp_f32_e32 v140, v66
	v_cvt_pk_bf16_f32 v70, v170, v174
	v_cvt_pk_bf16_f32 v71, v178, v172
	v_cvt_pk_bf16_f32 v72, v176, v180
	v_cvt_pk_bf16_f32 v73, v182, v184
	v_cvt_pk_bf16_f32 v66, v186, v188
	v_cvt_pk_bf16_f32 v67, v142, v144
	v_cvt_pk_bf16_f32 v68, v190, v192
	v_cvt_pk_bf16_f32 v69, v138, v140
	s_waitcnt lgkmcnt(0)
; #define LAS __attribute__((address_space(3)))
; #define LDS_WAIT() asm volatile("s_waitcnt lgkmcnt(0)" ::: "memory")
; __device__ __forceinline__ s16x4 vtr(const LAS unsigned char* p) { return __builtin_bit_cast(s16x4, __builtin_amdgcn_ds_read_tr16_b64_v4i16((LAS v4i16_t*)p)); }
; __device__ __forceinline__ bf16x8 cat8(s16x4 a, s16x4 b) { return (bf16x8){a[0], a[1], a[2], a[3], b[0], b[1], b[2], b[3]}; }
; #define MFMA32(a, b, c) __builtin_amdgcn_mfma_f32_32x32x16_bf16((a), (b), (c), 0, 0, 0)
; template <int DELTA> ...
;     ...
;         mx = fmaxf(mx, __shfl_xor(mx, 32));
;         const float m_new = fmaxf(m_run[qh], mx); const float alpha = __builtin_amdgcn_exp2f(m_run[qh] - m_new); m_run[qh] = m_new;
;         float ls = 0.f;
; #pragma unroll
;         for (int kvh = 0; kvh < 2; ++kvh) { const int toff = 64 * DELTA + 32 * (kvh - qh);
;             if (toff > 64 || toff < -64) continue;
; #pragma unroll
;             for (int rr = 0; rr < 16; ++rr) { const float e = __builtin_amdgcn_exp2f(s[kvh][rr] - m_new); s[kvh][rr] = e; ls += e; }
;             pb[qh][2 * kvh] = packp(s[kvh], 0); pb[qh][2 * kvh + 1] = packp(s[kvh], 8); }
;         l_run[qh] = l_run[qh] * alpha + ls;
; #pragma unroll
;         for (int i = 0; i < 16; ++i) { o[qh][0][i] *= alpha; o[qh][1][i] *= alpha; }
;     }
;     LDS_WAIT();
; #pragma unroll
;     for (int j = 0; j < 4; ++j) { const LAS unsigned char* vj = wl + voff + 16 * j * VP;
;         const bf16x8 a0 = cat8(vtr(vj), vtr(vj + 8 * VP)); const bf16x8 a1 = cat8(vtr(vj + 64), vtr(vj + 8 * VP + 64));
; #pragma unroll
;         for (int qh = 0; qh < 2; ++qh) { const int toff = 64 * DELTA + 32 * ((j >> 1) - qh);
;             if (toff > 64 || toff < -64) continue;
;             o[qh][0] = MFMA32(a0, pb[qh][j], o[qh][0]); o[qh][1] = MFMA32(a1, pb[qh][j], o[qh][1]); } }
	ds_read_b64_tr_b16 v[74:75], v222
	ds_read_b64_tr_b16 v[76:77], v222 offset:1536
	ds_read_b64_tr_b16 v[80:81], v222 offset:1600
	ds_read_b64_tr_b16 v[78:79], v222 offset:64
	v_pk_mul_f32 v[54:55], v[54:55], v[134:135] op_sel_hi:[1,0]
	v_pk_mul_f32 v[52:53], v[52:53], v[134:135] op_sel_hi:[1,0]
	v_pk_mul_f32 v[50:51], v[50:51], v[134:135] op_sel_hi:[1,0]
	v_pk_mul_f32 v[48:49], v[48:49], v[134:135] op_sel_hi:[1,0]
	v_pk_mul_f32 v[46:47], v[46:47], v[134:135] op_sel_hi:[1,0]
	s_waitcnt lgkmcnt(2)
	v_mfma_f32_32x32x16_bf16 v[50:65], v[74:77], v[86:89], v[50:65]
	v_mul_f32_e64 v44, v44, v134
	v_mul_f32_e64 v45, v45, v134
	v_mul_f32_e64 v42, v42, v134
	v_mul_f32_e64 v43, v43, v134
	v_mul_f32_e64 v40, v40, v134
	v_mul_f32_e64 v41, v41, v134
	v_pk_mul_f32 v[38:39], v[38:39], v[134:135] op_sel_hi:[1,0]
	v_pk_mul_f32 v[36:37], v[36:37], v[134:135] op_sel_hi:[1,0]
	v_pk_mul_f32 v[34:35], v[34:35], v[134:135] op_sel_hi:[1,0]
	s_mov_b64 s[40:41], s[6:7]
	s_waitcnt lgkmcnt(0)
	v_mfma_f32_32x32x16_bf16 v[34:49], v[78:81], v[86:89], v[34:49]
	ds_read_b64_tr_b16 v[74:75], v222 offset:3072
	ds_read_b64_tr_b16 v[76:77], v222 offset:4608
	ds_read_b64_tr_b16 v[80:81], v222 offset:4672
	ds_read_b64_tr_b16 v[78:79], v222 offset:3136
	s_waitcnt lgkmcnt(2)
	v_mfma_f32_32x32x16_bf16 v[50:65], v[74:77], v[82:85], v[50:65]
	v_add_f32_e32 v74, 0, v169
	v_add_f32_e32 v74, v235, v74
	v_add_f32_e32 v86, v237, v74
	ds_read_b64_tr_b16 v[74:75], v222 offset:6144
	ds_read_b64_tr_b16 v[76:77], v222 offset:7680
	s_waitcnt lgkmcnt(2)
	v_mfma_f32_32x32x16_bf16 v[34:49], v[78:81], v[82:85], v[34:49]
	v_add_f32_e32 v78, v225, v86
	v_add_f32_e32 v78, v236, v78
	v_add_f32_e32 v83, v238, v78
	v_sub_f32_e32 v78, v223, v130
	v_exp_f32_e32 v82, v78
	ds_read_b64_tr_b16 v[80:81], v222 offset:7744
	ds_read_b64_tr_b16 v[78:79], v222 offset:6208
	v_add_f32_e32 v83, v165, v83
	v_add_f32_e32 v84, v167, v83
	v_mov_b32_e32 v83, v134
	v_pk_mul_f32 v[32:33], v[32:33], v[82:83] op_sel_hi:[1,0]
	v_pk_mul_f32 v[30:31], v[30:31], v[82:83] op_sel_hi:[1,0]
	v_pk_mul_f32 v[28:29], v[28:29], v[82:83] op_sel_hi:[1,0]
	v_pk_mul_f32 v[26:27], v[26:27], v[82:83] op_sel_hi:[1,0]
	v_pk_mul_f32 v[24:25], v[24:25], v[82:83] op_sel_hi:[1,0]
	v_pk_mul_f32 v[22:23], v[22:23], v[82:83] op_sel_hi:[1,0]
	v_pk_mul_f32 v[20:21], v[20:21], v[82:83] op_sel_hi:[1,0]
	v_pk_mul_f32 v[18:19], v[18:19], v[82:83] op_sel_hi:[1,0]
	v_pk_mul_f32 v[16:17], v[16:17], v[82:83] op_sel_hi:[1,0]
	v_pk_mul_f32 v[14:15], v[14:15], v[82:83] op_sel_hi:[1,0]
	v_pk_mul_f32 v[12:13], v[12:13], v[82:83] op_sel_hi:[1,0]
	v_pk_mul_f32 v[10:11], v[10:11], v[82:83] op_sel_hi:[1,0]
	v_pk_mul_f32 v[8:9], v[8:9], v[82:83] op_sel_hi:[1,0]
	v_pk_mul_f32 v[6:7], v[6:7], v[82:83] op_sel_hi:[1,0]
	v_pk_mul_f32 v[4:5], v[4:5], v[82:83] op_sel_hi:[1,0]
	v_pk_mul_f32 v[2:3], v[2:3], v[82:83] op_sel_hi:[1,0]
	s_waitcnt lgkmcnt(2)
	v_mfma_f32_32x32x16_bf16 v[18:33], v[74:77], v[70:73], v[18:33]
	v_mov_b32_e32 v223, v130
	s_waitcnt lgkmcnt(0)
	v_mfma_f32_32x32x16_bf16 v[2:17], v[78:81], v[70:73], v[2:17]
	v_add_f32_e32 v70, v151, v84
	v_add_f32_e32 v70, v157, v70
	v_add_f32_e32 v70, v159, v70
	v_add_f32_e32 v70, v161, v70
	v_mfma_f32_32x32x16_bf16 v[34:49], v[78:81], v[94:97], v[34:49]
	v_add_f32_e32 v78, v163, v70
	v_add_f32_e32 v78, v147, v78
	v_add_f32_e32 v78, v149, v78
	v_add_f32_e32 v79, v153, v78
	v_mov_b32_e32 v78, v1
	v_pk_add_f32 v[78:79], v[170:171], v[78:79]
	v_mov_b32_e32 v170, v233
	v_mfma_f32_32x32x16_bf16 v[50:65], v[74:77], v[94:97], v[50:65]
	v_add_f32_e64 v78, v174, v78
	v_add_f32_e64 v79, v175, v79
	ds_read_b64_tr_b16 v[74:75], v222 offset:9216
	ds_read_b64_tr_b16 v[76:77], v222 offset:10752
	v_add_f32_e64 v78, v178, v78
	v_add_f32_e64 v79, v179, v79
	ds_read_b64_tr_b16 v[72:73], v222 offset:10816
	ds_read_b64_tr_b16 v[70:71], v222 offset:9280
	v_pk_add_f32 v[78:79], v[172:173], v[78:79]
	s_waitcnt lgkmcnt(0)
	s_nop 0
	v_pk_add_f32 v[78:79], v[176:177], v[78:79]
	s_waitcnt lgkmcnt(2)
	v_mfma_f32_32x32x16_bf16 v[50:65], v[74:77], v[90:93], v[50:65]
	v_add_f32_e64 v78, v180, v78
	v_add_f32_e64 v79, v181, v79
	v_add_f32_e64 v78, v182, v78
	v_add_f32_e64 v79, v183, v79
	v_add_f32_e64 v78, v184, v78
	v_add_f32_e64 v79, v185, v79
	v_pk_add_f32 v[78:79], v[186:187], v[78:79]
	s_waitcnt lgkmcnt(0)
	v_mfma_f32_32x32x16_bf16 v[34:49], v[70:73], v[90:93], v[34:49]
	v_add_f32_e64 v78, v188, v78
	v_add_f32_e64 v79, v189, v79
	v_mfma_f32_32x32x16_bf16 v[18:33], v[74:77], v[66:69], v[18:33]
	v_add_f32_e64 v74, v142, v78
	v_add_f32_e64 v75, v143, v79
	v_add_f32_e64 v74, v144, v74
	v_add_f32_e64 v75, v145, v75
	v_add_f32_e64 v74, v190, v74
	v_add_f32_e64 v75, v191, v75
	v_pk_add_f32 v[74:75], v[192:193], v[74:75]
	v_mfma_f32_32x32x16_bf16 v[2:17], v[70:73], v[66:69], v[2:17]
	v_add_f32_e64 v74, v138, v74
	v_add_f32_e64 v75, v139, v75
	v_add_f32_e64 v74, v140, v74
	v_add_f32_e64 v75, v141, v75
	v_fma_f32 v154, v154, v82, v74
	v_fma_f32 v155, v155, v83, v75
	s_andn2_b64 vcc, exec, s[40:41]
	s_cbranch_vccnz .LBB0_462
	s_branch .LBB0_461
